# G5 (gelu*val) epilogue: software-prefetch the next batch's three up-row loads during the current batch's compute (12 of 16 batches), counted vmcnt
# speedup vs baseline: 1.0083x; 1.0023x over previous
; __device__ __forceinline__ unsigned pk2(float lo, float hi) { unsigned r; asm("v_cvt_pk_bf16_f32 %0, %1, %2" : "=v"(r) : "v"(lo), "v"(hi)); return r; }
;     static __device__ __forceinline__ void unpack8(const u32x4 q, float (&x)[8]) { x[0] = bflo(q.x); x[1] = bfhi(q.x); x[2] = bflo(q.y); x[3] = bfhi(q.y); x[4] = bflo(q.z); x[5] = bfhi(q.z); x[6] = bflo(q.w); x[7] = bfhi(q.w); }
; __device__ __forceinline__ float gelu_f(float v) {
;     const float av = fabsf(v), d = av * 0.2316418882f + 1.0f;
;     const float t = __builtin_amdgcn_rcpf(d);
;     float q = t * 0.5307027145f + (-0.7265760135f); q = q * t + 0.7107068705f; q = q * t + (-0.142248368f); q = q * t + 0.127414796f; q = q * t;
;     const float e = __builtin_amdgcn_exp2f(v * v * (-0.72134752044f));
;     const float m = v * (q * e);
;     return v < 0.f ? m : v - m;
;     __device__ __forceinline__ void operator()(EPI_ARGS) const {
;     ...
;                     for (int t = 0; t < 1; ++t) { const int m = mp + t, row = row0 + ai * 128 + m * 16;
;                         const int i = row < TP ? row : ((row - TP) & 15); const int sidx = row < TP ? 0 : ((row - TP) >> 4);
;                         float x0[8], x1[8], x2[8]; unpack8(q0[t], x0); unpack8(q1[t], x1); unpack8(q2[t], x2);
;                         if (i < 2) {
;                             const bool smp = row >= TP; const float* p0 = cs + ((size_t)sidx * 2 + i) * DFF + col; const float* p1 = cs + ((size_t)sidx * 2 + 1) * DFF + col;
; #pragma unroll
;                             for (int e = 0; e < 8; ++e) { x0[e] = smp ? p0[e] : 0.f; if (i == 0) x1[e] = smp ? p1[e] : 0.f; } }
;                         float r[8];
; #pragma unroll
;                         for (int e = 0; e < 8; ++e) { const float cv = bb[e] + x0[e] * w0[e] + x1[e] * w1[e] + x2[e] * w2[e]; r[e] = gelu_f(cv) * acc[ai][bj][m][e >> 2][e & 3]; }
;                         u32x4 w; w.x = pk2(r[0], r[1]); w.y = pk2(r[2], r[3]); w.z = pk2(r[4], r[5]); w.w = pk2(r[6], r[7]);
;                         *(u32x4*)(act + (size_t)row * DFF + col) = w; } } } }
.LBB0_1173:
	s_or_b64 exec, exec, s[0:1]
	v_lshlrev_b32_e32 v194, 16, v170
	v_and_b32_e32 v170, 0xffff0000, v170
	v_lshlrev_b32_e32 v222, 16, v171
	v_and_b32_e32 v224, 0xffff0000, v171
	v_mov_b32_e32 v210, v166
	v_mov_b32_e32 v211, v106
	s_waitcnt vmcnt(0)
	v_add_u32_e32 v240, 16, v232
	v_mov_b64_e32 v[238:239], s[30:31]
	v_mad_i64_i32 v[238:239], s[0:1], v240, s76, v[238:239]
	v_lshl_add_u64 v[238:239], v[238:239], 0, v[186:187]
	global_load_dwordx4 v[196:199], v[238:239], off
	v_add_u32_e32 v240, -1, v240
	v_mov_b64_e32 v[246:247], s[30:31]
	v_mad_i64_i32 v[246:247], s[0:1], v240, s76, v[246:247]
	v_lshl_add_u64 v[246:247], v[246:247], 0, v[186:187]
	global_load_dwordx4 v[200:203], v[246:247], off
	v_add_u32_e32 v240, -1, v240
	v_mov_b64_e32 v[238:239], s[30:31]
	v_mad_i64_i32 v[238:239], s[0:1], v240, s76, v[238:239]
	v_lshl_add_u64 v[238:239], v[238:239], 0, v[186:187]
	global_load_dwordx4 v[242:245], v[238:239], off
	v_mov_b32_e32 v195, v0
	v_mov_b32_e32 v106, v167
	v_mov_b32_e32 v171, v1
	v_pk_mul_f32 v[194:195], v[210:211], v[194:195]
	v_pk_mul_f32 v[0:1], v[106:107], v[170:171]
	v_pk_fma_f32 v[166:167], v[102:103], v[212:213], v[110:111]
	v_mov_b32_e32 v170, v195
	v_mov_b32_e32 v171, v1
	v_pk_add_f32 v[166:167], v[170:171], v[166:167]
	v_mov_b32_e32 v195, v0
	v_pk_add_f32 v[0:1], v[194:195], v[166:167]
	v_lshlrev_b32_e32 v226, 16, v172
	v_fma_f32 v166, |v0|, s84, 1.0
	v_rcp_f32_e32 v167, v166
	v_and_b32_e32 v166, 0xffff0000, v172
	v_lshlrev_b32_e32 v170, 16, v173
	v_and_b32_e32 v194, 0xffff0000, v173
	v_pk_mul_f32 v[172:173], v[0:1], v[0:1]
	v_fmamk_f32 v171, v167, 0x3f07dc22, v241
	v_mul_f32_e32 v172, 0xbf38aa3b, v172
	v_fmaak_f32 v171, v167, v171, 0x3f35f0e3
	v_exp_f32_e32 v172, v172
	v_fmaak_f32 v171, v167, v171, 0xbe11a98e
	v_fmaak_f32 v171, v167, v171, 0x3e027906
	v_mul_f32_e32 v167, v167, v171
	v_mul_f32_e32 v167, v172, v167
	v_fma_f32 v172, |v1|, s84, 1.0
	v_rcp_f32_e32 v172, v172
	v_mad_i64_i32 v[220:221], s[0:1], v232, s76, 0
	v_mul_f32_e32 v171, v0, v167
	v_fma_f32 v167, -v0, v167, v0
	v_cmp_gt_f32_e64 s[0:1], 0, v0
	v_mov_b32_e32 v223, v2
	v_mov_b32_e32 v225, v3
	v_cndmask_b32_e64 v0, v167, v171, s[0:1]
	v_mul_f32_e32 v233, v158, v0
	v_fmamk_f32 v0, v172, 0x3f07dc22, v241
	v_fmaak_f32 v0, v172, v0, 0x3f35f0e3
	v_fmaak_f32 v0, v172, v0, 0xbe11a98e
	v_fmaak_f32 v0, v172, v0, 0x3e027906
	v_mul_f32_e32 v158, 0xbf38aa3b, v173
	v_mul_f32_e32 v0, v172, v0
	v_mov_b32_e32 v172, v168
	v_mov_b32_e32 v173, v108
	v_mov_b32_e32 v108, v169
	v_pk_mul_f32 v[212:213], v[172:173], v[222:223]
	v_pk_mul_f32 v[2:3], v[108:109], v[224:225]
	v_pk_fma_f32 v[168:169], v[104:105], v[214:215], v[112:113]
	v_mov_b32_e32 v214, v213
	v_mov_b32_e32 v215, v3
	v_exp_f32_e32 v158, v158
	v_pk_add_f32 v[168:169], v[214:215], v[168:169]
	v_mov_b32_e32 v213, v2
	v_pk_add_f32 v[2:3], v[212:213], v[168:169]
	v_mul_f32_e32 v0, v158, v0
	v_fma_f32 v167, |v2|, s84, 1.0
	v_rcp_f32_e32 v167, v167
	v_mul_f32_e32 v158, v1, v0
	v_fma_f32 v0, -v1, v0, v1
	v_cmp_gt_f32_e64 s[0:1], 0, v1
	v_mov_b32_e32 v212, v162
	v_mov_b32_e32 v213, v94
	v_cndmask_b32_e64 v0, v0, v158, s[0:1]
	v_mul_f32_e32 v168, v159, v0
	v_fmamk_f32 v0, v167, 0x3f07dc22, v241
	v_fmaak_f32 v158, v167, v0, 0x3f35f0e3
	v_pk_mul_f32 v[0:1], v[2:3], v[2:3]
	v_fmaak_f32 v158, v167, v158, 0xbe11a98e
	v_mul_f32_e32 v0, 0xbf38aa3b, v0
	v_exp_f32_e32 v0, v0
	v_fmaak_f32 v158, v167, v158, 0x3e027906
	v_fma_f32 v159, |v3|, s84, 1.0
	v_mul_f32_e32 v158, v167, v158
	v_rcp_f32_e32 v159, v159
	v_mul_f32_e32 v0, v0, v158
	v_mul_f32_e32 v158, v2, v0
	v_fma_f32 v0, -v2, v0, v2
	v_cmp_gt_f32_e64 s[0:1], 0, v2
	v_mul_f32_e32 v1, 0xbf38aa3b, v1
	v_exp_f32_e32 v1, v1
	v_cndmask_b32_e64 v0, v0, v158, s[0:1]
	v_mul_f32_e32 v160, v160, v0
	v_fmamk_f32 v0, v159, 0x3f07dc22, v241
	v_fmaak_f32 v0, v159, v0, 0x3f35f0e3
	v_fmaak_f32 v0, v159, v0, 0xbe11a98e
	v_fmaak_f32 v0, v159, v0, 0x3e027906
	v_mul_f32_e32 v0, v159, v0
	v_mul_f32_e32 v0, v1, v0
	v_mov_b32_e32 v227, v4
	v_mov_b32_e32 v94, v163
	v_mov_b32_e32 v167, v5
	v_mul_f32_e32 v2, v3, v0
	v_fma_f32 v169, -v3, v0, v3
	v_pk_mul_f32 v[0:1], v[212:213], v[226:227]
	v_pk_mul_f32 v[4:5], v[94:95], v[166:167]
	v_pk_fma_f32 v[158:159], v[90:91], v[216:217], v[98:99]
	v_mov_b32_e32 v162, v1
	v_mov_b32_e32 v163, v5
	v_pk_add_f32 v[158:159], v[162:163], v[158:159]
	v_mov_b32_e32 v1, v4
	v_pk_add_f32 v[0:1], v[0:1], v[158:159]
	v_cmp_gt_f32_e64 s[0:1], 0, v3
	v_fma_f32 v4, |v0|, s84, 1.0
	v_rcp_f32_e32 v4, v4
	v_cndmask_b32_e64 v2, v169, v2, s[0:1]
	v_mul_f32_e32 v161, v161, v2
	v_cmp_gt_f32_e64 s[0:1], 0, v0
	v_fmamk_f32 v2, v4, 0x3f07dc22, v241
;     static __device__ __forceinline__ void unpack8(const u32x4 q, float (&x)[8]) { x[0] = bflo(q.x); x[1] = bfhi(q.x); x[2] = bflo(q.y); x[3] = bfhi(q.y); x[4] = bflo(q.z); x[5] = bfhi(q.z); x[6] = bflo(q.w); x[7] = bfhi(q.w); }
;     __device__ __forceinline__ void operator()(EPI_ARGS) const {
;     ...
;                     for (int t = 0; t < 1; ++t) { const int row = row0 + ai * 128 + (mp + t) * 16; const int r1 = row > 0 ? row - 1 : 0, r2 = row > 1 ? row - 2 : 0;
;                         q2[t] = *(const u32x4*)(up + (size_t)row * DFF + col); q1[t] = *(const u32x4*)(up + (size_t)r1 * DFF + col); q0[t] = *(const u32x4*)(up + (size_t)r2 * DFF + col); }
;                     __builtin_amdgcn_sched_barrier(0);
; #pragma unroll
;                     for (int t = 0; t < 1; ++t) { const int m = mp + t, row = row0 + ai * 128 + m * 16;
;                         const int i = row < TP ? row : ((row - TP) & 15); const int sidx = row < TP ? 0 : ((row - TP) >> 4);
;                         float x0[8], x1[8], x2[8]; unpack8(q0[t], x0); unpack8(q1[t], x1); unpack8(q2[t], x2);
;                         if (i < 2) {
;                             const bool smp = row >= TP; const float* p0 = cs + ((size_t)sidx * 2 + i) * DFF + col; const float* p1 = cs + ((size_t)sidx * 2 + 1) * DFF + col;
; #pragma unroll
;                             for (int e = 0; e < 8; ++e) { x0[e] = smp ? p0[e] : 0.f; if (i == 0) x1[e] = smp ? p1[e] : 0.f; } }
	v_fmaak_f32 v5, v4, v2, 0x3f35f0e3
	v_pk_mul_f32 v[2:3], v[0:1], v[0:1]
	v_fmaak_f32 v5, v4, v5, 0xbe11a98e
	v_mul_f32_e32 v2, 0xbf38aa3b, v2
	v_exp_f32_e32 v2, v2
	v_fmaak_f32 v5, v4, v5, 0x3e027906
	v_mul_f32_e32 v4, v4, v5
	v_fma_f32 v5, |v1|, s84, 1.0
	v_rcp_f32_e32 v5, v5
	v_mul_f32_e32 v2, v2, v4
	v_mul_f32_e32 v4, v0, v2
	v_fma_f32 v2, -v0, v2, v0
	v_cndmask_b32_e64 v0, v2, v4, s[0:1]
	v_mul_f32_e32 v154, v154, v0
	v_fmamk_f32 v0, v5, 0x3f07dc22, v241
	v_mul_f32_e32 v2, 0xbf38aa3b, v3
	v_fmaak_f32 v0, v5, v0, 0x3f35f0e3
	v_exp_f32_e32 v2, v2
	v_fmaak_f32 v0, v5, v0, 0xbe11a98e
	v_fmaak_f32 v0, v5, v0, 0x3e027906
	v_mul_f32_e32 v0, v5, v0
	v_mov_b32_e32 v214, v164
	v_mov_b32_e32 v215, v96
	v_mov_b32_e32 v171, v6
	v_mov_b32_e32 v96, v165
	v_mov_b32_e32 v195, v7
	v_mul_f32_e32 v0, v2, v0
	v_pk_mul_f32 v[2:3], v[214:215], v[170:171]
	v_pk_mul_f32 v[4:5], v[96:97], v[194:195]
	v_pk_fma_f32 v[6:7], v[92:93], v[218:219], v[100:101]
	v_mov_b32_e32 v158, v3
	v_mov_b32_e32 v159, v5
	v_pk_add_f32 v[6:7], v[158:159], v[6:7]
	v_mov_b32_e32 v3, v4
	v_pk_add_f32 v[2:3], v[2:3], v[6:7]
	v_mul_f32_e32 v162, v1, v0
	v_fma_f32 v4, |v2|, s84, 1.0
	v_rcp_f32_e32 v4, v4
	v_fma_f32 v0, -v1, v0, v1
	v_cmp_gt_f32_e64 s[0:1], 0, v1
	v_or_b32_e32 v224, 16, v232
	s_nop 0
	v_cndmask_b32_e64 v0, v0, v162, s[0:1]
	v_mul_f32_e32 v5, v155, v0
	v_fmamk_f32 v0, v4, 0x3f07dc22, v241
	v_fmaak_f32 v6, v4, v0, 0x3f35f0e3
	v_pk_mul_f32 v[0:1], v[2:3], v[2:3]
	v_fmaak_f32 v6, v4, v6, 0xbe11a98e
	v_mul_f32_e32 v0, 0xbf38aa3b, v0
	v_exp_f32_e32 v0, v0
	v_fmaak_f32 v6, v4, v6, 0x3e027906
	v_mul_f32_e32 v4, v4, v6
	v_fma_f32 v6, |v3|, s84, 1.0
	v_rcp_f32_e32 v6, v6
	v_mul_f32_e32 v0, v0, v4
	v_mul_f32_e32 v4, v2, v0
	v_fma_f32 v0, -v2, v0, v2
	v_cmp_gt_f32_e64 s[0:1], 0, v2
	v_mul_f32_e32 v1, 0xbf38aa3b, v1
	v_exp_f32_e32 v1, v1
	v_cndmask_b32_e64 v0, v0, v4, s[0:1]
	v_mul_f32_e32 v4, v156, v0
	v_fmamk_f32 v0, v6, 0x3f07dc22, v241
	v_fmaak_f32 v0, v6, v0, 0x3f35f0e3
	v_fmaak_f32 v0, v6, v0, 0xbe11a98e
	v_fmaak_f32 v0, v6, v0, 0x3e027906
	v_mul_f32_e32 v0, v6, v0
	v_mul_f32_e32 v0, v1, v0
	v_mul_f32_e32 v1, v3, v0
	v_fma_f32 v0, -v3, v0, v3
	v_cmp_gt_f32_e64 s[0:1], 0, v3
	v_cvt_pk_bf16_f32 v2, v154, v5
	s_nop 1
	v_cndmask_b32_e64 v0, v0, v1, s[0:1]
	v_mul_f32_e32 v3, v157, v0
	v_cvt_pk_bf16_f32 v3, v4, v3
	v_lshl_add_u64 v[4:5], s[80:81], 0, v[220:221]
	v_cvt_pk_bf16_f32 v0, v233, v168
	v_cvt_pk_bf16_f32 v1, v160, v161
	v_lshl_add_u64 v[160:161], v[4:5], 0, v[186:187]
	global_store_dwordx4 v[160:161], v[0:3], off
	s_nop 1
	v_max_i32_e32 v0, 1, v224
	v_add_u32_e32 v4, -1, v0
	v_max_i32_e32 v0, 2, v224
	v_add_u32_e32 v158, -2, v0
	v_mov_b64_e32 v[0:1], s[30:31]
	v_mad_i64_i32 v[2:3], s[0:1], v224, s76, v[0:1]
	v_lshl_add_u64 v[162:163], v[2:3], 0, v[186:187]
	v_mad_u64_u32 v[2:3], s[0:1], v4, s76, v[0:1]
	v_mad_u64_u32 v[0:1], s[0:1], v158, s76, v[0:1]
	v_lshl_add_u64 v[166:167], v[0:1], 0, v[186:187]
	v_lshl_add_u64 v[164:165], v[2:3], 0, v[186:187]
	v_cmp_gt_i32_e64 s[54:55], s77, v224
	s_movk_i32 s0, 0x1fff
	s_waitcnt vmcnt(1)
	v_mov_b64_e32 v[154:155], v[196:197]
	v_mov_b64_e32 v[156:157], v[198:199]
	v_mov_b64_e32 v[4:5], v[200:201]
	v_mov_b64_e32 v[6:7], v[202:203]
	v_mov_b64_e32 v[0:1], v[242:243]
	v_mov_b64_e32 v[2:3], v[244:245]
	v_lshlrev_b32_e32 v168, 16, v0
	v_cndmask_b32_e64 v158, v228, v224, s[54:55]
	v_and_b32_e32 v169, 0xffff0000, v0
	v_lshlrev_b32_e32 v170, 16, v1
	v_and_b32_e32 v171, 0xffff0000, v1
	v_lshlrev_b32_e32 v216, 16, v2
	v_and_b32_e32 v217, 0xffff0000, v2
	v_lshlrev_b32_e32 v218, 16, v3
	v_and_b32_e32 v219, 0xffff0000, v3
	v_lshlrev_b32_e32 v0, 16, v4
	v_and_b32_e32 v1, 0xffff0000, v4
	v_lshlrev_b32_e32 v2, 16, v5
	v_and_b32_e32 v3, 0xffff0000, v5
	v_lshlrev_b32_e32 v4, 16, v6
	v_and_b32_e32 v5, 0xffff0000, v6
	v_lshlrev_b32_e32 v6, 16, v7
	v_and_b32_e32 v7, 0xffff0000, v7
	v_cmp_gt_i32_e64 s[60:61], 2, v158
	v_cmp_lt_i32_e64 s[40:41], s0, v224
	v_cmp_eq_u32_e64 s[42:43], 0, v158
	v_ashrrev_i32_e32 v159, 31, v158
	s_and_saveexec_b64 s[0:1], s[60:61]
	s_cbranch_execz .LBB0_1223
	s_add_i32 s8, s5, 0xffffe010
	s_ashr_i32 s8, s8, 4
	v_mov_b32_e32 v168, s8
	v_cndmask_b32_e64 v170, v168, 0, s[54:55]
	v_ashrrev_i32_e32 v171, 31, v170
	v_lshl_add_u64 v[168:169], v[170:171], 1, v[158:159]
	v_mov_b64_e32 v[194:195], s[68:69]
	v_mad_u64_u32 v[194:195], s[8:9], v168, s13, v[194:195]
	v_mad_i32_i24 v195, v169, s13, v195
	v_lshl_add_u64 v[222:223], v[184:185], 2, v[194:195]
	v_mov_b32_e32 v168, 0
	s_and_saveexec_b64 s[8:9], s[40:41]
	s_cbranch_execz .LBB0_1176
	global_load_dword v168, v[222:223], off

; __device__ __forceinline__ unsigned pk2(float lo, float hi) { unsigned r; asm("v_cvt_pk_bf16_f32 %0, %1, %2" : "=v"(r) : "v"(lo), "v"(hi)); return r; }
;     static __device__ __forceinline__ void unpack8(const u32x4 q, float (&x)[8]) { x[0] = bflo(q.x); x[1] = bfhi(q.x); x[2] = bflo(q.y); x[3] = bfhi(q.y); x[4] = bflo(q.z); x[5] = bfhi(q.z); x[6] = bflo(q.w); x[7] = bfhi(q.w); }
;     __device__ __forceinline__ void operator()(EPI_ARGS) const {
;     ...
;                     for (int t = 0; t < 1; ++t) { const int row = row0 + ai * 128 + (mp + t) * 16; const int r1 = row > 0 ? row - 1 : 0, r2 = row > 1 ? row - 2 : 0;
;                         q2[t] = *(const u32x4*)(up + (size_t)row * DFF + col); q1[t] = *(const u32x4*)(up + (size_t)r1 * DFF + col); q0[t] = *(const u32x4*)(up + (size_t)r2 * DFF + col); }
;                     __builtin_amdgcn_sched_barrier(0);
; #pragma unroll
;                     for (int t = 0; t < 1; ++t) { const int m = mp + t, row = row0 + ai * 128 + m * 16;
;                         const int i = row < TP ? row : ((row - TP) & 15); const int sidx = row < TP ? 0 : ((row - TP) >> 4);
;                         float x0[8], x1[8], x2[8]; unpack8(q0[t], x0); unpack8(q1[t], x1); unpack8(q2[t], x2);
;                         if (i < 2) {
;                             const bool smp = row >= TP; const float* p0 = cs + ((size_t)sidx * 2 + i) * DFF + col; const float* p1 = cs + ((size_t)sidx * 2 + 1) * DFF + col;
; #pragma unroll
;                             for (int e = 0; e < 8; ++e) { x0[e] = smp ? p0[e] : 0.f; if (i == 0) x1[e] = smp ? p1[e] : 0.f; } }
;                         float r[8];
; #pragma unroll
;                         for (int e = 0; e < 8; ++e) { const float cv = bb[e] + x0[e] * w0[e] + x1[e] * w1[e] + x2[e] * w2[e]; r[e] = gelu_f(cv) * acc[ai][bj][m][e >> 2][e & 3]; }
;                         u32x4 w; w.x = pk2(r[0], r[1]); w.y = pk2(r[2], r[3]); w.z = pk2(r[4], r[5]); w.w = pk2(r[6], r[7]);
;                         *(u32x4*)(act + (size_t)row * DFF + col) = w; } } } }
.LBB0_1221:
	s_or_b64 exec, exec, s[14:15]
.LBB0_1222:
	s_or_b64 exec, exec, s[8:9]
	s_waitcnt vmcnt(0)
.LBB0_1223:
	s_or_b64 exec, exec, s[0:1]
	v_mad_i64_i32 v[220:221], s[0:1], v224, s76, 0
	v_lshlrev_b32_e32 v194, 16, v154
	v_and_b32_e32 v154, 0xffff0000, v154
	v_lshlrev_b32_e32 v222, 16, v155
	v_and_b32_e32 v224, 0xffff0000, v155
	s_waitcnt vmcnt(1)
	v_add_u32_e32 v240, 32, v232
	v_mov_b64_e32 v[238:239], s[30:31]
	v_mad_i64_i32 v[238:239], s[0:1], v240, s76, v[238:239]
	v_lshl_add_u64 v[238:239], v[238:239], 0, v[186:187]
	global_load_dwordx4 v[196:199], v[238:239], off
	v_add_u32_e32 v240, -1, v240
	v_mov_b64_e32 v[246:247], s[30:31]
	v_mad_i64_i32 v[246:247], s[0:1], v240, s76, v[246:247]
	v_lshl_add_u64 v[246:247], v[246:247], 0, v[186:187]
	global_load_dwordx4 v[200:203], v[246:247], off
	v_add_u32_e32 v240, -1, v240
	v_mov_b64_e32 v[238:239], s[30:31]
	v_mad_i64_i32 v[238:239], s[0:1], v240, s76, v[238:239]
	v_lshl_add_u64 v[238:239], v[238:239], 0, v[186:187]
	global_load_dwordx4 v[242:245], v[238:239], off
	v_mov_b32_e32 v195, v0
	v_mov_b32_e32 v155, v1
	v_pk_mul_f32 v[194:195], v[210:211], v[194:195]
	v_pk_mul_f32 v[0:1], v[106:107], v[154:155]
	v_pk_fma_f32 v[154:155], v[102:103], v[168:169], v[110:111]
	v_mov_b32_e32 v168, v195
	v_mov_b32_e32 v169, v1
	v_pk_add_f32 v[154:155], v[168:169], v[154:155]
	v_mov_b32_e32 v195, v0
	v_pk_add_f32 v[0:1], v[194:195], v[154:155]
	v_lshlrev_b32_e32 v226, 16, v156
	v_fma_f32 v154, |v0|, s84, 1.0
	v_rcp_f32_e32 v155, v154
	v_pk_mul_f32 v[194:195], v[0:1], v[0:1]
	v_and_b32_e32 v154, 0xffff0000, v156
	v_lshlrev_b32_e32 v156, 16, v157
	v_and_b32_e32 v168, 0xffff0000, v157
	v_fmamk_f32 v157, v155, 0x3f07dc22, v241
	v_mul_f32_e32 v169, 0xbf38aa3b, v194
	v_fmaak_f32 v157, v155, v157, 0x3f35f0e3
	v_exp_f32_e32 v169, v169
	v_fmaak_f32 v157, v155, v157, 0xbe11a98e
	v_fmaak_f32 v157, v155, v157, 0x3e027906
	v_mul_f32_e32 v155, v155, v157
	v_mul_f32_e32 v155, v169, v155
	v_fma_f32 v169, |v1|, s84, 1.0
	v_rcp_f32_e32 v169, v169
	v_mul_f32_e32 v157, v0, v155
	v_fma_f32 v155, -v0, v155, v0
	v_cmp_gt_f32_e64 s[0:1], 0, v0
	v_mov_b32_e32 v223, v2
	v_mov_b32_e32 v225, v3
	v_cndmask_b32_e64 v0, v155, v157, s[0:1]
	v_mul_f32_e32 v233, v150, v0
	v_mul_f32_e32 v150, 0xbf38aa3b, v195
	v_pk_mul_f32 v[194:195], v[172:173], v[222:223]
	v_pk_mul_f32 v[2:3], v[108:109], v[224:225]
	v_fmamk_f32 v0, v169, 0x3f07dc22, v241
	v_pk_fma_f32 v[170:171], v[104:105], v[170:171], v[112:113]
	v_mov_b32_e32 v222, v195
	v_mov_b32_e32 v223, v3
	v_fmaak_f32 v0, v169, v0, 0x3f35f0e3
	v_exp_f32_e32 v150, v150
	v_pk_add_f32 v[170:171], v[222:223], v[170:171]
	v_mov_b32_e32 v195, v2
	v_fmaak_f32 v0, v169, v0, 0xbe11a98e
	v_pk_add_f32 v[2:3], v[194:195], v[170:171]
	v_fmaak_f32 v0, v169, v0, 0x3e027906
	v_fma_f32 v155, |v2|, s84, 1.0
	v_mul_f32_e32 v0, v169, v0
	v_rcp_f32_e32 v155, v155
	v_mul_f32_e32 v0, v150, v0
	v_mul_f32_e32 v150, v1, v0
	v_fma_f32 v0, -v1, v0, v1
	v_cmp_gt_f32_e64 s[0:1], 0, v1
	v_mov_b32_e32 v227, v4
	v_mov_b32_e32 v169, v7
	v_cndmask_b32_e64 v0, v0, v150, s[0:1]
	v_mul_f32_e32 v170, v151, v0
	v_fmamk_f32 v0, v155, 0x3f07dc22, v241
	v_fmaak_f32 v150, v155, v0, 0x3f35f0e3
	v_pk_mul_f32 v[0:1], v[2:3], v[2:3]
	v_fmaak_f32 v150, v155, v150, 0xbe11a98e
	v_mul_f32_e32 v0, 0xbf38aa3b, v0
	v_exp_f32_e32 v0, v0
	v_fmaak_f32 v150, v155, v150, 0x3e027906
	v_fma_f32 v151, |v3|, s84, 1.0
	v_mul_f32_e32 v150, v155, v150
	v_rcp_f32_e32 v151, v151
	v_mul_f32_e32 v0, v0, v150
	v_mul_f32_e32 v150, v2, v0
	v_fma_f32 v0, -v2, v0, v2
	v_cmp_gt_f32_e64 s[0:1], 0, v2
	v_mul_f32_e32 v1, 0xbf38aa3b, v1
	v_exp_f32_e32 v1, v1
	v_cndmask_b32_e64 v0, v0, v150, s[0:1]
	v_mul_f32_e32 v152, v152, v0
	v_fmamk_f32 v0, v151, 0x3f07dc22, v241
	v_fmaak_f32 v0, v151, v0, 0x3f35f0e3
	v_fmaak_f32 v0, v151, v0, 0xbe11a98e
	v_fmaak_f32 v0, v151, v0, 0x3e027906
	v_mul_f32_e32 v0, v151, v0
	v_mul_f32_e32 v0, v1, v0
	v_mov_b32_e32 v155, v5
	v_mul_f32_e32 v2, v3, v0
	v_fma_f32 v157, -v3, v0, v3
	v_pk_mul_f32 v[0:1], v[212:213], v[226:227]
	v_pk_mul_f32 v[4:5], v[94:95], v[154:155]
	v_pk_fma_f32 v[150:151], v[90:91], v[216:217], v[98:99]
	v_mov_b32_e32 v154, v1
	v_mov_b32_e32 v155, v5
	v_pk_add_f32 v[150:151], v[154:155], v[150:151]
	v_mov_b32_e32 v1, v4
	v_pk_add_f32 v[0:1], v[0:1], v[150:151]
	v_cmp_gt_f32_e64 s[0:1], 0, v3
	v_fma_f32 v4, |v0|, s84, 1.0
	v_rcp_f32_e32 v4, v4
	v_cndmask_b32_e64 v2, v157, v2, s[0:1]
	v_mul_f32_e32 v153, v153, v2
	v_cmp_gt_f32_e64 s[0:1], 0, v0
	v_fmamk_f32 v2, v4, 0x3f07dc22, v241
;     static __device__ __forceinline__ void unpack8(const u32x4 q, float (&x)[8]) { x[0] = bflo(q.x); x[1] = bfhi(q.x); x[2] = bflo(q.y); x[3] = bfhi(q.y); x[4] = bflo(q.z); x[5] = bfhi(q.z); x[6] = bflo(q.w); x[7] = bfhi(q.w); }
;     __device__ __forceinline__ void operator()(EPI_ARGS) const {
;     ...
;                     for (int t = 0; t < 1; ++t) { const int row = row0 + ai * 128 + (mp + t) * 16; const int r1 = row > 0 ? row - 1 : 0, r2 = row > 1 ? row - 2 : 0;
;                         q2[t] = *(const u32x4*)(up + (size_t)row * DFF + col); q1[t] = *(const u32x4*)(up + (size_t)r1 * DFF + col); q0[t] = *(const u32x4*)(up + (size_t)r2 * DFF + col); }
;                     __builtin_amdgcn_sched_barrier(0);
; #pragma unroll
;                     for (int t = 0; t < 1; ++t) { const int m = mp + t, row = row0 + ai * 128 + m * 16;
;                         const int i = row < TP ? row : ((row - TP) & 15); const int sidx = row < TP ? 0 : ((row - TP) >> 4);
;                         float x0[8], x1[8], x2[8]; unpack8(q0[t], x0); unpack8(q1[t], x1); unpack8(q2[t], x2);
;                         if (i < 2) {
;                             const bool smp = row >= TP; const float* p0 = cs + ((size_t)sidx * 2 + i) * DFF + col; const float* p1 = cs + ((size_t)sidx * 2 + 1) * DFF + col;
; #pragma unroll
;                             for (int e = 0; e < 8; ++e) { x0[e] = smp ? p0[e] : 0.f; if (i == 0) x1[e] = smp ? p1[e] : 0.f; } }
	v_fmaak_f32 v5, v4, v2, 0x3f35f0e3
	v_pk_mul_f32 v[2:3], v[0:1], v[0:1]
	v_fmaak_f32 v5, v4, v5, 0xbe11a98e
	v_mul_f32_e32 v2, 0xbf38aa3b, v2
	v_exp_f32_e32 v2, v2
	v_fmaak_f32 v5, v4, v5, 0x3e027906
	v_mul_f32_e32 v4, v4, v5
	v_fma_f32 v5, |v1|, s84, 1.0
	v_rcp_f32_e32 v5, v5
	v_mul_f32_e32 v2, v2, v4
	v_mul_f32_e32 v4, v0, v2
	v_fma_f32 v2, -v0, v2, v0
	v_cndmask_b32_e64 v0, v2, v4, s[0:1]
	v_mul_f32_e32 v146, v146, v0
	v_fmamk_f32 v0, v5, 0x3f07dc22, v241
	v_mul_f32_e32 v2, 0xbf38aa3b, v3
	v_fmaak_f32 v0, v5, v0, 0x3f35f0e3
	v_exp_f32_e32 v2, v2
	v_fmaak_f32 v0, v5, v0, 0xbe11a98e
	v_fmaak_f32 v0, v5, v0, 0x3e027906
	v_mul_f32_e32 v0, v5, v0
	v_mov_b32_e32 v157, v6
	v_mul_f32_e32 v0, v2, v0
	v_pk_mul_f32 v[2:3], v[214:215], v[156:157]
	v_pk_mul_f32 v[4:5], v[96:97], v[168:169]
	v_pk_fma_f32 v[6:7], v[92:93], v[218:219], v[100:101]
	v_mov_b32_e32 v150, v3
	v_mov_b32_e32 v151, v5
	v_pk_add_f32 v[6:7], v[150:151], v[6:7]
	v_mov_b32_e32 v3, v4
	v_pk_add_f32 v[2:3], v[2:3], v[6:7]
	v_mul_f32_e32 v154, v1, v0
	v_fma_f32 v4, |v2|, s84, 1.0
	v_rcp_f32_e32 v4, v4
	v_fma_f32 v0, -v1, v0, v1
	v_cmp_gt_f32_e64 s[0:1], 0, v1
	v_or_b32_e32 v226, 32, v232
	s_nop 0
	v_cndmask_b32_e64 v0, v0, v154, s[0:1]
	v_mul_f32_e32 v5, v147, v0
	v_fmamk_f32 v0, v4, 0x3f07dc22, v241
	v_fmaak_f32 v6, v4, v0, 0x3f35f0e3
	v_pk_mul_f32 v[0:1], v[2:3], v[2:3]
	v_fmaak_f32 v6, v4, v6, 0xbe11a98e
	v_mul_f32_e32 v0, 0xbf38aa3b, v0
	v_exp_f32_e32 v0, v0
	v_fmaak_f32 v6, v4, v6, 0x3e027906
	v_mul_f32_e32 v4, v4, v6
	v_fma_f32 v6, |v3|, s84, 1.0
	v_rcp_f32_e32 v6, v6
	v_mul_f32_e32 v0, v0, v4
	v_mul_f32_e32 v4, v2, v0
	v_fma_f32 v0, -v2, v0, v2
	v_cmp_gt_f32_e64 s[0:1], 0, v2
	v_mul_f32_e32 v1, 0xbf38aa3b, v1
	v_exp_f32_e32 v1, v1
	v_cndmask_b32_e64 v0, v0, v4, s[0:1]
	v_mul_f32_e32 v4, v148, v0
	v_fmamk_f32 v0, v6, 0x3f07dc22, v241
	v_fmaak_f32 v0, v6, v0, 0x3f35f0e3
	v_fmaak_f32 v0, v6, v0, 0xbe11a98e
	v_fmaak_f32 v0, v6, v0, 0x3e027906
	v_mul_f32_e32 v0, v6, v0
	v_mul_f32_e32 v0, v1, v0
	v_mul_f32_e32 v1, v3, v0
	v_fma_f32 v0, -v3, v0, v3
	v_cmp_gt_f32_e64 s[0:1], 0, v3
	v_cvt_pk_bf16_f32 v2, v146, v5
	s_nop 1
	v_cndmask_b32_e64 v0, v0, v1, s[0:1]
	v_mul_f32_e32 v3, v149, v0
	v_cvt_pk_bf16_f32 v3, v4, v3
	v_lshl_add_u64 v[4:5], s[80:81], 0, v[220:221]
	v_cvt_pk_bf16_f32 v0, v233, v170
	v_cvt_pk_bf16_f32 v1, v152, v153
	v_lshl_add_u64 v[152:153], v[4:5], 0, v[186:187]
	global_store_dwordx4 v[152:153], v[0:3], off
	s_nop 1
	v_max_i32_e32 v0, 1, v226
	v_add_u32_e32 v4, -1, v0
	v_max_i32_e32 v0, 2, v226
	v_add_u32_e32 v150, -2, v0
	v_mov_b64_e32 v[0:1], s[30:31]
	v_mad_i64_i32 v[2:3], s[0:1], v226, s76, v[0:1]
	v_lshl_add_u64 v[154:155], v[2:3], 0, v[186:187]
	v_mad_u64_u32 v[2:3], s[0:1], v4, s76, v[0:1]
	v_mad_u64_u32 v[0:1], s[0:1], v150, s76, v[0:1]
	v_lshl_add_u64 v[168:169], v[0:1], 0, v[186:187]
	v_lshl_add_u64 v[156:157], v[2:3], 0, v[186:187]
	v_cmp_gt_i32_e64 s[58:59], s77, v226
	s_movk_i32 s0, 0x1fff
	s_waitcnt vmcnt(1)
	v_mov_b64_e32 v[146:147], v[196:197]
	v_mov_b64_e32 v[148:149], v[198:199]
	v_mov_b64_e32 v[4:5], v[200:201]
	v_mov_b64_e32 v[6:7], v[202:203]
	v_mov_b64_e32 v[0:1], v[242:243]
	v_mov_b64_e32 v[2:3], v[244:245]
	v_lshlrev_b32_e32 v170, 16, v0
	v_cndmask_b32_e64 v150, v228, v226, s[58:59]
	v_and_b32_e32 v171, 0xffff0000, v0
	v_lshlrev_b32_e32 v216, 16, v1
	v_and_b32_e32 v217, 0xffff0000, v1
	v_lshlrev_b32_e32 v218, 16, v2
	v_and_b32_e32 v219, 0xffff0000, v2
	v_lshlrev_b32_e32 v220, 16, v3
	v_and_b32_e32 v221, 0xffff0000, v3
	v_lshlrev_b32_e32 v0, 16, v4
	v_and_b32_e32 v1, 0xffff0000, v4
	v_lshlrev_b32_e32 v2, 16, v5
	v_and_b32_e32 v3, 0xffff0000, v5
	v_lshlrev_b32_e32 v4, 16, v6
	v_and_b32_e32 v5, 0xffff0000, v6
	v_lshlrev_b32_e32 v6, 16, v7
	v_and_b32_e32 v7, 0xffff0000, v7
	v_cmp_gt_i32_e64 s[64:65], 2, v150
	v_cmp_lt_i32_e64 s[44:45], s0, v226
	v_cmp_eq_u32_e64 s[46:47], 0, v150
	v_ashrrev_i32_e32 v151, 31, v150
	s_and_saveexec_b64 s[0:1], s[64:65]
	s_cbranch_execz .LBB0_1273
	s_add_i32 s8, s5, 0xffffe020
	s_ashr_i32 s8, s8, 4
	v_mov_b32_e32 v170, s8
	v_cndmask_b32_e64 v216, v170, 0, s[58:59]
	v_ashrrev_i32_e32 v217, 31, v216
	v_lshl_add_u64 v[170:171], v[216:217], 1, v[150:151]
	v_mov_b64_e32 v[194:195], s[68:69]
	v_mad_u64_u32 v[194:195], s[8:9], v170, s13, v[194:195]
	v_mad_i32_i24 v195, v171, s13, v195
	v_lshl_add_u64 v[224:225], v[184:185], 2, v[194:195]
	v_mov_b32_e32 v170, 0
	s_and_saveexec_b64 s[8:9], s[44:45]
	s_cbranch_execz .LBB0_1226
	global_load_dword v170, v[224:225], off

; __device__ __forceinline__ unsigned pk2(float lo, float hi) { unsigned r; asm("v_cvt_pk_bf16_f32 %0, %1, %2" : "=v"(r) : "v"(lo), "v"(hi)); return r; }
;     static __device__ __forceinline__ void unpack8(const u32x4 q, float (&x)[8]) { x[0] = bflo(q.x); x[1] = bfhi(q.x); x[2] = bflo(q.y); x[3] = bfhi(q.y); x[4] = bflo(q.z); x[5] = bfhi(q.z); x[6] = bflo(q.w); x[7] = bfhi(q.w); }
;     __device__ __forceinline__ void operator()(EPI_ARGS) const {
;     ...
;                     for (int t = 0; t < 1; ++t) { const int row = row0 + ai * 128 + (mp + t) * 16; const int r1 = row > 0 ? row - 1 : 0, r2 = row > 1 ? row - 2 : 0;
;                         q2[t] = *(const u32x4*)(up + (size_t)row * DFF + col); q1[t] = *(const u32x4*)(up + (size_t)r1 * DFF + col); q0[t] = *(const u32x4*)(up + (size_t)r2 * DFF + col); }
;                     __builtin_amdgcn_sched_barrier(0);
; #pragma unroll
;                     for (int t = 0; t < 1; ++t) { const int m = mp + t, row = row0 + ai * 128 + m * 16;
;                         const int i = row < TP ? row : ((row - TP) & 15); const int sidx = row < TP ? 0 : ((row - TP) >> 4);
;                         float x0[8], x1[8], x2[8]; unpack8(q0[t], x0); unpack8(q1[t], x1); unpack8(q2[t], x2);
;                         if (i < 2) {
;                             const bool smp = row >= TP; const float* p0 = cs + ((size_t)sidx * 2 + i) * DFF + col; const float* p1 = cs + ((size_t)sidx * 2 + 1) * DFF + col;
; #pragma unroll
;                             for (int e = 0; e < 8; ++e) { x0[e] = smp ? p0[e] : 0.f; if (i == 0) x1[e] = smp ? p1[e] : 0.f; } }
;                         float r[8];
; #pragma unroll
;                         for (int e = 0; e < 8; ++e) { const float cv = bb[e] + x0[e] * w0[e] + x1[e] * w1[e] + x2[e] * w2[e]; r[e] = gelu_f(cv) * acc[ai][bj][m][e >> 2][e & 3]; }
;                         u32x4 w; w.x = pk2(r[0], r[1]); w.y = pk2(r[2], r[3]); w.z = pk2(r[4], r[5]); w.w = pk2(r[6], r[7]);
;                         *(u32x4*)(act + (size_t)row * DFF + col) = w; } } } }
.LBB0_1271:
	s_or_b64 exec, exec, s[14:15]
.LBB0_1272:
	s_or_b64 exec, exec, s[8:9]
	s_waitcnt vmcnt(0)
.LBB0_1273:
	s_or_b64 exec, exec, s[0:1]
	v_mad_i64_i32 v[222:223], s[0:1], v226, s76, 0
	v_lshlrev_b32_e32 v194, 16, v146
	v_and_b32_e32 v146, 0xffff0000, v146
	v_lshlrev_b32_e32 v224, 16, v147
	v_and_b32_e32 v226, 0xffff0000, v147
	s_waitcnt vmcnt(1)
	v_add_u32_e32 v240, 48, v232
	v_mov_b64_e32 v[238:239], s[30:31]
	v_mad_i64_i32 v[238:239], s[0:1], v240, s76, v[238:239]
	v_lshl_add_u64 v[238:239], v[238:239], 0, v[186:187]
	global_load_dwordx4 v[196:199], v[238:239], off
	v_add_u32_e32 v240, -1, v240
	v_mov_b64_e32 v[246:247], s[30:31]
	v_mad_i64_i32 v[246:247], s[0:1], v240, s76, v[246:247]
	v_lshl_add_u64 v[246:247], v[246:247], 0, v[186:187]
	global_load_dwordx4 v[200:203], v[246:247], off
	v_add_u32_e32 v240, -1, v240
	v_mov_b64_e32 v[238:239], s[30:31]
	v_mad_i64_i32 v[238:239], s[0:1], v240, s76, v[238:239]
	v_lshl_add_u64 v[238:239], v[238:239], 0, v[186:187]
	global_load_dwordx4 v[242:245], v[238:239], off
	v_mov_b32_e32 v195, v0
	v_mov_b32_e32 v147, v1
	v_pk_mul_f32 v[194:195], v[210:211], v[194:195]
	v_pk_mul_f32 v[0:1], v[106:107], v[146:147]
	v_pk_fma_f32 v[146:147], v[102:103], v[170:171], v[110:111]
	v_mov_b32_e32 v170, v195
	v_mov_b32_e32 v171, v1
	v_pk_add_f32 v[146:147], v[170:171], v[146:147]
	v_mov_b32_e32 v195, v0
	v_pk_add_f32 v[0:1], v[194:195], v[146:147]
	v_lshlrev_b32_e32 v234, 16, v148
	v_fma_f32 v146, |v0|, s84, 1.0
	v_rcp_f32_e32 v147, v146
	v_pk_mul_f32 v[194:195], v[0:1], v[0:1]
	v_and_b32_e32 v146, 0xffff0000, v148
	v_lshlrev_b32_e32 v148, 16, v149
	v_and_b32_e32 v170, 0xffff0000, v149
	v_fmamk_f32 v149, v147, 0x3f07dc22, v241
	v_mul_f32_e32 v171, 0xbf38aa3b, v194
	v_fmaak_f32 v149, v147, v149, 0x3f35f0e3
	v_exp_f32_e32 v171, v171
	v_fmaak_f32 v149, v147, v149, 0xbe11a98e
	v_fmaak_f32 v149, v147, v149, 0x3e027906
	v_mul_f32_e32 v147, v147, v149
	v_mul_f32_e32 v147, v171, v147
	v_fma_f32 v171, |v1|, s84, 1.0
	v_rcp_f32_e32 v171, v171
	v_mul_f32_e32 v149, v0, v147
	v_fma_f32 v147, -v0, v147, v0
	v_cmp_gt_f32_e64 s[0:1], 0, v0
	v_mov_b32_e32 v225, v2
	v_mov_b32_e32 v227, v3
	v_cndmask_b32_e64 v0, v147, v149, s[0:1]
	v_mul_f32_e32 v233, v142, v0
	v_mul_f32_e32 v142, 0xbf38aa3b, v195
	v_pk_mul_f32 v[194:195], v[172:173], v[224:225]
	v_pk_mul_f32 v[2:3], v[108:109], v[226:227]
	v_fmamk_f32 v0, v171, 0x3f07dc22, v241
	v_pk_fma_f32 v[216:217], v[104:105], v[216:217], v[112:113]
	v_mov_b32_e32 v224, v195
	v_mov_b32_e32 v225, v3
	v_fmaak_f32 v0, v171, v0, 0x3f35f0e3
	v_exp_f32_e32 v142, v142
	v_pk_add_f32 v[216:217], v[224:225], v[216:217]
	v_mov_b32_e32 v195, v2
	v_fmaak_f32 v0, v171, v0, 0xbe11a98e
	v_pk_add_f32 v[2:3], v[194:195], v[216:217]
	v_fmaak_f32 v0, v171, v0, 0x3e027906
	v_fma_f32 v147, |v2|, s84, 1.0
	v_mul_f32_e32 v0, v171, v0
	v_rcp_f32_e32 v147, v147
	v_mul_f32_e32 v0, v142, v0
	v_mul_f32_e32 v142, v1, v0
	v_fma_f32 v0, -v1, v0, v1
	v_cmp_gt_f32_e64 s[0:1], 0, v1
	v_mov_b32_e32 v235, v4
	v_mov_b32_e32 v171, v7
	v_cndmask_b32_e64 v0, v0, v142, s[0:1]
	v_mul_f32_e32 v194, v143, v0
	v_fmamk_f32 v0, v147, 0x3f07dc22, v241
	v_fmaak_f32 v142, v147, v0, 0x3f35f0e3
	v_pk_mul_f32 v[0:1], v[2:3], v[2:3]
	v_fmaak_f32 v142, v147, v142, 0xbe11a98e
	v_mul_f32_e32 v0, 0xbf38aa3b, v0
	v_exp_f32_e32 v0, v0
	v_fmaak_f32 v142, v147, v142, 0x3e027906
	v_fma_f32 v143, |v3|, s84, 1.0
	v_mul_f32_e32 v142, v147, v142
	v_rcp_f32_e32 v143, v143
	v_mul_f32_e32 v0, v0, v142
	v_mul_f32_e32 v142, v2, v0
	v_fma_f32 v0, -v2, v0, v2
	v_cmp_gt_f32_e64 s[0:1], 0, v2
	v_mul_f32_e32 v1, 0xbf38aa3b, v1
	v_exp_f32_e32 v1, v1
	v_cndmask_b32_e64 v0, v0, v142, s[0:1]
	v_mul_f32_e32 v144, v144, v0
	v_fmamk_f32 v0, v143, 0x3f07dc22, v241
	v_fmaak_f32 v0, v143, v0, 0x3f35f0e3
	v_fmaak_f32 v0, v143, v0, 0xbe11a98e
	v_fmaak_f32 v0, v143, v0, 0x3e027906
	v_mul_f32_e32 v0, v143, v0
	v_mul_f32_e32 v0, v1, v0
	v_mov_b32_e32 v147, v5
	v_mul_f32_e32 v2, v3, v0
	v_fma_f32 v149, -v3, v0, v3
	v_pk_mul_f32 v[0:1], v[212:213], v[234:235]
	v_pk_mul_f32 v[4:5], v[94:95], v[146:147]
	v_pk_fma_f32 v[142:143], v[90:91], v[218:219], v[98:99]
	v_mov_b32_e32 v146, v1
	v_mov_b32_e32 v147, v5
	v_pk_add_f32 v[142:143], v[146:147], v[142:143]
	v_mov_b32_e32 v1, v4
	v_pk_add_f32 v[0:1], v[0:1], v[142:143]
	v_cmp_gt_f32_e64 s[0:1], 0, v3
	v_fma_f32 v4, |v0|, s84, 1.0
	v_rcp_f32_e32 v4, v4
	v_cndmask_b32_e64 v2, v149, v2, s[0:1]
	v_mul_f32_e32 v145, v145, v2
	v_cmp_gt_f32_e64 s[0:1], 0, v0
	v_fmamk_f32 v2, v4, 0x3f07dc22, v241
;     static __device__ __forceinline__ void unpack8(const u32x4 q, float (&x)[8]) { x[0] = bflo(q.x); x[1] = bfhi(q.x); x[2] = bflo(q.y); x[3] = bfhi(q.y); x[4] = bflo(q.z); x[5] = bfhi(q.z); x[6] = bflo(q.w); x[7] = bfhi(q.w); }
;     __device__ __forceinline__ void operator()(EPI_ARGS) const {
;     ...
;                     for (int t = 0; t < 1; ++t) { const int row = row0 + ai * 128 + (mp + t) * 16; const int r1 = row > 0 ? row - 1 : 0, r2 = row > 1 ? row - 2 : 0;
;                         q2[t] = *(const u32x4*)(up + (size_t)row * DFF + col); q1[t] = *(const u32x4*)(up + (size_t)r1 * DFF + col); q0[t] = *(const u32x4*)(up + (size_t)r2 * DFF + col); }
;                     __builtin_amdgcn_sched_barrier(0);
; #pragma unroll
;                     for (int t = 0; t < 1; ++t) { const int m = mp + t, row = row0 + ai * 128 + m * 16;
;                         const int i = row < TP ? row : ((row - TP) & 15); const int sidx = row < TP ? 0 : ((row - TP) >> 4);
;                         float x0[8], x1[8], x2[8]; unpack8(q0[t], x0); unpack8(q1[t], x1); unpack8(q2[t], x2);
;                         if (i < 2) {
;                             const bool smp = row >= TP; const float* p0 = cs + ((size_t)sidx * 2 + i) * DFF + col; const float* p1 = cs + ((size_t)sidx * 2 + 1) * DFF + col;
; #pragma unroll
;                             for (int e = 0; e < 8; ++e) { x0[e] = smp ? p0[e] : 0.f; if (i == 0) x1[e] = smp ? p1[e] : 0.f; } }
	v_fmaak_f32 v5, v4, v2, 0x3f35f0e3
	v_pk_mul_f32 v[2:3], v[0:1], v[0:1]
	v_fmaak_f32 v5, v4, v5, 0xbe11a98e
	v_mul_f32_e32 v2, 0xbf38aa3b, v2
	v_exp_f32_e32 v2, v2
	v_fmaak_f32 v5, v4, v5, 0x3e027906
	v_mul_f32_e32 v4, v4, v5
	v_fma_f32 v5, |v1|, s84, 1.0
	v_rcp_f32_e32 v5, v5
	v_mul_f32_e32 v2, v2, v4
	v_mul_f32_e32 v4, v0, v2
	v_fma_f32 v2, -v0, v2, v0
	v_cndmask_b32_e64 v0, v2, v4, s[0:1]
	v_mul_f32_e32 v138, v138, v0
	v_fmamk_f32 v0, v5, 0x3f07dc22, v241
	v_mul_f32_e32 v2, 0xbf38aa3b, v3
	v_fmaak_f32 v0, v5, v0, 0x3f35f0e3
	v_exp_f32_e32 v2, v2
	v_fmaak_f32 v0, v5, v0, 0xbe11a98e
	v_fmaak_f32 v0, v5, v0, 0x3e027906
	v_mul_f32_e32 v0, v5, v0
	v_mov_b32_e32 v149, v6
	v_mul_f32_e32 v0, v2, v0
	v_pk_mul_f32 v[2:3], v[214:215], v[148:149]
	v_pk_mul_f32 v[4:5], v[96:97], v[170:171]
	v_pk_fma_f32 v[6:7], v[92:93], v[220:221], v[100:101]
	v_mov_b32_e32 v142, v3
	v_mov_b32_e32 v143, v5
	v_pk_add_f32 v[6:7], v[142:143], v[6:7]
	v_mov_b32_e32 v3, v4
	v_pk_add_f32 v[2:3], v[2:3], v[6:7]
	v_mul_f32_e32 v146, v1, v0
	v_fma_f32 v4, |v2|, s84, 1.0
	v_rcp_f32_e32 v4, v4
	v_fma_f32 v0, -v1, v0, v1
	v_cmp_gt_f32_e64 s[0:1], 0, v1
	s_nop 1
	v_cndmask_b32_e64 v0, v0, v146, s[0:1]
	v_mul_f32_e32 v5, v139, v0
	v_fmamk_f32 v0, v4, 0x3f07dc22, v241
	v_fmaak_f32 v6, v4, v0, 0x3f35f0e3
	v_pk_mul_f32 v[0:1], v[2:3], v[2:3]
	v_fmaak_f32 v6, v4, v6, 0xbe11a98e
	v_mul_f32_e32 v0, 0xbf38aa3b, v0
	v_exp_f32_e32 v0, v0
	v_fmaak_f32 v6, v4, v6, 0x3e027906
	v_mul_f32_e32 v4, v4, v6
	v_fma_f32 v6, |v3|, s84, 1.0
	v_rcp_f32_e32 v6, v6
	v_mul_f32_e32 v0, v0, v4
	v_mul_f32_e32 v4, v2, v0
	v_fma_f32 v0, -v2, v0, v2
	v_cmp_gt_f32_e64 s[0:1], 0, v2
	v_mul_f32_e32 v1, 0xbf38aa3b, v1
	v_exp_f32_e32 v1, v1
	v_cndmask_b32_e64 v0, v0, v4, s[0:1]
	v_mul_f32_e32 v4, v140, v0
	v_fmamk_f32 v0, v6, 0x3f07dc22, v241
	v_fmaak_f32 v0, v6, v0, 0x3f35f0e3
	v_fmaak_f32 v0, v6, v0, 0xbe11a98e
	v_fmaak_f32 v0, v6, v0, 0x3e027906
	v_mul_f32_e32 v0, v6, v0
	v_mul_f32_e32 v0, v1, v0
	v_mul_f32_e32 v1, v3, v0
	v_fma_f32 v0, -v3, v0, v3
	v_cmp_gt_f32_e64 s[0:1], 0, v3
	v_cvt_pk_bf16_f32 v2, v138, v5
	s_nop 1
	v_cndmask_b32_e64 v0, v0, v1, s[0:1]
	v_mul_f32_e32 v3, v141, v0
	v_cvt_pk_bf16_f32 v3, v4, v3
	v_lshl_add_u64 v[4:5], s[80:81], 0, v[222:223]
	v_cvt_pk_bf16_f32 v0, v233, v194
	v_cvt_pk_bf16_f32 v1, v144, v145
	v_lshl_add_u64 v[144:145], v[4:5], 0, v[186:187]
	v_or_b32_e32 v233, 48, v232
	global_store_dwordx4 v[144:145], v[0:3], off
	s_nop 1
	v_max_i32_e32 v0, 1, v233
	v_add_u32_e32 v4, -1, v0
	v_max_i32_e32 v0, 2, v233
	v_add_u32_e32 v142, -2, v0
	v_mov_b64_e32 v[0:1], s[30:31]
	v_mad_i64_i32 v[2:3], s[0:1], v233, s76, v[0:1]
	v_lshl_add_u64 v[146:147], v[2:3], 0, v[186:187]
	v_mad_u64_u32 v[2:3], s[0:1], v4, s76, v[0:1]
	v_mad_u64_u32 v[0:1], s[0:1], v142, s76, v[0:1]
	v_lshl_add_u64 v[170:171], v[0:1], 0, v[186:187]
	v_lshl_add_u64 v[148:149], v[2:3], 0, v[186:187]
	v_cmp_gt_i32_e64 s[62:63], s77, v233
	s_movk_i32 s0, 0x1fff
	s_waitcnt vmcnt(1)
	v_mov_b64_e32 v[138:139], v[196:197]
	v_mov_b64_e32 v[140:141], v[198:199]
	v_mov_b64_e32 v[4:5], v[200:201]
	v_mov_b64_e32 v[6:7], v[202:203]
	v_mov_b64_e32 v[0:1], v[242:243]
	v_mov_b64_e32 v[2:3], v[244:245]
	v_lshlrev_b32_e32 v216, 16, v0
	v_cndmask_b32_e64 v142, v228, v233, s[62:63]
	v_and_b32_e32 v217, 0xffff0000, v0
	v_lshlrev_b32_e32 v218, 16, v1
	v_and_b32_e32 v219, 0xffff0000, v1
	v_lshlrev_b32_e32 v220, 16, v2
	v_and_b32_e32 v221, 0xffff0000, v2
	v_lshlrev_b32_e32 v222, 16, v3
	v_and_b32_e32 v223, 0xffff0000, v3
	v_lshlrev_b32_e32 v0, 16, v4
	v_and_b32_e32 v1, 0xffff0000, v4
	v_lshlrev_b32_e32 v2, 16, v5
	v_and_b32_e32 v3, 0xffff0000, v5
	v_lshlrev_b32_e32 v4, 16, v6
	v_and_b32_e32 v5, 0xffff0000, v6
	v_lshlrev_b32_e32 v6, 16, v7
	v_and_b32_e32 v7, 0xffff0000, v7
	v_cmp_gt_i32_e64 s[66:67], 2, v142
	v_cmp_lt_i32_e64 s[48:49], s0, v233
	v_cmp_eq_u32_e64 s[50:51], 0, v142
	v_ashrrev_i32_e32 v143, 31, v142
	s_and_saveexec_b64 s[0:1], s[66:67]
	s_cbranch_execz .LBB0_1323
	s_add_i32 s8, s5, 0xffffe030
	s_ashr_i32 s8, s8, 4
	v_mov_b32_e32 v194, s8
	v_cndmask_b32_e64 v218, v194, 0, s[62:63]
	v_ashrrev_i32_e32 v219, 31, v218
	v_lshl_add_u64 v[194:195], v[218:219], 1, v[142:143]
	v_mov_b64_e32 v[216:217], s[68:69]
	v_mad_u64_u32 v[216:217], s[8:9], v194, s13, v[216:217]
	v_mad_i32_i24 v217, v195, s13, v217
	v_lshl_add_u64 v[226:227], v[184:185], 2, v[216:217]
	v_mov_b32_e32 v216, 0
	s_and_saveexec_b64 s[8:9], s[48:49]
	s_cbranch_execz .LBB0_1276
	global_load_dword v216, v[226:227], off

; __device__ __forceinline__ unsigned pk2(float lo, float hi) { unsigned r; asm("v_cvt_pk_bf16_f32 %0, %1, %2" : "=v"(r) : "v"(lo), "v"(hi)); return r; }
;     static __device__ __forceinline__ void unpack8(const u32x4 q, float (&x)[8]) { x[0] = bflo(q.x); x[1] = bfhi(q.x); x[2] = bflo(q.y); x[3] = bfhi(q.y); x[4] = bflo(q.z); x[5] = bfhi(q.z); x[6] = bflo(q.w); x[7] = bfhi(q.w); }
;     __device__ __forceinline__ void operator()(EPI_ARGS) const {
;     ...
;             for (int ai = 0; ai < 2; ++ai) {
;                 if (u.pm == 32 && ai == 1) continue;
; #pragma unroll
;                 for (int mp = 0; mp < 4; ++mp) {
;                     u32x4 q2[1], q1[1], q0[1];
; #pragma unroll
;                     for (int t = 0; t < 1; ++t) { const int row = row0 + ai * 128 + (mp + t) * 16; const int r1 = row > 0 ? row - 1 : 0, r2 = row > 1 ? row - 2 : 0;
;                         q2[t] = *(const u32x4*)(up + (size_t)row * DFF + col); q1[t] = *(const u32x4*)(up + (size_t)r1 * DFF + col); q0[t] = *(const u32x4*)(up + (size_t)r2 * DFF + col); }
;                     __builtin_amdgcn_sched_barrier(0);
; #pragma unroll
;                     for (int t = 0; t < 1; ++t) { const int m = mp + t, row = row0 + ai * 128 + m * 16;
;                         const int i = row < TP ? row : ((row - TP) & 15); const int sidx = row < TP ? 0 : ((row - TP) >> 4);
;                         float x0[8], x1[8], x2[8]; unpack8(q0[t], x0); unpack8(q1[t], x1); unpack8(q2[t], x2);
;                         if (i < 2) {
;                             const bool smp = row >= TP; const float* p0 = cs + ((size_t)sidx * 2 + i) * DFF + col; const float* p1 = cs + ((size_t)sidx * 2 + 1) * DFF + col;
; #pragma unroll
;                             for (int e = 0; e < 8; ++e) { x0[e] = smp ? p0[e] : 0.f; if (i == 0) x1[e] = smp ? p1[e] : 0.f; } }
;                         float r[8];
; #pragma unroll
;                         for (int e = 0; e < 8; ++e) { const float cv = bb[e] + x0[e] * w0[e] + x1[e] * w1[e] + x2[e] * w2[e]; r[e] = gelu_f(cv) * acc[ai][bj][m][e >> 2][e & 3]; }
;                         u32x4 w; w.x = pk2(r[0], r[1]); w.y = pk2(r[2], r[3]); w.z = pk2(r[4], r[5]); w.w = pk2(r[6], r[7]);
;                         *(u32x4*)(act + (size_t)row * DFF + col) = w; } } } }
.LBB0_1321:
	s_or_b64 exec, exec, s[14:15]
.LBB0_1322:
	s_or_b64 exec, exec, s[8:9]
	s_waitcnt vmcnt(0)
.LBB0_1323:
	s_or_b64 exec, exec, s[0:1]
	v_lshlrev_b32_e32 v194, 16, v138
	v_and_b32_e32 v138, 0xffff0000, v138
	v_lshlrev_b32_e32 v226, 16, v139
	v_and_b32_e32 v234, 0xffff0000, v139
	s_waitcnt vmcnt(1)
	v_mov_b32_e32 v195, v0
	v_mov_b32_e32 v139, v1
	v_pk_mul_f32 v[194:195], v[210:211], v[194:195]
	v_pk_mul_f32 v[0:1], v[106:107], v[138:139]
	v_pk_fma_f32 v[138:139], v[102:103], v[216:217], v[110:111]
	v_mov_b32_e32 v216, v195
	v_mov_b32_e32 v217, v1
	v_pk_add_f32 v[138:139], v[216:217], v[138:139]
	v_mov_b32_e32 v195, v0
	v_pk_add_f32 v[0:1], v[194:195], v[138:139]
	v_lshlrev_b32_e32 v248, 16, v141
	v_fma_f32 v138, |v0|, s84, 1.0
	v_and_b32_e32 v250, 0xffff0000, v141
	v_rcp_f32_e32 v141, v138
	v_mad_i64_i32 v[224:225], s[0:1], v233, s76, 0
	v_cmp_gt_f32_e64 s[0:1], 0, v0
	v_fmamk_f32 v138, v141, 0x3f07dc22, v241
	v_fmaak_f32 v194, v141, v138, 0x3f35f0e3
	v_pk_mul_f32 v[138:139], v[0:1], v[0:1]
	v_fmaak_f32 v194, v141, v194, 0xbe11a98e
	v_mul_f32_e32 v138, 0xbf38aa3b, v138
	v_exp_f32_e32 v138, v138
	v_fmaak_f32 v194, v141, v194, 0x3e027906
	v_mul_f32_e32 v141, v141, v194
	v_fma_f32 v194, |v1|, s84, 1.0
	v_rcp_f32_e32 v194, v194
	v_mul_f32_e32 v138, v138, v141
	v_mul_f32_e32 v141, v0, v138
	v_fma_f32 v138, -v0, v138, v0
	v_cndmask_b32_e64 v0, v138, v141, s[0:1]
	v_mul_f32_e32 v233, v134, v0
	v_fmamk_f32 v0, v194, 0x3f07dc22, v241
	v_fmaak_f32 v0, v194, v0, 0x3f35f0e3
	v_fmaak_f32 v0, v194, v0, 0xbe11a98e
	v_mov_b32_e32 v227, v2
	v_mov_b32_e32 v235, v3
	v_mul_f32_e32 v134, 0xbf38aa3b, v139
	v_fmaak_f32 v0, v194, v0, 0x3e027906
	v_pk_mul_f32 v[138:139], v[172:173], v[226:227]
	v_pk_mul_f32 v[2:3], v[108:109], v[234:235]
	v_mul_f32_e32 v0, v194, v0
	v_pk_fma_f32 v[194:195], v[104:105], v[218:219], v[112:113]
	v_mov_b32_e32 v216, v139
	v_mov_b32_e32 v217, v3
	v_exp_f32_e32 v134, v134
	v_pk_add_f32 v[194:195], v[216:217], v[194:195]
	v_mov_b32_e32 v139, v2
	v_pk_add_f32 v[2:3], v[138:139], v[194:195]
	v_mul_f32_e32 v0, v134, v0
	v_fma_f32 v138, |v2|, s84, 1.0
	v_rcp_f32_e32 v138, v138
	v_mul_f32_e32 v134, v1, v0
	v_fma_f32 v0, -v1, v0, v1
	v_cmp_gt_f32_e64 s[0:1], 0, v1
	v_lshlrev_b32_e32 v236, 16, v140
	v_and_b32_e32 v140, 0xffff0000, v140
	v_cndmask_b32_e64 v0, v0, v134, s[0:1]
	v_mul_f32_e32 v194, v135, v0
	v_fmamk_f32 v0, v138, 0x3f07dc22, v241
	v_fmaak_f32 v134, v138, v0, 0x3f35f0e3
	v_pk_mul_f32 v[0:1], v[2:3], v[2:3]
	v_fmaak_f32 v134, v138, v134, 0xbe11a98e
	v_mul_f32_e32 v0, 0xbf38aa3b, v0
	v_exp_f32_e32 v0, v0
	v_fmaak_f32 v134, v138, v134, 0x3e027906
	v_fma_f32 v135, |v3|, s84, 1.0
	v_mul_f32_e32 v134, v138, v134
	v_rcp_f32_e32 v135, v135
	v_mul_f32_e32 v0, v0, v134
	v_mul_f32_e32 v134, v2, v0
	v_fma_f32 v0, -v2, v0, v2
	v_cmp_gt_f32_e64 s[0:1], 0, v2
	v_mul_f32_e32 v1, 0xbf38aa3b, v1
	v_exp_f32_e32 v1, v1
	v_cndmask_b32_e64 v0, v0, v134, s[0:1]
	v_mul_f32_e32 v136, v136, v0
	v_fmamk_f32 v0, v135, 0x3f07dc22, v241
	v_fmaak_f32 v0, v135, v0, 0x3f35f0e3
	v_fmaak_f32 v0, v135, v0, 0xbe11a98e
	v_fmaak_f32 v0, v135, v0, 0x3e027906
	v_mul_f32_e32 v0, v135, v0
	v_mul_f32_e32 v0, v1, v0
	v_mov_b32_e32 v237, v4
	v_mov_b32_e32 v141, v5
	v_mul_f32_e32 v2, v3, v0
	v_fma_f32 v195, -v3, v0, v3
	v_pk_mul_f32 v[0:1], v[212:213], v[236:237]
	v_pk_mul_f32 v[4:5], v[94:95], v[140:141]
	v_pk_fma_f32 v[134:135], v[90:91], v[220:221], v[98:99]
	v_mov_b32_e32 v138, v1
	v_mov_b32_e32 v139, v5
	v_pk_add_f32 v[134:135], v[138:139], v[134:135]
	v_mov_b32_e32 v1, v4
	v_pk_add_f32 v[0:1], v[0:1], v[134:135]
	v_cmp_gt_f32_e64 s[0:1], 0, v3
	v_fma_f32 v4, |v0|, s84, 1.0
	v_rcp_f32_e32 v4, v4
	v_cndmask_b32_e64 v2, v195, v2, s[0:1]
	v_mul_f32_e32 v137, v137, v2
	v_cmp_gt_f32_e64 s[0:1], 0, v0
	v_fmamk_f32 v2, v4, 0x3f07dc22, v241
	v_fmaak_f32 v5, v4, v2, 0x3f35f0e3
	v_pk_mul_f32 v[2:3], v[0:1], v[0:1]
	v_fmaak_f32 v5, v4, v5, 0xbe11a98e
	v_mul_f32_e32 v2, 0xbf38aa3b, v2
	v_exp_f32_e32 v2, v2
	v_fmaak_f32 v5, v4, v5, 0x3e027906
	v_mul_f32_e32 v4, v4, v5
	v_fma_f32 v5, |v1|, s84, 1.0
	v_rcp_f32_e32 v5, v5
	v_mul_f32_e32 v2, v2, v4
	v_mul_f32_e32 v4, v0, v2
	v_fma_f32 v2, -v0, v2, v0
	v_cndmask_b32_e64 v0, v2, v4, s[0:1]
	v_mul_f32_e32 v130, v130, v0
	v_fmamk_f32 v0, v5, 0x3f07dc22, v241
	v_mul_f32_e32 v2, 0xbf38aa3b, v3
	v_fmaak_f32 v0, v5, v0, 0x3f35f0e3
	v_exp_f32_e32 v2, v2
	v_fmaak_f32 v0, v5, v0, 0xbe11a98e
	v_fmaak_f32 v0, v5, v0, 0x3e027906
	v_mul_f32_e32 v0, v5, v0
	v_mov_b32_e32 v249, v6
	v_mov_b32_e32 v251, v7
	v_mul_f32_e32 v0, v2, v0
	v_pk_mul_f32 v[2:3], v[214:215], v[248:249]
	v_pk_mul_f32 v[4:5], v[96:97], v[250:251]
	v_pk_fma_f32 v[6:7], v[92:93], v[222:223], v[100:101]
	v_mov_b32_e32 v134, v3
	v_mov_b32_e32 v135, v5
	v_pk_add_f32 v[6:7], v[134:135], v[6:7]
	v_mov_b32_e32 v3, v4
	v_pk_add_f32 v[2:3], v[2:3], v[6:7]
	v_mul_f32_e32 v138, v1, v0
	v_fma_f32 v4, |v2|, s84, 1.0
	v_rcp_f32_e32 v4, v4
	v_fma_f32 v0, -v1, v0, v1
	v_cmp_gt_f32_e64 s[0:1], 0, v1
	s_cmp_lg_u32 s70, 32
	s_cselect_b64 s[8:9], -1, 0
	v_cndmask_b32_e64 v0, v0, v138, s[0:1]
	v_mul_f32_e32 v5, v131, v0
	v_fmamk_f32 v0, v4, 0x3f07dc22, v241
	v_fmaak_f32 v6, v4, v0, 0x3f35f0e3
	v_pk_mul_f32 v[0:1], v[2:3], v[2:3]
	v_fmaak_f32 v6, v4, v6, 0xbe11a98e
	v_mul_f32_e32 v0, 0xbf38aa3b, v0
	v_exp_f32_e32 v0, v0
	v_fmaak_f32 v6, v4, v6, 0x3e027906
	v_mul_f32_e32 v4, v4, v6
	v_fma_f32 v6, |v3|, s84, 1.0
	v_rcp_f32_e32 v6, v6
	v_mul_f32_e32 v0, v0, v4
	v_mul_f32_e32 v4, v2, v0
	v_fma_f32 v0, -v2, v0, v2
	v_cmp_gt_f32_e64 s[0:1], 0, v2
	v_mul_f32_e32 v1, 0xbf38aa3b, v1
	v_exp_f32_e32 v1, v1
	v_cndmask_b32_e64 v0, v0, v4, s[0:1]
	v_mul_f32_e32 v4, v132, v0
	v_fmamk_f32 v0, v6, 0x3f07dc22, v241
	v_fmaak_f32 v0, v6, v0, 0x3f35f0e3
	v_fmaak_f32 v0, v6, v0, 0xbe11a98e
	v_fmaak_f32 v0, v6, v0, 0x3e027906
	v_mul_f32_e32 v0, v6, v0
	v_mul_f32_e32 v0, v1, v0
	v_mul_f32_e32 v1, v3, v0
	v_fma_f32 v0, -v3, v0, v3
	v_cmp_gt_f32_e64 s[0:1], 0, v3
	v_cvt_pk_bf16_f32 v2, v130, v5
	s_cmp_eq_u32 s70, 32
	s_nop 0
	v_cndmask_b32_e64 v0, v0, v1, s[0:1]
	v_mul_f32_e32 v3, v133, v0
	v_cvt_pk_bf16_f32 v3, v4, v3
	v_lshl_add_u64 v[4:5], s[80:81], 0, v[224:225]
	v_add_u32_e32 v224, 0x80, v232
	s_movk_i32 s0, 0x1f80
	v_lshl_add_u64 v[134:135], v[184:185], 1, v[4:5]
	v_cmp_gt_i32_e64 s[70:71], s0, v232
	v_max_i32_e32 v225, 1, v224
	v_max_i32_e32 v226, 2, v224
	v_cvt_pk_bf16_f32 v0, v233, v194
	v_cvt_pk_bf16_f32 v1, v136, v137
	global_store_dwordx4 v[134:135], v[0:3], off
	s_cbranch_scc1 .LBB0_1525
;     static __device__ __forceinline__ void unpack8(const u32x4 q, float (&x)[8]) { x[0] = bflo(q.x); x[1] = bfhi(q.x); x[2] = bflo(q.y); x[3] = bfhi(q.y); x[4] = bflo(q.z); x[5] = bfhi(q.z); x[6] = bflo(q.w); x[7] = bfhi(q.w); }
;     __device__ __forceinline__ void operator()(EPI_ARGS) const {
;     ...
;             for (int ai = 0; ai < 2; ++ai) {
;                 if (u.pm == 32 && ai == 1) continue;
; #pragma unroll
;                 for (int mp = 0; mp < 4; ++mp) {
;                     u32x4 q2[1], q1[1], q0[1];
; #pragma unroll
;                     for (int t = 0; t < 1; ++t) { const int row = row0 + ai * 128 + (mp + t) * 16; const int r1 = row > 0 ? row - 1 : 0, r2 = row > 1 ? row - 2 : 0;
;                         q2[t] = *(const u32x4*)(up + (size_t)row * DFF + col); q1[t] = *(const u32x4*)(up + (size_t)r1 * DFF + col); q0[t] = *(const u32x4*)(up + (size_t)r2 * DFF + col); }
;                     __builtin_amdgcn_sched_barrier(0);
; #pragma unroll
;                     for (int t = 0; t < 1; ++t) { const int m = mp + t, row = row0 + ai * 128 + m * 16;
;                         const int i = row < TP ? row : ((row - TP) & 15); const int sidx = row < TP ? 0 : ((row - TP) >> 4);
;                         float x0[8], x1[8], x2[8]; unpack8(q0[t], x0); unpack8(q1[t], x1); unpack8(q2[t], x2);
;                         if (i < 2) {
;                             const bool smp = row >= TP; const float* p0 = cs + ((size_t)sidx * 2 + i) * DFF + col; const float* p1 = cs + ((size_t)sidx * 2 + 1) * DFF + col;
; #pragma unroll
;                             for (int e = 0; e < 8; ++e) { x0[e] = smp ? p0[e] : 0.f; if (i == 0) x1[e] = smp ? p1[e] : 0.f; } }
	v_add_u32_e32 v4, -1, v225
	v_add_u32_e32 v136, -2, v226
	v_mov_b64_e32 v[0:1], s[30:31]
	v_mad_i64_i32 v[2:3], s[0:1], v224, s76, v[0:1]
	v_mad_u64_u32 v[4:5], s[0:1], v4, s76, v[0:1]
	v_mad_u64_u32 v[0:1], s[0:1], v136, s76, v[0:1]
	v_lshl_add_u64 v[2:3], v[2:3], 0, v[186:187]
	v_lshl_add_u64 v[4:5], v[4:5], 0, v[186:187]
	v_lshl_add_u64 v[0:1], v[0:1], 0, v[186:187]
	global_load_dwordx4 v[130:133], v[2:3], off
	s_nop 0
	global_load_dwordx4 v[4:7], v[4:5], off
	s_nop 0
	global_load_dwordx4 v[0:3], v[0:1], off
	v_cndmask_b32_e64 v222, v228, v224, s[70:71]
	s_waitcnt vmcnt(0)
	v_lshlrev_b32_e32 v136, 16, v0
	v_and_b32_e32 v137, 0xffff0000, v0
	v_lshlrev_b32_e32 v138, 16, v1
	v_and_b32_e32 v139, 0xffff0000, v1
	v_lshlrev_b32_e32 v140, 16, v2
	v_and_b32_e32 v141, 0xffff0000, v2
	v_lshlrev_b32_e32 v216, 16, v3
	v_and_b32_e32 v217, 0xffff0000, v3
	v_lshlrev_b32_e32 v0, 16, v4
	v_and_b32_e32 v1, 0xffff0000, v4
	v_lshlrev_b32_e32 v2, 16, v5
	v_and_b32_e32 v3, 0xffff0000, v5
	v_lshlrev_b32_e32 v4, 16, v6
	v_and_b32_e32 v5, 0xffff0000, v6
	v_lshlrev_b32_e32 v6, 16, v7
	v_and_b32_e32 v7, 0xffff0000, v7
	v_cmp_gt_i32_e64 s[0:1], 2, v222
	s_and_saveexec_b64 s[14:15], s[0:1]
	s_cbranch_execz .LBB0_1374
	s_add_i32 s18, s5, 0xffffe080
	s_ashr_i32 s18, s18, 4
	v_mov_b32_e32 v136, s18
	v_cndmask_b32_e64 v138, v136, 0, s[70:71]
	v_ashrrev_i32_e32 v139, 31, v138
	v_ashrrev_i32_e32 v223, 31, v222
	v_lshl_add_u64 v[136:137], v[138:139], 1, v[222:223]
	v_mov_b64_e32 v[140:141], s[68:69]
	v_mad_u64_u32 v[140:141], s[18:19], v136, s13, v[140:141]
	s_movk_i32 s0, 0x1f7f
	v_mad_i32_i24 v141, v137, s13, v141
	v_cmp_lt_i32_e64 s[0:1], s0, v232
	v_lshl_add_u64 v[220:221], v[184:185], 2, v[140:141]
	v_mov_b32_e32 v136, 0
	s_and_saveexec_b64 s[18:19], s[0:1]
	s_cbranch_execz .LBB0_1327
	global_load_dword v136, v[220:221], off

; __device__ __forceinline__ unsigned pk2(float lo, float hi) { unsigned r; asm("v_cvt_pk_bf16_f32 %0, %1, %2" : "=v"(r) : "v"(lo), "v"(hi)); return r; }
;     static __device__ __forceinline__ void unpack8(const u32x4 q, float (&x)[8]) { x[0] = bflo(q.x); x[1] = bfhi(q.x); x[2] = bflo(q.y); x[3] = bfhi(q.y); x[4] = bflo(q.z); x[5] = bfhi(q.z); x[6] = bflo(q.w); x[7] = bfhi(q.w); }
;     __device__ __forceinline__ void operator()(EPI_ARGS) const {
;     ...
;                     for (int t = 0; t < 1; ++t) { const int row = row0 + ai * 128 + (mp + t) * 16; const int r1 = row > 0 ? row - 1 : 0, r2 = row > 1 ? row - 2 : 0;
;                         q2[t] = *(const u32x4*)(up + (size_t)row * DFF + col); q1[t] = *(const u32x4*)(up + (size_t)r1 * DFF + col); q0[t] = *(const u32x4*)(up + (size_t)r2 * DFF + col); }
;                     __builtin_amdgcn_sched_barrier(0);
; #pragma unroll
;                     for (int t = 0; t < 1; ++t) { const int m = mp + t, row = row0 + ai * 128 + m * 16;
;                         const int i = row < TP ? row : ((row - TP) & 15); const int sidx = row < TP ? 0 : ((row - TP) >> 4);
;                         float x0[8], x1[8], x2[8]; unpack8(q0[t], x0); unpack8(q1[t], x1); unpack8(q2[t], x2);
;                         if (i < 2) {
;                             const bool smp = row >= TP; const float* p0 = cs + ((size_t)sidx * 2 + i) * DFF + col; const float* p1 = cs + ((size_t)sidx * 2 + 1) * DFF + col;
; #pragma unroll
;                             for (int e = 0; e < 8; ++e) { x0[e] = smp ? p0[e] : 0.f; if (i == 0) x1[e] = smp ? p1[e] : 0.f; } }
;                         float r[8];
; #pragma unroll
;                         for (int e = 0; e < 8; ++e) { const float cv = bb[e] + x0[e] * w0[e] + x1[e] * w1[e] + x2[e] * w2[e]; r[e] = gelu_f(cv) * acc[ai][bj][m][e >> 2][e & 3]; }
;                         u32x4 w; w.x = pk2(r[0], r[1]); w.y = pk2(r[2], r[3]); w.z = pk2(r[4], r[5]); w.w = pk2(r[6], r[7]);
;                         *(u32x4*)(act + (size_t)row * DFF + col) = w; } } } }
.LBB0_1374:
	s_or_b64 exec, exec, s[14:15]
	v_lshlrev_b32_e32 v194, 16, v130
	v_and_b32_e32 v130, 0xffff0000, v130
	v_lshlrev_b32_e32 v220, 16, v131
	v_and_b32_e32 v222, 0xffff0000, v131
	s_waitcnt vmcnt(0)
	v_add_u32_e32 v240, 144, v232
	v_mov_b64_e32 v[238:239], s[30:31]
	v_mad_i64_i32 v[238:239], s[0:1], v240, s76, v[238:239]
	v_lshl_add_u64 v[238:239], v[238:239], 0, v[186:187]
	global_load_dwordx4 v[196:199], v[238:239], off
	v_add_u32_e32 v240, -1, v240
	v_mov_b64_e32 v[246:247], s[30:31]
	v_mad_i64_i32 v[246:247], s[0:1], v240, s76, v[246:247]
	v_lshl_add_u64 v[246:247], v[246:247], 0, v[186:187]
	global_load_dwordx4 v[200:203], v[246:247], off
	v_add_u32_e32 v240, -1, v240
	v_mov_b64_e32 v[238:239], s[30:31]
	v_mad_i64_i32 v[238:239], s[0:1], v240, s76, v[238:239]
	v_lshl_add_u64 v[238:239], v[238:239], 0, v[186:187]
	global_load_dwordx4 v[242:245], v[238:239], off
	v_mov_b32_e32 v195, v0
	v_mov_b32_e32 v131, v1
	v_pk_mul_f32 v[194:195], v[210:211], v[194:195]
	v_pk_mul_f32 v[0:1], v[106:107], v[130:131]
	v_pk_fma_f32 v[130:131], v[102:103], v[136:137], v[110:111]
	v_mov_b32_e32 v136, v195
	v_mov_b32_e32 v137, v1
	v_pk_add_f32 v[130:131], v[136:137], v[130:131]
	v_mov_b32_e32 v195, v0
	v_pk_add_f32 v[0:1], v[194:195], v[130:131]
	v_lshlrev_b32_e32 v234, 16, v132
	v_fma_f32 v130, |v0|, s84, 1.0
	v_rcp_f32_e32 v131, v130
	v_pk_mul_f32 v[194:195], v[0:1], v[0:1]
	v_and_b32_e32 v130, 0xffff0000, v132
	v_lshlrev_b32_e32 v132, 16, v133
	v_and_b32_e32 v136, 0xffff0000, v133
	v_fmamk_f32 v133, v131, 0x3f07dc22, v241
	v_mul_f32_e32 v137, 0xbf38aa3b, v194
	v_fmaak_f32 v133, v131, v133, 0x3f35f0e3
	v_exp_f32_e32 v137, v137
	v_fmaak_f32 v133, v131, v133, 0xbe11a98e
	v_fmaak_f32 v133, v131, v133, 0x3e027906
	v_mul_f32_e32 v131, v131, v133
	v_mul_f32_e32 v131, v137, v131
	v_fma_f32 v137, |v1|, s84, 1.0
	v_mad_i64_i32 v[218:219], s[0:1], v224, s76, 0
	v_rcp_f32_e32 v137, v137
	v_mul_f32_e32 v133, v0, v131
	v_fma_f32 v131, -v0, v131, v0
	v_cmp_gt_f32_e64 s[0:1], 0, v0
	v_mov_b32_e32 v221, v2
	v_mov_b32_e32 v223, v3
	v_cndmask_b32_e64 v0, v131, v133, s[0:1]
	v_mul_f32_e32 v227, v126, v0
	v_mul_f32_e32 v126, 0xbf38aa3b, v195
	v_pk_mul_f32 v[194:195], v[172:173], v[220:221]
	v_pk_mul_f32 v[2:3], v[108:109], v[222:223]
	v_fmamk_f32 v0, v137, 0x3f07dc22, v241
	v_pk_fma_f32 v[138:139], v[104:105], v[138:139], v[112:113]
	v_mov_b32_e32 v220, v195
	v_mov_b32_e32 v221, v3
	v_fmaak_f32 v0, v137, v0, 0x3f35f0e3
	v_exp_f32_e32 v126, v126
	v_pk_add_f32 v[138:139], v[220:221], v[138:139]
	v_mov_b32_e32 v195, v2
	v_fmaak_f32 v0, v137, v0, 0xbe11a98e
	v_pk_add_f32 v[2:3], v[194:195], v[138:139]
	v_fmaak_f32 v0, v137, v0, 0x3e027906
	v_fma_f32 v131, |v2|, s84, 1.0
	v_mul_f32_e32 v0, v137, v0
	v_rcp_f32_e32 v131, v131
	v_mul_f32_e32 v0, v126, v0
	v_mul_f32_e32 v126, v1, v0
	v_fma_f32 v0, -v1, v0, v1
	v_cmp_gt_f32_e64 s[0:1], 0, v1
	v_mov_b32_e32 v235, v4
	v_mov_b32_e32 v137, v7
	v_cndmask_b32_e64 v0, v0, v126, s[0:1]
	v_mul_f32_e32 v138, v127, v0
	v_fmamk_f32 v0, v131, 0x3f07dc22, v241
	v_fmaak_f32 v126, v131, v0, 0x3f35f0e3
	v_pk_mul_f32 v[0:1], v[2:3], v[2:3]
	v_fmaak_f32 v126, v131, v126, 0xbe11a98e
	v_mul_f32_e32 v0, 0xbf38aa3b, v0
	v_exp_f32_e32 v0, v0
	v_fmaak_f32 v126, v131, v126, 0x3e027906
	v_fma_f32 v127, |v3|, s84, 1.0
	v_mul_f32_e32 v126, v131, v126
	v_rcp_f32_e32 v127, v127
	v_mul_f32_e32 v0, v0, v126
	v_mul_f32_e32 v126, v2, v0
	v_fma_f32 v0, -v2, v0, v2
	v_cmp_gt_f32_e64 s[0:1], 0, v2
	v_mul_f32_e32 v1, 0xbf38aa3b, v1
	v_exp_f32_e32 v1, v1
	v_cndmask_b32_e64 v0, v0, v126, s[0:1]
	v_mul_f32_e32 v128, v128, v0
	v_fmamk_f32 v0, v127, 0x3f07dc22, v241
	v_fmaak_f32 v0, v127, v0, 0x3f35f0e3
	v_fmaak_f32 v0, v127, v0, 0xbe11a98e
	v_fmaak_f32 v0, v127, v0, 0x3e027906
	v_mul_f32_e32 v0, v127, v0
	v_mul_f32_e32 v0, v1, v0
	v_mov_b32_e32 v131, v5
	v_mul_f32_e32 v2, v3, v0
	v_fma_f32 v133, -v3, v0, v3
	v_pk_mul_f32 v[0:1], v[212:213], v[234:235]
	v_pk_mul_f32 v[4:5], v[94:95], v[130:131]
	v_pk_fma_f32 v[126:127], v[90:91], v[140:141], v[98:99]
	v_mov_b32_e32 v130, v1
	v_mov_b32_e32 v131, v5
	v_pk_add_f32 v[126:127], v[130:131], v[126:127]
	v_mov_b32_e32 v1, v4
	v_pk_add_f32 v[0:1], v[0:1], v[126:127]
	v_cmp_gt_f32_e64 s[0:1], 0, v3
	v_fma_f32 v4, |v0|, s84, 1.0
	v_rcp_f32_e32 v4, v4
	v_cndmask_b32_e64 v2, v133, v2, s[0:1]
	v_mul_f32_e32 v129, v129, v2
	v_cmp_gt_f32_e64 s[0:1], 0, v0
	v_fmamk_f32 v2, v4, 0x3f07dc22, v241
	v_fmaak_f32 v5, v4, v2, 0x3f35f0e3
;     static __device__ __forceinline__ void unpack8(const u32x4 q, float (&x)[8]) { x[0] = bflo(q.x); x[1] = bfhi(q.x); x[2] = bflo(q.y); x[3] = bfhi(q.y); x[4] = bflo(q.z); x[5] = bfhi(q.z); x[6] = bflo(q.w); x[7] = bfhi(q.w); }
;     __device__ __forceinline__ void operator()(EPI_ARGS) const {
;     ...
;                     for (int t = 0; t < 1; ++t) { const int row = row0 + ai * 128 + (mp + t) * 16; const int r1 = row > 0 ? row - 1 : 0, r2 = row > 1 ? row - 2 : 0;
;                         q2[t] = *(const u32x4*)(up + (size_t)row * DFF + col); q1[t] = *(const u32x4*)(up + (size_t)r1 * DFF + col); q0[t] = *(const u32x4*)(up + (size_t)r2 * DFF + col); }
;                     __builtin_amdgcn_sched_barrier(0);
; #pragma unroll
;                     for (int t = 0; t < 1; ++t) { const int m = mp + t, row = row0 + ai * 128 + m * 16;
;                         const int i = row < TP ? row : ((row - TP) & 15); const int sidx = row < TP ? 0 : ((row - TP) >> 4);
;                         float x0[8], x1[8], x2[8]; unpack8(q0[t], x0); unpack8(q1[t], x1); unpack8(q2[t], x2);
;                         if (i < 2) {
;                             const bool smp = row >= TP; const float* p0 = cs + ((size_t)sidx * 2 + i) * DFF + col; const float* p1 = cs + ((size_t)sidx * 2 + 1) * DFF + col;
; #pragma unroll
;                             for (int e = 0; e < 8; ++e) { x0[e] = smp ? p0[e] : 0.f; if (i == 0) x1[e] = smp ? p1[e] : 0.f; } }
	v_pk_mul_f32 v[2:3], v[0:1], v[0:1]
	v_fmaak_f32 v5, v4, v5, 0xbe11a98e
	v_mul_f32_e32 v2, 0xbf38aa3b, v2
	v_exp_f32_e32 v2, v2
	v_fmaak_f32 v5, v4, v5, 0x3e027906
	v_mul_f32_e32 v4, v4, v5
	v_fma_f32 v5, |v1|, s84, 1.0
	v_rcp_f32_e32 v5, v5
	v_mul_f32_e32 v2, v2, v4
	v_mul_f32_e32 v4, v0, v2
	v_fma_f32 v2, -v0, v2, v0
	v_cndmask_b32_e64 v0, v2, v4, s[0:1]
	v_mul_f32_e32 v122, v122, v0
	v_fmamk_f32 v0, v5, 0x3f07dc22, v241
	v_mul_f32_e32 v2, 0xbf38aa3b, v3
	v_fmaak_f32 v0, v5, v0, 0x3f35f0e3
	v_exp_f32_e32 v2, v2
	v_fmaak_f32 v0, v5, v0, 0xbe11a98e
	v_fmaak_f32 v0, v5, v0, 0x3e027906
	v_mul_f32_e32 v0, v5, v0
	v_mov_b32_e32 v133, v6
	v_mul_f32_e32 v0, v2, v0
	v_pk_mul_f32 v[2:3], v[214:215], v[132:133]
	v_pk_mul_f32 v[4:5], v[96:97], v[136:137]
	v_pk_fma_f32 v[6:7], v[92:93], v[216:217], v[100:101]
	v_mov_b32_e32 v126, v3
	v_mov_b32_e32 v127, v5
	v_pk_add_f32 v[6:7], v[126:127], v[6:7]
	v_mov_b32_e32 v3, v4
	v_pk_add_f32 v[2:3], v[2:3], v[6:7]
	v_mul_f32_e32 v130, v1, v0
	v_fma_f32 v4, |v2|, s84, 1.0
	v_rcp_f32_e32 v4, v4
	v_fma_f32 v0, -v1, v0, v1
	v_cmp_gt_f32_e64 s[0:1], 0, v1
	v_add_u32_e32 v216, 0x90, v232
	s_nop 0
	v_cndmask_b32_e64 v0, v0, v130, s[0:1]
	v_mul_f32_e32 v5, v123, v0
	v_fmamk_f32 v0, v4, 0x3f07dc22, v241
	v_fmaak_f32 v6, v4, v0, 0x3f35f0e3
	v_pk_mul_f32 v[0:1], v[2:3], v[2:3]
	v_fmaak_f32 v6, v4, v6, 0xbe11a98e
	v_mul_f32_e32 v0, 0xbf38aa3b, v0
	v_exp_f32_e32 v0, v0
	v_fmaak_f32 v6, v4, v6, 0x3e027906
	v_mul_f32_e32 v4, v4, v6
	v_fma_f32 v6, |v3|, s84, 1.0
	v_rcp_f32_e32 v6, v6
	v_mul_f32_e32 v0, v0, v4
	v_mul_f32_e32 v4, v2, v0
	v_fma_f32 v0, -v2, v0, v2
	v_cmp_gt_f32_e64 s[0:1], 0, v2
	v_mul_f32_e32 v1, 0xbf38aa3b, v1
	v_exp_f32_e32 v1, v1
	v_cndmask_b32_e64 v0, v0, v4, s[0:1]
	v_mul_f32_e32 v4, v124, v0
	v_fmamk_f32 v0, v6, 0x3f07dc22, v241
	v_fmaak_f32 v0, v6, v0, 0x3f35f0e3
	v_fmaak_f32 v0, v6, v0, 0xbe11a98e
	v_fmaak_f32 v0, v6, v0, 0x3e027906
	v_mul_f32_e32 v0, v6, v0
	v_mul_f32_e32 v0, v1, v0
	v_mul_f32_e32 v1, v3, v0
	v_fma_f32 v0, -v3, v0, v3
	v_cmp_gt_f32_e64 s[0:1], 0, v3
	v_cvt_pk_bf16_f32 v2, v122, v5
	s_nop 1
	v_cndmask_b32_e64 v0, v0, v1, s[0:1]
	v_mul_f32_e32 v3, v125, v0
	v_cvt_pk_bf16_f32 v3, v4, v3
	v_lshl_add_u64 v[4:5], s[80:81], 0, v[218:219]
	v_cvt_pk_bf16_f32 v0, v227, v138
	v_lshl_add_u64 v[4:5], v[4:5], 0, v[186:187]
	v_cvt_pk_bf16_f32 v1, v128, v129
	global_store_dwordx4 v[4:5], v[0:3], off
	s_nop 1
	v_max_i32_e32 v0, 1, v216
	v_add_u32_e32 v4, -1, v0
	v_max_i32_e32 v0, 2, v216
	v_add_u32_e32 v126, -2, v0
	v_mov_b64_e32 v[0:1], s[30:31]
	v_mad_i64_i32 v[2:3], s[0:1], v216, s76, v[0:1]
	v_mad_u64_u32 v[4:5], s[0:1], v4, s76, v[0:1]
	v_mad_u64_u32 v[0:1], s[0:1], v126, s76, v[0:1]
	v_lshl_add_u64 v[2:3], v[2:3], 0, v[186:187]
	v_lshl_add_u64 v[4:5], v[4:5], 0, v[186:187]
	v_lshl_add_u64 v[0:1], v[0:1], 0, v[186:187]
	s_movk_i32 s0, 0x1f70
	v_cmp_gt_i32_e64 s[70:71], s0, v232
	s_waitcnt vmcnt(1)
	v_mov_b64_e32 v[122:123], v[196:197]
	v_mov_b64_e32 v[124:125], v[198:199]
	v_mov_b64_e32 v[4:5], v[200:201]
	v_mov_b64_e32 v[6:7], v[202:203]
	v_mov_b64_e32 v[0:1], v[242:243]
	v_mov_b64_e32 v[2:3], v[244:245]
	v_lshlrev_b32_e32 v126, 16, v0
	v_and_b32_e32 v127, 0xffff0000, v0
	v_cndmask_b32_e64 v140, v228, v216, s[70:71]
	v_lshlrev_b32_e32 v128, 16, v1
	v_and_b32_e32 v129, 0xffff0000, v1
	v_lshlrev_b32_e32 v130, 16, v2
	v_and_b32_e32 v131, 0xffff0000, v2
	v_lshlrev_b32_e32 v132, 16, v3
	v_and_b32_e32 v133, 0xffff0000, v3
	v_lshlrev_b32_e32 v0, 16, v4
	v_and_b32_e32 v1, 0xffff0000, v4
	v_lshlrev_b32_e32 v2, 16, v5
	v_and_b32_e32 v3, 0xffff0000, v5
	v_lshlrev_b32_e32 v4, 16, v6
	v_and_b32_e32 v5, 0xffff0000, v6
	v_lshlrev_b32_e32 v6, 16, v7
	v_and_b32_e32 v7, 0xffff0000, v7
	v_cmp_gt_i32_e64 s[0:1], 2, v140
	s_and_saveexec_b64 s[14:15], s[0:1]
	s_cbranch_execz .LBB0_1424
	s_add_i32 s18, s5, 0xffffe090
	s_ashr_i32 s18, s18, 4
	v_mov_b32_e32 v126, s18
	v_cndmask_b32_e64 v128, v126, 0, s[70:71]
	v_ashrrev_i32_e32 v129, 31, v128
	v_ashrrev_i32_e32 v141, 31, v140
	v_lshl_add_u64 v[126:127], v[128:129], 1, v[140:141]
	v_mov_b64_e32 v[130:131], s[68:69]
	v_mad_u64_u32 v[130:131], s[18:19], v126, s13, v[130:131]
	s_movk_i32 s0, 0x1f6f
	v_mad_i32_i24 v131, v127, s13, v131
	v_cmp_lt_i32_e64 s[0:1], s0, v232
	v_lshl_add_u64 v[138:139], v[184:185], 2, v[130:131]
	v_mov_b32_e32 v126, 0
	s_and_saveexec_b64 s[18:19], s[0:1]
	s_cbranch_execz .LBB0_1377
	global_load_dword v126, v[138:139], off

; __device__ __forceinline__ unsigned pk2(float lo, float hi) { unsigned r; asm("v_cvt_pk_bf16_f32 %0, %1, %2" : "=v"(r) : "v"(lo), "v"(hi)); return r; }
;     static __device__ __forceinline__ void unpack8(const u32x4 q, float (&x)[8]) { x[0] = bflo(q.x); x[1] = bfhi(q.x); x[2] = bflo(q.y); x[3] = bfhi(q.y); x[4] = bflo(q.z); x[5] = bfhi(q.z); x[6] = bflo(q.w); x[7] = bfhi(q.w); }
;     __device__ __forceinline__ void operator()(EPI_ARGS) const {
;     ...
;                     for (int t = 0; t < 1; ++t) { const int row = row0 + ai * 128 + (mp + t) * 16; const int r1 = row > 0 ? row - 1 : 0, r2 = row > 1 ? row - 2 : 0;
;                         q2[t] = *(const u32x4*)(up + (size_t)row * DFF + col); q1[t] = *(const u32x4*)(up + (size_t)r1 * DFF + col); q0[t] = *(const u32x4*)(up + (size_t)r2 * DFF + col); }
;                     __builtin_amdgcn_sched_barrier(0);
; #pragma unroll
;                     for (int t = 0; t < 1; ++t) { const int m = mp + t, row = row0 + ai * 128 + m * 16;
;                         const int i = row < TP ? row : ((row - TP) & 15); const int sidx = row < TP ? 0 : ((row - TP) >> 4);
;                         float x0[8], x1[8], x2[8]; unpack8(q0[t], x0); unpack8(q1[t], x1); unpack8(q2[t], x2);
;                         if (i < 2) {
;                             const bool smp = row >= TP; const float* p0 = cs + ((size_t)sidx * 2 + i) * DFF + col; const float* p1 = cs + ((size_t)sidx * 2 + 1) * DFF + col;
; #pragma unroll
;                             for (int e = 0; e < 8; ++e) { x0[e] = smp ? p0[e] : 0.f; if (i == 0) x1[e] = smp ? p1[e] : 0.f; } }
;                         float r[8];
; #pragma unroll
;                         for (int e = 0; e < 8; ++e) { const float cv = bb[e] + x0[e] * w0[e] + x1[e] * w1[e] + x2[e] * w2[e]; r[e] = gelu_f(cv) * acc[ai][bj][m][e >> 2][e & 3]; }
;                         u32x4 w; w.x = pk2(r[0], r[1]); w.y = pk2(r[2], r[3]); w.z = pk2(r[4], r[5]); w.w = pk2(r[6], r[7]);
;                         *(u32x4*)(act + (size_t)row * DFF + col) = w; } } } }
.LBB0_1422:
	s_or_b64 exec, exec, s[20:21]
.LBB0_1423:
	s_or_b64 exec, exec, s[18:19]
	s_waitcnt vmcnt(0)
.LBB0_1424:
	s_or_b64 exec, exec, s[14:15]
	v_lshlrev_b32_e32 v138, 16, v122
	v_and_b32_e32 v122, 0xffff0000, v122
	v_lshlrev_b32_e32 v140, 16, v123
	v_and_b32_e32 v194, 0xffff0000, v123
	s_waitcnt vmcnt(1)
	v_add_u32_e32 v240, 160, v232
	v_mov_b64_e32 v[238:239], s[30:31]
	v_mad_i64_i32 v[238:239], s[0:1], v240, s76, v[238:239]
	v_lshl_add_u64 v[238:239], v[238:239], 0, v[186:187]
	global_load_dwordx4 v[196:199], v[238:239], off
	v_add_u32_e32 v240, -1, v240
	v_mov_b64_e32 v[246:247], s[30:31]
	v_mad_i64_i32 v[246:247], s[0:1], v240, s76, v[246:247]
	v_lshl_add_u64 v[246:247], v[246:247], 0, v[186:187]
	global_load_dwordx4 v[200:203], v[246:247], off
	v_add_u32_e32 v240, -1, v240
	v_mov_b64_e32 v[238:239], s[30:31]
	v_mad_i64_i32 v[238:239], s[0:1], v240, s76, v[238:239]
	v_lshl_add_u64 v[238:239], v[238:239], 0, v[186:187]
	global_load_dwordx4 v[242:245], v[238:239], off
	v_mov_b32_e32 v139, v0
	v_mov_b32_e32 v123, v1
	v_pk_mul_f32 v[138:139], v[210:211], v[138:139]
	v_pk_mul_f32 v[0:1], v[106:107], v[122:123]
	v_pk_fma_f32 v[122:123], v[102:103], v[126:127], v[110:111]
	v_mov_b32_e32 v126, v139
	v_mov_b32_e32 v127, v1
	v_pk_add_f32 v[122:123], v[126:127], v[122:123]
	v_mov_b32_e32 v139, v0
	v_pk_add_f32 v[0:1], v[138:139], v[122:123]
	v_mad_i64_i32 v[136:137], s[0:1], v216, s76, 0
	v_fma_f32 v122, |v0|, s84, 1.0
	v_rcp_f32_e32 v123, v122
	v_pk_mul_f32 v[138:139], v[0:1], v[0:1]
	v_lshlrev_b32_e32 v216, 16, v124
	v_and_b32_e32 v122, 0xffff0000, v124
	v_lshlrev_b32_e32 v124, 16, v125
	v_and_b32_e32 v126, 0xffff0000, v125
	v_fmamk_f32 v125, v123, 0x3f07dc22, v241
	v_mul_f32_e32 v127, 0xbf38aa3b, v138
	v_fmaak_f32 v125, v123, v125, 0x3f35f0e3
	v_exp_f32_e32 v127, v127
	v_fmaak_f32 v125, v123, v125, 0xbe11a98e
	v_fmaak_f32 v125, v123, v125, 0x3e027906
	v_mul_f32_e32 v123, v123, v125
	v_mul_f32_e32 v123, v127, v123
	v_fma_f32 v127, |v1|, s84, 1.0
	v_rcp_f32_e32 v127, v127
	v_mul_f32_e32 v125, v0, v123
	v_fma_f32 v123, -v0, v123, v0
	v_cmp_gt_f32_e64 s[0:1], 0, v0
	v_mov_b32_e32 v141, v2
	v_mov_b32_e32 v195, v3
	v_cndmask_b32_e64 v0, v123, v125, s[0:1]
	v_mul_f32_e32 v218, v118, v0
	v_mul_f32_e32 v118, 0xbf38aa3b, v139
	v_pk_mul_f32 v[138:139], v[172:173], v[140:141]
	v_pk_mul_f32 v[2:3], v[108:109], v[194:195]
	v_fmamk_f32 v0, v127, 0x3f07dc22, v241
	v_pk_fma_f32 v[128:129], v[104:105], v[128:129], v[112:113]
	v_mov_b32_e32 v140, v139
	v_mov_b32_e32 v141, v3
	v_fmaak_f32 v0, v127, v0, 0x3f35f0e3
	v_exp_f32_e32 v118, v118
	v_pk_add_f32 v[128:129], v[140:141], v[128:129]
	v_mov_b32_e32 v139, v2
	v_fmaak_f32 v0, v127, v0, 0xbe11a98e
	v_pk_add_f32 v[2:3], v[138:139], v[128:129]
	v_fmaak_f32 v0, v127, v0, 0x3e027906
	v_fma_f32 v123, |v2|, s84, 1.0
	v_mul_f32_e32 v0, v127, v0
	v_rcp_f32_e32 v123, v123
	v_mul_f32_e32 v0, v118, v0
	v_mul_f32_e32 v118, v1, v0
	v_fma_f32 v0, -v1, v0, v1
	v_cmp_gt_f32_e64 s[0:1], 0, v1
	v_mov_b32_e32 v217, v4
	v_mov_b32_e32 v127, v7
	v_cndmask_b32_e64 v0, v0, v118, s[0:1]
	v_mul_f32_e32 v128, v119, v0
	v_fmamk_f32 v0, v123, 0x3f07dc22, v241
	v_fmaak_f32 v118, v123, v0, 0x3f35f0e3
	v_pk_mul_f32 v[0:1], v[2:3], v[2:3]
	v_fmaak_f32 v118, v123, v118, 0xbe11a98e
	v_mul_f32_e32 v0, 0xbf38aa3b, v0
	v_exp_f32_e32 v0, v0
	v_fmaak_f32 v118, v123, v118, 0x3e027906
	v_fma_f32 v119, |v3|, s84, 1.0
	v_mul_f32_e32 v118, v123, v118
	v_rcp_f32_e32 v119, v119
	v_mul_f32_e32 v0, v0, v118
	v_mul_f32_e32 v118, v2, v0
	v_fma_f32 v0, -v2, v0, v2
	v_cmp_gt_f32_e64 s[0:1], 0, v2
	v_mul_f32_e32 v1, 0xbf38aa3b, v1
	v_exp_f32_e32 v1, v1
	v_cndmask_b32_e64 v0, v0, v118, s[0:1]
	v_mul_f32_e32 v120, v120, v0
	v_fmamk_f32 v0, v119, 0x3f07dc22, v241
	v_fmaak_f32 v0, v119, v0, 0x3f35f0e3
	v_fmaak_f32 v0, v119, v0, 0xbe11a98e
	v_fmaak_f32 v0, v119, v0, 0x3e027906
	v_mul_f32_e32 v0, v119, v0
	v_mul_f32_e32 v0, v1, v0
	v_mov_b32_e32 v123, v5
	v_mul_f32_e32 v2, v3, v0
	v_fma_f32 v125, -v3, v0, v3
	v_pk_mul_f32 v[0:1], v[212:213], v[216:217]
	v_pk_mul_f32 v[4:5], v[94:95], v[122:123]
	v_pk_fma_f32 v[118:119], v[90:91], v[130:131], v[98:99]
	v_mov_b32_e32 v122, v1
	v_mov_b32_e32 v123, v5
	v_pk_add_f32 v[118:119], v[122:123], v[118:119]
	v_mov_b32_e32 v1, v4
	v_pk_add_f32 v[0:1], v[0:1], v[118:119]
	v_cmp_gt_f32_e64 s[0:1], 0, v3
	v_fma_f32 v4, |v0|, s84, 1.0
	v_rcp_f32_e32 v4, v4
	v_cndmask_b32_e64 v2, v125, v2, s[0:1]
	v_mul_f32_e32 v121, v121, v2
	v_cmp_gt_f32_e64 s[0:1], 0, v0
; __device__ __forceinline__ unsigned pk2(float lo, float hi) { unsigned r; asm("v_cvt_pk_bf16_f32 %0, %1, %2" : "=v"(r) : "v"(lo), "v"(hi)); return r; }
;     static __device__ __forceinline__ void unpack8(const u32x4 q, float (&x)[8]) { x[0] = bflo(q.x); x[1] = bfhi(q.x); x[2] = bflo(q.y); x[3] = bfhi(q.y); x[4] = bflo(q.z); x[5] = bfhi(q.z); x[6] = bflo(q.w); x[7] = bfhi(q.w); }
;     __device__ __forceinline__ void operator()(EPI_ARGS) const {
;     ...
;                     for (int t = 0; t < 1; ++t) { const int row = row0 + ai * 128 + (mp + t) * 16; const int r1 = row > 0 ? row - 1 : 0, r2 = row > 1 ? row - 2 : 0;
;                         q2[t] = *(const u32x4*)(up + (size_t)row * DFF + col); q1[t] = *(const u32x4*)(up + (size_t)r1 * DFF + col); q0[t] = *(const u32x4*)(up + (size_t)r2 * DFF + col); }
;                     __builtin_amdgcn_sched_barrier(0);
; #pragma unroll
;                     for (int t = 0; t < 1; ++t) { const int m = mp + t, row = row0 + ai * 128 + m * 16;
;                         const int i = row < TP ? row : ((row - TP) & 15); const int sidx = row < TP ? 0 : ((row - TP) >> 4);
;                         float x0[8], x1[8], x2[8]; unpack8(q0[t], x0); unpack8(q1[t], x1); unpack8(q2[t], x2);
;                         if (i < 2) {
;                             const bool smp = row >= TP; const float* p0 = cs + ((size_t)sidx * 2 + i) * DFF + col; const float* p1 = cs + ((size_t)sidx * 2 + 1) * DFF + col;
; #pragma unroll
;                             for (int e = 0; e < 8; ++e) { x0[e] = smp ? p0[e] : 0.f; if (i == 0) x1[e] = smp ? p1[e] : 0.f; } }
;                         float r[8];
; #pragma unroll
;                         for (int e = 0; e < 8; ++e) { const float cv = bb[e] + x0[e] * w0[e] + x1[e] * w1[e] + x2[e] * w2[e]; r[e] = gelu_f(cv) * acc[ai][bj][m][e >> 2][e & 3]; }
;                         u32x4 w; w.x = pk2(r[0], r[1]); w.y = pk2(r[2], r[3]); w.z = pk2(r[4], r[5]); w.w = pk2(r[6], r[7]);
;                         *(u32x4*)(act + (size_t)row * DFF + col) = w; } } } }
	v_fmamk_f32 v2, v4, 0x3f07dc22, v241
	v_fmaak_f32 v5, v4, v2, 0x3f35f0e3
	v_pk_mul_f32 v[2:3], v[0:1], v[0:1]
	v_fmaak_f32 v5, v4, v5, 0xbe11a98e
	v_mul_f32_e32 v2, 0xbf38aa3b, v2
	v_exp_f32_e32 v2, v2
	v_fmaak_f32 v5, v4, v5, 0x3e027906
	v_mul_f32_e32 v4, v4, v5
	v_fma_f32 v5, |v1|, s84, 1.0
	v_rcp_f32_e32 v5, v5
	v_mul_f32_e32 v2, v2, v4
	v_mul_f32_e32 v4, v0, v2
	v_fma_f32 v2, -v0, v2, v0
	v_cndmask_b32_e64 v0, v2, v4, s[0:1]
	v_mul_f32_e32 v114, v114, v0
	v_fmamk_f32 v0, v5, 0x3f07dc22, v241
	v_mul_f32_e32 v2, 0xbf38aa3b, v3
	v_fmaak_f32 v0, v5, v0, 0x3f35f0e3
	v_exp_f32_e32 v2, v2
	v_fmaak_f32 v0, v5, v0, 0xbe11a98e
	v_fmaak_f32 v0, v5, v0, 0x3e027906
	v_mul_f32_e32 v0, v5, v0
	v_mov_b32_e32 v125, v6
	v_mul_f32_e32 v0, v2, v0
	v_pk_mul_f32 v[2:3], v[214:215], v[124:125]
	v_pk_mul_f32 v[4:5], v[96:97], v[126:127]
	v_pk_fma_f32 v[6:7], v[92:93], v[132:133], v[100:101]
	v_mov_b32_e32 v118, v3
	v_mov_b32_e32 v119, v5
	v_pk_add_f32 v[6:7], v[118:119], v[6:7]
	v_mov_b32_e32 v3, v4
	v_pk_add_f32 v[2:3], v[2:3], v[6:7]
	v_mul_f32_e32 v122, v1, v0
	v_fma_f32 v4, |v2|, s84, 1.0
	v_rcp_f32_e32 v4, v4
	v_fma_f32 v0, -v1, v0, v1
	v_cmp_gt_f32_e64 s[0:1], 0, v1
	v_add_u32_e32 v132, 0xa0, v232
	s_nop 0
	v_cndmask_b32_e64 v0, v0, v122, s[0:1]
	v_mul_f32_e32 v5, v115, v0
	v_fmamk_f32 v0, v4, 0x3f07dc22, v241
	v_fmaak_f32 v6, v4, v0, 0x3f35f0e3
	v_pk_mul_f32 v[0:1], v[2:3], v[2:3]
	v_fmaak_f32 v6, v4, v6, 0xbe11a98e
	v_mul_f32_e32 v0, 0xbf38aa3b, v0
	v_exp_f32_e32 v0, v0
	v_fmaak_f32 v6, v4, v6, 0x3e027906
	v_mul_f32_e32 v4, v4, v6
	v_fma_f32 v6, |v3|, s84, 1.0
	v_rcp_f32_e32 v6, v6
	v_mul_f32_e32 v0, v0, v4
	v_mul_f32_e32 v4, v2, v0
	v_fma_f32 v0, -v2, v0, v2
	v_cmp_gt_f32_e64 s[0:1], 0, v2
	v_mul_f32_e32 v1, 0xbf38aa3b, v1
	v_exp_f32_e32 v1, v1
	v_cndmask_b32_e64 v0, v0, v4, s[0:1]
	v_mul_f32_e32 v4, v116, v0
	v_fmamk_f32 v0, v6, 0x3f07dc22, v241
	v_fmaak_f32 v0, v6, v0, 0x3f35f0e3
	v_fmaak_f32 v0, v6, v0, 0xbe11a98e
	v_fmaak_f32 v0, v6, v0, 0x3e027906
	v_mul_f32_e32 v0, v6, v0
	v_mul_f32_e32 v0, v1, v0
	v_mul_f32_e32 v1, v3, v0
	v_fma_f32 v0, -v3, v0, v3
	v_cmp_gt_f32_e64 s[0:1], 0, v3
	v_cvt_pk_bf16_f32 v2, v114, v5
	s_nop 1
	v_cndmask_b32_e64 v0, v0, v1, s[0:1]
	v_mul_f32_e32 v3, v117, v0
	v_cvt_pk_bf16_f32 v3, v4, v3
	v_lshl_add_u64 v[4:5], s[80:81], 0, v[136:137]
	v_cvt_pk_bf16_f32 v0, v218, v128
	v_lshl_add_u64 v[4:5], v[4:5], 0, v[186:187]
	v_cvt_pk_bf16_f32 v1, v120, v121
	global_store_dwordx4 v[4:5], v[0:3], off
	s_nop 1
	v_max_i32_e32 v0, 1, v132
	v_add_u32_e32 v4, -1, v0
	v_max_i32_e32 v0, 2, v132
	v_add_u32_e32 v118, -2, v0
	v_mov_b64_e32 v[0:1], s[30:31]
	v_mad_i64_i32 v[2:3], s[0:1], v132, s76, v[0:1]
	v_mad_u64_u32 v[4:5], s[0:1], v4, s76, v[0:1]
	v_mad_u64_u32 v[0:1], s[0:1], v118, s76, v[0:1]
	v_lshl_add_u64 v[2:3], v[2:3], 0, v[186:187]
	v_lshl_add_u64 v[4:5], v[4:5], 0, v[186:187]
	v_lshl_add_u64 v[0:1], v[0:1], 0, v[186:187]
	s_movk_i32 s0, 0x1f60
	v_cmp_gt_i32_e64 s[70:71], s0, v232
	s_waitcnt vmcnt(1)
	v_mov_b64_e32 v[114:115], v[196:197]
	v_mov_b64_e32 v[116:117], v[198:199]
	v_mov_b64_e32 v[4:5], v[200:201]
	v_mov_b64_e32 v[6:7], v[202:203]
	v_mov_b64_e32 v[0:1], v[242:243]
	v_mov_b64_e32 v[2:3], v[244:245]
	v_lshlrev_b32_e32 v118, 16, v0
	v_and_b32_e32 v119, 0xffff0000, v0
	v_cndmask_b32_e64 v130, v228, v132, s[70:71]
	v_lshlrev_b32_e32 v120, 16, v1
	v_and_b32_e32 v121, 0xffff0000, v1
	v_lshlrev_b32_e32 v122, 16, v2
	v_and_b32_e32 v123, 0xffff0000, v2
	v_lshlrev_b32_e32 v124, 16, v3
	v_and_b32_e32 v125, 0xffff0000, v3
	v_lshlrev_b32_e32 v0, 16, v4
	v_and_b32_e32 v1, 0xffff0000, v4
	v_lshlrev_b32_e32 v2, 16, v5
	v_and_b32_e32 v3, 0xffff0000, v5
	v_lshlrev_b32_e32 v4, 16, v6
	v_and_b32_e32 v5, 0xffff0000, v6
	v_lshlrev_b32_e32 v6, 16, v7
	v_and_b32_e32 v7, 0xffff0000, v7
	v_cmp_gt_i32_e64 s[0:1], 2, v130
	s_and_saveexec_b64 s[14:15], s[0:1]
	s_cbranch_execz .LBB0_1474
	s_add_i32 s18, s5, 0xffffe0a0
	s_ashr_i32 s18, s18, 4
	v_mov_b32_e32 v118, s18
	v_cndmask_b32_e64 v120, v118, 0, s[70:71]
	v_ashrrev_i32_e32 v121, 31, v120
	v_ashrrev_i32_e32 v131, 31, v130
	v_lshl_add_u64 v[118:119], v[120:121], 1, v[130:131]
	v_mov_b64_e32 v[122:123], s[68:69]
	v_mad_u64_u32 v[122:123], s[18:19], v118, s13, v[122:123]
	s_movk_i32 s0, 0x1f5f
	v_mad_i32_i24 v123, v119, s13, v123
	v_cmp_lt_i32_e64 s[0:1], s0, v232
	v_lshl_add_u64 v[128:129], v[184:185], 2, v[122:123]
	v_mov_b32_e32 v118, 0
	s_and_saveexec_b64 s[18:19], s[0:1]
	s_cbranch_execz .LBB0_1427
	global_load_dword v118, v[128:129], off

;     static __device__ __forceinline__ void unpack8(const u32x4 q, float (&x)[8]) { x[0] = bflo(q.x); x[1] = bfhi(q.x); x[2] = bflo(q.y); x[3] = bfhi(q.y); x[4] = bflo(q.z); x[5] = bfhi(q.z); x[6] = bflo(q.w); x[7] = bfhi(q.w); }
;     __device__ __forceinline__ void operator()(EPI_ARGS) const {
;     ...
;                     for (int t = 0; t < 1; ++t) { const int row = row0 + ai * 128 + (mp + t) * 16; const int r1 = row > 0 ? row - 1 : 0, r2 = row > 1 ? row - 2 : 0;
;                         q2[t] = *(const u32x4*)(up + (size_t)row * DFF + col); q1[t] = *(const u32x4*)(up + (size_t)r1 * DFF + col); q0[t] = *(const u32x4*)(up + (size_t)r2 * DFF + col); }
;                     __builtin_amdgcn_sched_barrier(0);
; #pragma unroll
;                     for (int t = 0; t < 1; ++t) { const int m = mp + t, row = row0 + ai * 128 + m * 16;
;                         const int i = row < TP ? row : ((row - TP) & 15); const int sidx = row < TP ? 0 : ((row - TP) >> 4);
;                         float x0[8], x1[8], x2[8]; unpack8(q0[t], x0); unpack8(q1[t], x1); unpack8(q2[t], x2);
;                         if (i < 2) {
;                             const bool smp = row >= TP; const float* p0 = cs + ((size_t)sidx * 2 + i) * DFF + col; const float* p1 = cs + ((size_t)sidx * 2 + 1) * DFF + col;
; #pragma unroll
;                             for (int e = 0; e < 8; ++e) { x0[e] = smp ? p0[e] : 0.f; if (i == 0) x1[e] = smp ? p1[e] : 0.f; } }
;                         float r[8];
; #pragma unroll
;                         for (int e = 0; e < 8; ++e) { const float cv = bb[e] + x0[e] * w0[e] + x1[e] * w1[e] + x2[e] * w2[e]; r[e] = gelu_f(cv) * acc[ai][bj][m][e >> 2][e & 3]; }
.LBB0_1472:
	s_or_b64 exec, exec, s[20:21]
.LBB0_1473:
	s_or_b64 exec, exec, s[18:19]
	s_waitcnt vmcnt(0)
.LBB0_1474:
	s_or_b64 exec, exec, s[14:15]
	v_mad_i64_i32 v[126:127], s[0:1], v132, s76, 0
	v_lshlrev_b32_e32 v128, 16, v114
	v_and_b32_e32 v114, 0xffff0000, v114
	v_lshlrev_b32_e32 v130, 16, v115
	v_and_b32_e32 v132, 0xffff0000, v115
	s_waitcnt vmcnt(1)
	v_add_u32_e32 v240, 176, v232
	v_mov_b64_e32 v[238:239], s[30:31]
	v_mad_i64_i32 v[238:239], s[0:1], v240, s76, v[238:239]
	v_lshl_add_u64 v[238:239], v[238:239], 0, v[186:187]
	global_load_dwordx4 v[196:199], v[238:239], off
	v_add_u32_e32 v240, -1, v240
	v_mov_b64_e32 v[246:247], s[30:31]
	v_mad_i64_i32 v[246:247], s[0:1], v240, s76, v[246:247]
	v_lshl_add_u64 v[246:247], v[246:247], 0, v[186:187]
	global_load_dwordx4 v[200:203], v[246:247], off
	v_add_u32_e32 v240, -1, v240
	v_mov_b64_e32 v[238:239], s[30:31]
	v_mad_i64_i32 v[238:239], s[0:1], v240, s76, v[238:239]
	v_lshl_add_u64 v[238:239], v[238:239], 0, v[186:187]
	global_load_dwordx4 v[242:245], v[238:239], off
	v_mov_b32_e32 v129, v0
	v_mov_b32_e32 v115, v1
	v_pk_mul_f32 v[128:129], v[210:211], v[128:129]
	v_pk_mul_f32 v[0:1], v[106:107], v[114:115]
	v_pk_fma_f32 v[114:115], v[102:103], v[118:119], v[110:111]
	v_mov_b32_e32 v118, v129
	v_mov_b32_e32 v119, v1
	v_pk_add_f32 v[114:115], v[118:119], v[114:115]
	v_mov_b32_e32 v129, v0
	v_pk_add_f32 v[0:1], v[128:129], v[114:115]
	v_lshlrev_b32_e32 v136, 16, v116
	v_fma_f32 v114, |v0|, s84, 1.0
	v_rcp_f32_e32 v115, v114
	v_pk_mul_f32 v[128:129], v[0:1], v[0:1]
	v_and_b32_e32 v114, 0xffff0000, v116
	v_lshlrev_b32_e32 v116, 16, v117
	v_and_b32_e32 v118, 0xffff0000, v117
	v_fmamk_f32 v117, v115, 0x3f07dc22, v241
	v_mul_f32_e32 v119, 0xbf38aa3b, v128
	v_fmaak_f32 v117, v115, v117, 0x3f35f0e3
	v_exp_f32_e32 v119, v119
	v_fmaak_f32 v117, v115, v117, 0xbe11a98e
	v_fmaak_f32 v117, v115, v117, 0x3e027906
	v_mul_f32_e32 v115, v115, v117
	v_mul_f32_e32 v115, v119, v115
	v_fma_f32 v119, |v1|, s84, 1.0
	v_rcp_f32_e32 v119, v119
	v_mul_f32_e32 v117, v0, v115
	v_fma_f32 v115, -v0, v115, v0
	v_cmp_gt_f32_e64 s[0:1], 0, v0
	v_mov_b32_e32 v131, v2
	v_mov_b32_e32 v133, v3
	v_cndmask_b32_e64 v0, v115, v117, s[0:1]
	v_mul_f32_e32 v138, v86, v0
	v_mul_f32_e32 v86, 0xbf38aa3b, v129
	v_pk_mul_f32 v[128:129], v[172:173], v[130:131]
	v_pk_mul_f32 v[2:3], v[108:109], v[132:133]
	v_fmamk_f32 v0, v119, 0x3f07dc22, v241
	v_pk_fma_f32 v[120:121], v[104:105], v[120:121], v[112:113]
	v_mov_b32_e32 v130, v129
	v_mov_b32_e32 v131, v3
	v_fmaak_f32 v0, v119, v0, 0x3f35f0e3
	v_exp_f32_e32 v86, v86
	v_pk_add_f32 v[120:121], v[130:131], v[120:121]
	v_mov_b32_e32 v129, v2
	v_fmaak_f32 v0, v119, v0, 0xbe11a98e
	v_pk_add_f32 v[2:3], v[128:129], v[120:121]
	v_fmaak_f32 v0, v119, v0, 0x3e027906
	v_fma_f32 v115, |v2|, s84, 1.0
	v_mul_f32_e32 v0, v119, v0
	v_rcp_f32_e32 v115, v115
	v_mul_f32_e32 v0, v86, v0
	v_mul_f32_e32 v86, v1, v0
	v_fma_f32 v0, -v1, v0, v1
	v_cmp_gt_f32_e64 s[0:1], 0, v1
	v_mov_b32_e32 v137, v4
	v_mov_b32_e32 v119, v7
	v_cndmask_b32_e64 v0, v0, v86, s[0:1]
	v_mul_f32_e32 v120, v87, v0
	v_fmamk_f32 v0, v115, 0x3f07dc22, v241
	v_fmaak_f32 v86, v115, v0, 0x3f35f0e3
	v_pk_mul_f32 v[0:1], v[2:3], v[2:3]
	v_fmaak_f32 v86, v115, v86, 0xbe11a98e
	v_mul_f32_e32 v0, 0xbf38aa3b, v0
	v_exp_f32_e32 v0, v0
	v_fmaak_f32 v86, v115, v86, 0x3e027906
	v_fma_f32 v87, |v3|, s84, 1.0
	v_mul_f32_e32 v86, v115, v86
	v_rcp_f32_e32 v87, v87
	v_mul_f32_e32 v0, v0, v86
	v_mul_f32_e32 v86, v2, v0
	v_fma_f32 v0, -v2, v0, v2
	v_cmp_gt_f32_e64 s[0:1], 0, v2
	v_mul_f32_e32 v1, 0xbf38aa3b, v1
	v_exp_f32_e32 v1, v1
	v_cndmask_b32_e64 v0, v0, v86, s[0:1]
	v_mul_f32_e32 v88, v88, v0
	v_fmamk_f32 v0, v87, 0x3f07dc22, v241
	v_fmaak_f32 v0, v87, v0, 0x3f35f0e3
	v_fmaak_f32 v0, v87, v0, 0xbe11a98e
	v_fmaak_f32 v0, v87, v0, 0x3e027906
	v_mul_f32_e32 v0, v87, v0
	v_mul_f32_e32 v0, v1, v0
	v_mov_b32_e32 v115, v5
	v_mul_f32_e32 v2, v3, v0
	v_fma_f32 v117, -v3, v0, v3
	v_pk_mul_f32 v[0:1], v[212:213], v[136:137]
	v_pk_mul_f32 v[4:5], v[94:95], v[114:115]
	v_pk_fma_f32 v[86:87], v[90:91], v[122:123], v[98:99]
	v_mov_b32_e32 v114, v1
	v_mov_b32_e32 v115, v5
	v_pk_add_f32 v[86:87], v[114:115], v[86:87]
	v_mov_b32_e32 v1, v4
	v_pk_add_f32 v[0:1], v[0:1], v[86:87]
	v_cmp_gt_f32_e64 s[0:1], 0, v3
	v_fma_f32 v4, |v0|, s84, 1.0
	v_rcp_f32_e32 v4, v4
	v_cndmask_b32_e64 v2, v117, v2, s[0:1]
	v_mul_f32_e32 v89, v89, v2
	v_cmp_gt_f32_e64 s[0:1], 0, v0
; __device__ __forceinline__ unsigned pk2(float lo, float hi) { unsigned r; asm("v_cvt_pk_bf16_f32 %0, %1, %2" : "=v"(r) : "v"(lo), "v"(hi)); return r; }
;     static __device__ __forceinline__ void unpack8(const u32x4 q, float (&x)[8]) { x[0] = bflo(q.x); x[1] = bfhi(q.x); x[2] = bflo(q.y); x[3] = bfhi(q.y); x[4] = bflo(q.z); x[5] = bfhi(q.z); x[6] = bflo(q.w); x[7] = bfhi(q.w); }
;     __device__ __forceinline__ void operator()(EPI_ARGS) const {
;     ...
;                     for (int t = 0; t < 1; ++t) { const int row = row0 + ai * 128 + (mp + t) * 16; const int r1 = row > 0 ? row - 1 : 0, r2 = row > 1 ? row - 2 : 0;
;                         q2[t] = *(const u32x4*)(up + (size_t)row * DFF + col); q1[t] = *(const u32x4*)(up + (size_t)r1 * DFF + col); q0[t] = *(const u32x4*)(up + (size_t)r2 * DFF + col); }
;                     __builtin_amdgcn_sched_barrier(0);
; #pragma unroll
;                     for (int t = 0; t < 1; ++t) { const int m = mp + t, row = row0 + ai * 128 + m * 16;
;                         const int i = row < TP ? row : ((row - TP) & 15); const int sidx = row < TP ? 0 : ((row - TP) >> 4);
;                         float x0[8], x1[8], x2[8]; unpack8(q0[t], x0); unpack8(q1[t], x1); unpack8(q2[t], x2);
;                         if (i < 2) {
;                             const bool smp = row >= TP; const float* p0 = cs + ((size_t)sidx * 2 + i) * DFF + col; const float* p1 = cs + ((size_t)sidx * 2 + 1) * DFF + col;
; #pragma unroll
;                             for (int e = 0; e < 8; ++e) { x0[e] = smp ? p0[e] : 0.f; if (i == 0) x1[e] = smp ? p1[e] : 0.f; } }
;                         float r[8];
; #pragma unroll
;                         for (int e = 0; e < 8; ++e) { const float cv = bb[e] + x0[e] * w0[e] + x1[e] * w1[e] + x2[e] * w2[e]; r[e] = gelu_f(cv) * acc[ai][bj][m][e >> 2][e & 3]; }
;                         u32x4 w; w.x = pk2(r[0], r[1]); w.y = pk2(r[2], r[3]); w.z = pk2(r[4], r[5]); w.w = pk2(r[6], r[7]);
;                         *(u32x4*)(act + (size_t)row * DFF + col) = w; } } } }
	v_fmamk_f32 v2, v4, 0x3f07dc22, v241
	v_fmaak_f32 v5, v4, v2, 0x3f35f0e3
	v_pk_mul_f32 v[2:3], v[0:1], v[0:1]
	v_fmaak_f32 v5, v4, v5, 0xbe11a98e
	v_mul_f32_e32 v2, 0xbf38aa3b, v2
	v_exp_f32_e32 v2, v2
	v_fmaak_f32 v5, v4, v5, 0x3e027906
	v_mul_f32_e32 v4, v4, v5
	v_fma_f32 v5, |v1|, s84, 1.0
	v_rcp_f32_e32 v5, v5
	v_mul_f32_e32 v2, v2, v4
	v_mul_f32_e32 v4, v0, v2
	v_fma_f32 v2, -v0, v2, v0
	v_cndmask_b32_e64 v0, v2, v4, s[0:1]
	v_mul_f32_e32 v82, v82, v0
	v_fmamk_f32 v0, v5, 0x3f07dc22, v241
	v_mul_f32_e32 v2, 0xbf38aa3b, v3
	v_fmaak_f32 v0, v5, v0, 0x3f35f0e3
	v_exp_f32_e32 v2, v2
	v_fmaak_f32 v0, v5, v0, 0xbe11a98e
	v_fmaak_f32 v0, v5, v0, 0x3e027906
	v_mul_f32_e32 v0, v5, v0
	v_mov_b32_e32 v117, v6
	v_mul_f32_e32 v0, v2, v0
	v_pk_mul_f32 v[2:3], v[214:215], v[116:117]
	v_pk_mul_f32 v[4:5], v[96:97], v[118:119]
	v_pk_fma_f32 v[6:7], v[92:93], v[124:125], v[100:101]
	v_mov_b32_e32 v86, v3
	v_mov_b32_e32 v87, v5
	v_pk_add_f32 v[6:7], v[86:87], v[6:7]
	v_mov_b32_e32 v3, v4
	v_pk_add_f32 v[2:3], v[2:3], v[6:7]
	v_mul_f32_e32 v114, v1, v0
	v_fma_f32 v4, |v2|, s84, 1.0
	v_rcp_f32_e32 v4, v4
	v_fma_f32 v0, -v1, v0, v1
	v_cmp_gt_f32_e64 s[0:1], 0, v1
	v_add_u32_e32 v124, 0xb0, v232
	s_nop 0
	v_cndmask_b32_e64 v0, v0, v114, s[0:1]
	v_mul_f32_e32 v5, v83, v0
	v_fmamk_f32 v0, v4, 0x3f07dc22, v241
	v_fmaak_f32 v6, v4, v0, 0x3f35f0e3
	v_pk_mul_f32 v[0:1], v[2:3], v[2:3]
	v_fmaak_f32 v6, v4, v6, 0xbe11a98e
	v_mul_f32_e32 v0, 0xbf38aa3b, v0
	v_exp_f32_e32 v0, v0
	v_fmaak_f32 v6, v4, v6, 0x3e027906
	v_mul_f32_e32 v4, v4, v6
	v_fma_f32 v6, |v3|, s84, 1.0
	v_rcp_f32_e32 v6, v6
	v_mul_f32_e32 v0, v0, v4
	v_mul_f32_e32 v4, v2, v0
	v_fma_f32 v0, -v2, v0, v2
	v_cmp_gt_f32_e64 s[0:1], 0, v2
	v_mul_f32_e32 v1, 0xbf38aa3b, v1
	v_exp_f32_e32 v1, v1
	v_cndmask_b32_e64 v0, v0, v4, s[0:1]
	v_mul_f32_e32 v4, v84, v0
	v_fmamk_f32 v0, v6, 0x3f07dc22, v241
	v_fmaak_f32 v0, v6, v0, 0x3f35f0e3
	v_fmaak_f32 v0, v6, v0, 0xbe11a98e
	v_fmaak_f32 v0, v6, v0, 0x3e027906
	v_mul_f32_e32 v0, v6, v0
	v_mul_f32_e32 v0, v1, v0
	v_mul_f32_e32 v1, v3, v0
	v_fma_f32 v0, -v3, v0, v3
	v_cmp_gt_f32_e64 s[0:1], 0, v3
	v_cvt_pk_bf16_f32 v2, v82, v5
	s_nop 1
	v_cndmask_b32_e64 v0, v0, v1, s[0:1]
	v_mul_f32_e32 v3, v85, v0
	v_cvt_pk_bf16_f32 v3, v4, v3
	v_lshl_add_u64 v[4:5], s[80:81], 0, v[126:127]
	v_cvt_pk_bf16_f32 v0, v138, v120
	v_lshl_add_u64 v[4:5], v[4:5], 0, v[186:187]
	v_cvt_pk_bf16_f32 v1, v88, v89
	global_store_dwordx4 v[4:5], v[0:3], off
	s_nop 1
	v_max_i32_e32 v0, 1, v124
	v_add_u32_e32 v4, -1, v0
	v_max_i32_e32 v0, 2, v124
	v_add_u32_e32 v86, -2, v0
	v_mov_b64_e32 v[0:1], s[30:31]
	v_mad_i64_i32 v[2:3], s[0:1], v124, s76, v[0:1]
	v_mad_u64_u32 v[4:5], s[0:1], v4, s76, v[0:1]
	v_mad_u64_u32 v[0:1], s[0:1], v86, s76, v[0:1]
	v_lshl_add_u64 v[2:3], v[2:3], 0, v[186:187]
	v_lshl_add_u64 v[4:5], v[4:5], 0, v[186:187]
	v_lshl_add_u64 v[0:1], v[0:1], 0, v[186:187]
	s_movk_i32 s0, 0x1f50
	v_cmp_gt_i32_e64 s[70:71], s0, v232
	s_waitcnt vmcnt(1)
	v_mov_b64_e32 v[82:83], v[196:197]
	v_mov_b64_e32 v[84:85], v[198:199]
	v_mov_b64_e32 v[4:5], v[200:201]
	v_mov_b64_e32 v[6:7], v[202:203]
	v_mov_b64_e32 v[0:1], v[242:243]
	v_mov_b64_e32 v[2:3], v[244:245]
	v_lshlrev_b32_e32 v86, 16, v0
	v_and_b32_e32 v87, 0xffff0000, v0
	v_cndmask_b32_e64 v122, v228, v124, s[70:71]
	v_lshlrev_b32_e32 v88, 16, v1
	v_and_b32_e32 v89, 0xffff0000, v1
	v_lshlrev_b32_e32 v114, 16, v2
	v_and_b32_e32 v115, 0xffff0000, v2
	v_lshlrev_b32_e32 v116, 16, v3
	v_and_b32_e32 v117, 0xffff0000, v3
	v_lshlrev_b32_e32 v0, 16, v4
	v_and_b32_e32 v1, 0xffff0000, v4
	v_lshlrev_b32_e32 v2, 16, v5
	v_and_b32_e32 v3, 0xffff0000, v5
	v_lshlrev_b32_e32 v4, 16, v6
	v_and_b32_e32 v5, 0xffff0000, v6
	v_lshlrev_b32_e32 v6, 16, v7
	v_and_b32_e32 v7, 0xffff0000, v7
	v_cmp_gt_i32_e64 s[0:1], 2, v122
	s_and_saveexec_b64 s[14:15], s[0:1]
	s_cbranch_execz .LBB0_1524
	s_add_i32 s18, s5, 0xffffe0b0
	s_ashr_i32 s18, s18, 4
	v_mov_b32_e32 v86, s18
	v_cndmask_b32_e64 v88, v86, 0, s[70:71]
	v_ashrrev_i32_e32 v89, 31, v88
	v_ashrrev_i32_e32 v123, 31, v122
	v_lshl_add_u64 v[86:87], v[88:89], 1, v[122:123]
	v_mov_b64_e32 v[114:115], s[68:69]
	v_mad_u64_u32 v[114:115], s[18:19], v86, s13, v[114:115]
	s_movk_i32 s0, 0x1f4f
	v_mad_i32_i24 v115, v87, s13, v115
	v_cmp_lt_i32_e64 s[0:1], s0, v232
	v_lshl_add_u64 v[120:121], v[184:185], 2, v[114:115]
	v_mov_b32_e32 v86, 0
	s_and_saveexec_b64 s[18:19], s[0:1]
	s_cbranch_execz .LBB0_1477
	global_load_dword v86, v[120:121], off

; __device__ __forceinline__ unsigned pk2(float lo, float hi) { unsigned r; asm("v_cvt_pk_bf16_f32 %0, %1, %2" : "=v"(r) : "v"(lo), "v"(hi)); return r; }
;     static __device__ __forceinline__ void unpack8(const u32x4 q, float (&x)[8]) { x[0] = bflo(q.x); x[1] = bfhi(q.x); x[2] = bflo(q.y); x[3] = bfhi(q.y); x[4] = bflo(q.z); x[5] = bfhi(q.z); x[6] = bflo(q.w); x[7] = bfhi(q.w); }
;     __device__ __forceinline__ void operator()(EPI_ARGS) const {
;     ...
;                     for (int t = 0; t < 1; ++t) { const int m = mp + t, row = row0 + ai * 128 + m * 16;
;                         const int i = row < TP ? row : ((row - TP) & 15); const int sidx = row < TP ? 0 : ((row - TP) >> 4);
;                         float x0[8], x1[8], x2[8]; unpack8(q0[t], x0); unpack8(q1[t], x1); unpack8(q2[t], x2);
;                         if (i < 2) {
;                             const bool smp = row >= TP; const float* p0 = cs + ((size_t)sidx * 2 + i) * DFF + col; const float* p1 = cs + ((size_t)sidx * 2 + 1) * DFF + col;
; #pragma unroll
;                             for (int e = 0; e < 8; ++e) { x0[e] = smp ? p0[e] : 0.f; if (i == 0) x1[e] = smp ? p1[e] : 0.f; } }
;                         float r[8];
; #pragma unroll
;                         for (int e = 0; e < 8; ++e) { const float cv = bb[e] + x0[e] * w0[e] + x1[e] * w1[e] + x2[e] * w2[e]; r[e] = gelu_f(cv) * acc[ai][bj][m][e >> 2][e & 3]; }
;                         u32x4 w; w.x = pk2(r[0], r[1]); w.y = pk2(r[2], r[3]); w.z = pk2(r[4], r[5]); w.w = pk2(r[6], r[7]);
;                         *(u32x4*)(act + (size_t)row * DFF + col) = w; } } } }
.LBB0_1522:
	s_or_b64 exec, exec, s[20:21]
.LBB0_1523:
	s_or_b64 exec, exec, s[18:19]
	s_waitcnt vmcnt(0)
.LBB0_1524:
	s_or_b64 exec, exec, s[14:15]
	v_mad_i64_i32 v[118:119], s[0:1], v124, s76, 0
	v_lshlrev_b32_e32 v120, 16, v82
	v_and_b32_e32 v82, 0xffff0000, v82
	v_lshlrev_b32_e32 v122, 16, v83
	v_and_b32_e32 v124, 0xffff0000, v83
	s_waitcnt vmcnt(1)
	v_mov_b32_e32 v121, v0
	v_mov_b32_e32 v83, v1
	v_pk_mul_f32 v[120:121], v[210:211], v[120:121]
	v_pk_mul_f32 v[0:1], v[106:107], v[82:83]
	v_pk_fma_f32 v[82:83], v[102:103], v[86:87], v[110:111]
	v_mov_b32_e32 v86, v121
	v_mov_b32_e32 v87, v1
	v_pk_add_f32 v[82:83], v[86:87], v[82:83]
	v_mov_b32_e32 v121, v0
	v_pk_add_f32 v[0:1], v[120:121], v[82:83]
	v_lshlrev_b32_e32 v126, 16, v84
	v_fma_f32 v82, |v0|, s84, 1.0
	v_rcp_f32_e32 v83, v82
	v_pk_mul_f32 v[102:103], v[0:1], v[0:1]
	v_and_b32_e32 v82, 0xffff0000, v84
	v_lshlrev_b32_e32 v84, 16, v85
	v_and_b32_e32 v86, 0xffff0000, v85
	v_fmamk_f32 v85, v83, 0x3f07dc22, v241
	v_mul_f32_e32 v87, 0xbf38aa3b, v102
	v_fmaak_f32 v85, v83, v85, 0x3f35f0e3
	v_exp_f32_e32 v87, v87
	v_fmaak_f32 v85, v83, v85, 0xbe11a98e
	v_fmaak_f32 v85, v83, v85, 0x3e027906
	v_mul_f32_e32 v83, v83, v85
	v_mul_f32_e32 v83, v87, v83
	v_fma_f32 v87, |v1|, s84, 1.0
	v_rcp_f32_e32 v87, v87
	v_mul_f32_e32 v85, v0, v83
	v_fma_f32 v83, -v0, v83, v0
	v_cmp_gt_f32_e64 s[0:1], 0, v0
	v_mov_b32_e32 v123, v2
	v_mov_b32_e32 v125, v3
	v_cndmask_b32_e64 v0, v83, v85, s[0:1]
	v_mul_f32_e32 v106, v78, v0
	v_mul_f32_e32 v78, 0xbf38aa3b, v103
	v_pk_mul_f32 v[102:103], v[172:173], v[122:123]
	v_pk_mul_f32 v[2:3], v[108:109], v[124:125]
	v_fmamk_f32 v0, v87, 0x3f07dc22, v241
	v_pk_fma_f32 v[88:89], v[104:105], v[88:89], v[112:113]
	v_mov_b32_e32 v104, v103
	v_mov_b32_e32 v105, v3
	v_fmaak_f32 v0, v87, v0, 0x3f35f0e3
	v_exp_f32_e32 v78, v78
	v_pk_add_f32 v[88:89], v[104:105], v[88:89]
	v_mov_b32_e32 v103, v2
	v_fmaak_f32 v0, v87, v0, 0xbe11a98e
	v_pk_add_f32 v[2:3], v[102:103], v[88:89]
	v_fmaak_f32 v0, v87, v0, 0x3e027906
	v_fma_f32 v83, |v2|, s84, 1.0
	v_mul_f32_e32 v0, v87, v0
	v_rcp_f32_e32 v83, v83
	v_mul_f32_e32 v0, v78, v0
	v_mul_f32_e32 v78, v1, v0
	v_fma_f32 v0, -v1, v0, v1
	v_cmp_gt_f32_e64 s[0:1], 0, v1
	v_mov_b32_e32 v127, v4
	v_mov_b32_e32 v87, v7
	v_cndmask_b32_e64 v0, v0, v78, s[0:1]
	v_mul_f32_e32 v88, v79, v0
	v_fmamk_f32 v0, v83, 0x3f07dc22, v241
	v_fmaak_f32 v78, v83, v0, 0x3f35f0e3
	v_pk_mul_f32 v[0:1], v[2:3], v[2:3]
	v_fmaak_f32 v78, v83, v78, 0xbe11a98e
	v_mul_f32_e32 v0, 0xbf38aa3b, v0
	v_exp_f32_e32 v0, v0
	v_fmaak_f32 v78, v83, v78, 0x3e027906
	v_fma_f32 v79, |v3|, s84, 1.0
	v_mul_f32_e32 v78, v83, v78
	v_rcp_f32_e32 v79, v79
	v_mul_f32_e32 v0, v0, v78
	v_mul_f32_e32 v78, v2, v0
	v_fma_f32 v0, -v2, v0, v2
	v_cmp_gt_f32_e64 s[0:1], 0, v2
	v_mul_f32_e32 v1, 0xbf38aa3b, v1
	v_exp_f32_e32 v1, v1
	v_cndmask_b32_e64 v0, v0, v78, s[0:1]
	v_mul_f32_e32 v80, v80, v0
	v_fmamk_f32 v0, v79, 0x3f07dc22, v241
	v_fmaak_f32 v0, v79, v0, 0x3f35f0e3
	v_fmaak_f32 v0, v79, v0, 0xbe11a98e
	v_fmaak_f32 v0, v79, v0, 0x3e027906
	v_mul_f32_e32 v0, v79, v0
	v_mul_f32_e32 v0, v1, v0
	v_mov_b32_e32 v83, v5
	v_mul_f32_e32 v2, v3, v0
	v_fma_f32 v85, -v3, v0, v3
	v_pk_mul_f32 v[0:1], v[212:213], v[126:127]
	v_pk_mul_f32 v[4:5], v[94:95], v[82:83]
	v_pk_fma_f32 v[78:79], v[90:91], v[114:115], v[98:99]
	v_mov_b32_e32 v82, v1
	v_mov_b32_e32 v83, v5
	v_pk_add_f32 v[78:79], v[82:83], v[78:79]
	v_mov_b32_e32 v1, v4
	v_pk_add_f32 v[0:1], v[0:1], v[78:79]
	v_cmp_gt_f32_e64 s[0:1], 0, v3
	v_fma_f32 v4, |v0|, s84, 1.0
	v_rcp_f32_e32 v4, v4
	v_cndmask_b32_e64 v2, v85, v2, s[0:1]
	v_mul_f32_e32 v81, v81, v2
	v_cmp_gt_f32_e64 s[0:1], 0, v0
	v_fmamk_f32 v2, v4, 0x3f07dc22, v241
	v_fmaak_f32 v5, v4, v2, 0x3f35f0e3
	v_pk_mul_f32 v[2:3], v[0:1], v[0:1]
	v_fmaak_f32 v5, v4, v5, 0xbe11a98e
	v_mul_f32_e32 v2, 0xbf38aa3b, v2
	v_exp_f32_e32 v2, v2
	v_fmaak_f32 v5, v4, v5, 0x3e027906
	v_mul_f32_e32 v4, v4, v5
	v_fma_f32 v5, |v1|, s84, 1.0
	v_rcp_f32_e32 v5, v5
	v_mul_f32_e32 v2, v2, v4
	v_mul_f32_e32 v4, v0, v2
	v_fma_f32 v2, -v0, v2, v0
	v_cndmask_b32_e64 v0, v2, v4, s[0:1]
	v_mul_f32_e32 v74, v74, v0
	v_fmamk_f32 v0, v5, 0x3f07dc22, v241
	v_mul_f32_e32 v2, 0xbf38aa3b, v3
	v_fmaak_f32 v0, v5, v0, 0x3f35f0e3
	v_exp_f32_e32 v2, v2
	v_fmaak_f32 v0, v5, v0, 0xbe11a98e
	v_fmaak_f32 v0, v5, v0, 0x3e027906
	v_mul_f32_e32 v0, v5, v0
	v_mov_b32_e32 v85, v6
	v_mul_f32_e32 v0, v2, v0
	v_pk_mul_f32 v[2:3], v[214:215], v[84:85]
	v_pk_mul_f32 v[4:5], v[96:97], v[86:87]
	v_pk_fma_f32 v[6:7], v[92:93], v[116:117], v[100:101]
	v_mov_b32_e32 v78, v3
	v_mov_b32_e32 v79, v5
	v_pk_add_f32 v[6:7], v[78:79], v[6:7]
	v_mov_b32_e32 v3, v4
	v_pk_add_f32 v[2:3], v[2:3], v[6:7]
	v_mul_f32_e32 v82, v1, v0
	v_fma_f32 v4, |v2|, s84, 1.0
	v_rcp_f32_e32 v4, v4
	v_fma_f32 v0, -v1, v0, v1
	v_cmp_gt_f32_e64 s[0:1], 0, v1
	s_nop 1
	v_cndmask_b32_e64 v0, v0, v82, s[0:1]
	v_mul_f32_e32 v5, v75, v0
	v_fmamk_f32 v0, v4, 0x3f07dc22, v241
	v_fmaak_f32 v6, v4, v0, 0x3f35f0e3
	v_pk_mul_f32 v[0:1], v[2:3], v[2:3]
	v_fmaak_f32 v6, v4, v6, 0xbe11a98e
	v_mul_f32_e32 v0, 0xbf38aa3b, v0
	v_exp_f32_e32 v0, v0
	v_fmaak_f32 v6, v4, v6, 0x3e027906
	v_mul_f32_e32 v4, v4, v6
	v_fma_f32 v6, |v3|, s84, 1.0
	v_rcp_f32_e32 v6, v6
	v_mul_f32_e32 v0, v0, v4
	v_mul_f32_e32 v4, v2, v0
	v_fma_f32 v0, -v2, v0, v2
	v_cmp_gt_f32_e64 s[0:1], 0, v2
	v_mul_f32_e32 v1, 0xbf38aa3b, v1
	v_exp_f32_e32 v1, v1
	v_cndmask_b32_e64 v0, v0, v4, s[0:1]
	v_mul_f32_e32 v4, v76, v0
	v_fmamk_f32 v0, v6, 0x3f07dc22, v241
	v_fmaak_f32 v0, v6, v0, 0x3f35f0e3
	v_fmaak_f32 v0, v6, v0, 0xbe11a98e
	v_fmaak_f32 v0, v6, v0, 0x3e027906
	v_mul_f32_e32 v0, v6, v0
	v_mul_f32_e32 v0, v1, v0
	v_mul_f32_e32 v1, v3, v0
	v_fma_f32 v0, -v3, v0, v3
	v_cmp_gt_f32_e64 s[0:1], 0, v3
	v_cvt_pk_bf16_f32 v2, v74, v5
	s_nop 1
	v_cndmask_b32_e64 v0, v0, v1, s[0:1]
	v_mul_f32_e32 v3, v77, v0
	v_cvt_pk_bf16_f32 v3, v4, v3
	v_lshl_add_u64 v[4:5], s[80:81], 0, v[118:119]
	v_lshl_add_u64 v[4:5], v[184:185], 1, v[4:5]
	v_cvt_pk_bf16_f32 v0, v106, v88
	v_cvt_pk_bf16_f32 v1, v80, v81
	global_store_dwordx4 v[4:5], v[0:3], off

; __device__ __forceinline__ unsigned pk2(float lo, float hi) { unsigned r; asm("v_cvt_pk_bf16_f32 %0, %1, %2" : "=v"(r) : "v"(lo), "v"(hi)); return r; }
;     static __device__ __forceinline__ void unpack8(const u32x4 q, float (&x)[8]) { x[0] = bflo(q.x); x[1] = bfhi(q.x); x[2] = bflo(q.y); x[3] = bfhi(q.y); x[4] = bflo(q.z); x[5] = bfhi(q.z); x[6] = bflo(q.w); x[7] = bfhi(q.w); }
;     __device__ __forceinline__ void operator()(EPI_ARGS) const {
;     ...
;                     for (int t = 0; t < 1; ++t) { const int row = row0 + ai * 128 + (mp + t) * 16; const int r1 = row > 0 ? row - 1 : 0, r2 = row > 1 ? row - 2 : 0;
;                         q2[t] = *(const u32x4*)(up + (size_t)row * DFF + col); q1[t] = *(const u32x4*)(up + (size_t)r1 * DFF + col); q0[t] = *(const u32x4*)(up + (size_t)r2 * DFF + col); }
;                     __builtin_amdgcn_sched_barrier(0);
; #pragma unroll
;                     for (int t = 0; t < 1; ++t) { const int m = mp + t, row = row0 + ai * 128 + m * 16;
;                         const int i = row < TP ? row : ((row - TP) & 15); const int sidx = row < TP ? 0 : ((row - TP) >> 4);
;                         float x0[8], x1[8], x2[8]; unpack8(q0[t], x0); unpack8(q1[t], x1); unpack8(q2[t], x2);
;                         if (i < 2) {
;                             const bool smp = row >= TP; const float* p0 = cs + ((size_t)sidx * 2 + i) * DFF + col; const float* p1 = cs + ((size_t)sidx * 2 + 1) * DFF + col;
; #pragma unroll
;                             for (int e = 0; e < 8; ++e) { x0[e] = smp ? p0[e] : 0.f; if (i == 0) x1[e] = smp ? p1[e] : 0.f; } }
;                         float r[8];
; #pragma unroll
;                         for (int e = 0; e < 8; ++e) { const float cv = bb[e] + x0[e] * w0[e] + x1[e] * w1[e] + x2[e] * w2[e]; r[e] = gelu_f(cv) * acc[ai][bj][m][e >> 2][e & 3]; }
;                         u32x4 w; w.x = pk2(r[0], r[1]); w.y = pk2(r[2], r[3]); w.z = pk2(r[4], r[5]); w.w = pk2(r[6], r[7]);
;                         *(u32x4*)(act + (size_t)row * DFF + col) = w; } } } }
.LBB0_1575:
	s_or_b64 exec, exec, s[0:1]
	v_lshlrev_b32_e32 v120, 16, v106
	v_and_b32_e32 v122, 0xffff0000, v106
	v_lshlrev_b32_e32 v124, 16, v107
	v_and_b32_e32 v126, 0xffff0000, v107
	v_mov_b32_e32 v106, v102
	v_mov_b32_e32 v107, v90
	s_waitcnt vmcnt(0)
	v_add_u32_e32 v240, 16, v232
	v_mov_b64_e32 v[238:239], s[30:31]
	v_mad_i64_i32 v[238:239], s[0:1], v240, s76, v[238:239]
	v_lshl_add_u64 v[238:239], v[238:239], 0, v[186:187]
	global_load_dwordx4 v[196:199], v[238:239], off offset:256
	v_add_u32_e32 v240, -1, v240
	v_mov_b64_e32 v[246:247], s[30:31]
	v_mad_i64_i32 v[246:247], s[0:1], v240, s76, v[246:247]
	v_lshl_add_u64 v[246:247], v[246:247], 0, v[186:187]
	global_load_dwordx4 v[200:203], v[246:247], off offset:256
	v_add_u32_e32 v240, -1, v240
	v_mov_b64_e32 v[238:239], s[30:31]
	v_mad_i64_i32 v[238:239], s[0:1], v240, s76, v[238:239]
	v_lshl_add_u64 v[238:239], v[238:239], 0, v[186:187]
	global_load_dwordx4 v[242:245], v[238:239], off offset:256
	v_mov_b32_e32 v121, v0
	v_mov_b32_e32 v90, v103
	v_mov_b32_e32 v123, v1
	v_pk_mul_f32 v[120:121], v[106:107], v[120:121]
	v_pk_mul_f32 v[0:1], v[90:91], v[122:123]
	v_pk_fma_f32 v[102:103], v[86:87], v[112:113], v[94:95]
	v_mov_b32_e32 v112, v121
	v_mov_b32_e32 v113, v1
	v_pk_add_f32 v[102:103], v[112:113], v[102:103]
	v_mov_b32_e32 v121, v0
	v_pk_add_f32 v[0:1], v[120:121], v[102:103]
	v_lshlrev_b32_e32 v112, 16, v109
	v_fma_f32 v102, |v0|, s84, 1.0
	v_rcp_f32_e32 v113, v102
	v_and_b32_e32 v120, 0xffff0000, v109
	v_cmp_gt_f32_e32 vcc, 0, v0
	v_mov_b32_e32 v125, v2
	v_fmamk_f32 v102, v113, 0x3f07dc22, v241
	v_fmaak_f32 v109, v113, v102, 0x3f35f0e3
	v_pk_mul_f32 v[102:103], v[0:1], v[0:1]
	v_fmaak_f32 v109, v113, v109, 0xbe11a98e
	v_mul_f32_e32 v102, 0xbf38aa3b, v102
	v_exp_f32_e32 v102, v102
	v_fmaak_f32 v109, v113, v109, 0x3e027906
	v_mul_f32_e32 v109, v113, v109
	v_fma_f32 v113, |v1|, s84, 1.0
	v_mul_f32_e32 v102, v102, v109
	v_mul_f32_e32 v109, v0, v102
	v_fma_f32 v102, -v0, v102, v0
	v_rcp_f32_e32 v113, v113
	v_cndmask_b32_e32 v0, v102, v109, vcc
	v_mul_f32_e32 v130, v70, v0
	v_mul_f32_e32 v70, 0xbf38aa3b, v103
	v_mov_b32_e32 v102, v104
	v_mov_b32_e32 v103, v92
	v_mov_b32_e32 v92, v105
	v_mov_b32_e32 v127, v3
	v_pk_mul_f32 v[122:123], v[102:103], v[124:125]
	v_pk_mul_f32 v[2:3], v[92:93], v[126:127]
	v_fmamk_f32 v0, v113, 0x3f07dc22, v241
	v_pk_fma_f32 v[104:105], v[88:89], v[114:115], v[96:97]
	v_mov_b32_e32 v114, v123
	v_mov_b32_e32 v115, v3
	v_fmaak_f32 v0, v113, v0, 0x3f35f0e3
	v_exp_f32_e32 v70, v70
	v_pk_add_f32 v[104:105], v[114:115], v[104:105]
	v_mov_b32_e32 v123, v2
	v_fmaak_f32 v0, v113, v0, 0xbe11a98e
	v_pk_add_f32 v[2:3], v[122:123], v[104:105]
	v_fmaak_f32 v0, v113, v0, 0x3e027906
	v_fma_f32 v104, |v2|, s84, 1.0
	v_mul_f32_e32 v0, v113, v0
	v_rcp_f32_e32 v104, v104
	v_mul_f32_e32 v0, v70, v0
	v_mul_f32_e32 v70, v1, v0
	v_fma_f32 v0, -v1, v0, v1
	v_cmp_gt_f32_e32 vcc, 0, v1
	v_lshlrev_b32_e32 v128, 16, v108
	v_and_b32_e32 v108, 0xffff0000, v108
	v_cndmask_b32_e32 v0, v0, v70, vcc
	v_mul_f32_e32 v114, v71, v0
	v_fmamk_f32 v0, v104, 0x3f07dc22, v241
	v_fmaak_f32 v70, v104, v0, 0x3f35f0e3
	v_pk_mul_f32 v[0:1], v[2:3], v[2:3]
	v_fmaak_f32 v70, v104, v70, 0xbe11a98e
	v_mul_f32_e32 v0, 0xbf38aa3b, v0
	v_exp_f32_e32 v0, v0
	v_fmaak_f32 v70, v104, v70, 0x3e027906
	v_fma_f32 v71, |v3|, s84, 1.0
	v_mul_f32_e32 v70, v104, v70
	v_rcp_f32_e32 v71, v71
	v_mul_f32_e32 v0, v0, v70
	v_mul_f32_e32 v70, v2, v0
	v_fma_f32 v0, -v2, v0, v2
	v_cmp_gt_f32_e32 vcc, 0, v2
	v_mul_f32_e32 v1, 0xbf38aa3b, v1
	v_exp_f32_e32 v1, v1
	v_cndmask_b32_e32 v0, v0, v70, vcc
	v_mul_f32_e32 v115, v72, v0
	v_fmamk_f32 v0, v71, 0x3f07dc22, v241
	v_fmaak_f32 v0, v71, v0, 0x3f35f0e3
	v_fmaak_f32 v0, v71, v0, 0xbe11a98e
	v_fmaak_f32 v0, v71, v0, 0x3e027906
	v_mul_f32_e32 v0, v71, v0
	v_mul_f32_e32 v0, v1, v0
	v_mov_b32_e32 v70, v98
	v_mov_b32_e32 v71, v78
	v_mov_b32_e32 v129, v4
	v_mov_b32_e32 v78, v99
	v_mov_b32_e32 v109, v5
	v_mul_f32_e32 v2, v3, v0
	v_fma_f32 v72, -v3, v0, v3
	v_pk_mul_f32 v[0:1], v[70:71], v[128:129]
	v_pk_mul_f32 v[4:5], v[78:79], v[108:109]
	v_pk_fma_f32 v[98:99], v[74:75], v[116:117], v[82:83]
	v_mov_b32_e32 v104, v1
	v_mov_b32_e32 v105, v5
	v_pk_add_f32 v[98:99], v[104:105], v[98:99]
	v_mov_b32_e32 v1, v4
	v_pk_add_f32 v[0:1], v[0:1], v[98:99]
	v_cmp_gt_f32_e32 vcc, 0, v3
	v_fma_f32 v4, |v0|, s84, 1.0
	v_rcp_f32_e32 v4, v4
	v_cndmask_b32_e32 v2, v72, v2, vcc
	v_mul_f32_e32 v104, v73, v2
	v_cmp_gt_f32_e32 vcc, 0, v0
	v_fmamk_f32 v2, v4, 0x3f07dc22, v241
	v_fmaak_f32 v5, v4, v2, 0x3f35f0e3
	v_pk_mul_f32 v[2:3], v[0:1], v[0:1]
	v_fmaak_f32 v5, v4, v5, 0xbe11a98e
	v_mul_f32_e32 v2, 0xbf38aa3b, v2
	v_exp_f32_e32 v2, v2
	v_fmaak_f32 v5, v4, v5, 0x3e027906
	v_mul_f32_e32 v4, v4, v5
	v_fma_f32 v5, |v1|, s84, 1.0
	v_rcp_f32_e32 v5, v5
	v_mul_f32_e32 v2, v2, v4
	v_mul_f32_e32 v4, v0, v2
	v_fma_f32 v2, -v0, v2, v0
	v_cndmask_b32_e32 v0, v2, v4, vcc
	v_mul_f32_e32 v66, v66, v0
	v_fmamk_f32 v0, v5, 0x3f07dc22, v241
	v_mul_f32_e32 v2, 0xbf38aa3b, v3
	v_fmaak_f32 v0, v5, v0, 0x3f35f0e3
	v_exp_f32_e32 v2, v2
	v_fmaak_f32 v0, v5, v0, 0xbe11a98e
	v_fmaak_f32 v0, v5, v0, 0x3e027906
	v_mul_f32_e32 v0, v5, v0
	v_mov_b32_e32 v72, v100
	v_mov_b32_e32 v73, v80
	v_mov_b32_e32 v113, v6
	v_mov_b32_e32 v80, v101
	v_mov_b32_e32 v121, v7
	v_mul_f32_e32 v0, v2, v0
	v_pk_mul_f32 v[2:3], v[72:73], v[112:113]
	v_pk_mul_f32 v[4:5], v[80:81], v[120:121]
	v_pk_fma_f32 v[6:7], v[76:77], v[118:119], v[84:85]
	v_mov_b32_e32 v98, v3
	v_mov_b32_e32 v99, v5
	v_pk_add_f32 v[6:7], v[98:99], v[6:7]
	v_mov_b32_e32 v3, v4
	v_pk_add_f32 v[2:3], v[2:3], v[6:7]
	v_mul_f32_e32 v105, v1, v0
	v_fma_f32 v4, |v2|, s84, 1.0
	v_rcp_f32_e32 v4, v4
	v_fma_f32 v0, -v1, v0, v1
	v_cmp_gt_f32_e32 vcc, 0, v1
	s_nop 1
	v_cndmask_b32_e32 v0, v0, v105, vcc
	v_mul_f32_e32 v5, v67, v0
	v_fmamk_f32 v0, v4, 0x3f07dc22, v241
	v_fmaak_f32 v6, v4, v0, 0x3f35f0e3
	v_pk_mul_f32 v[0:1], v[2:3], v[2:3]
	v_fmaak_f32 v6, v4, v6, 0xbe11a98e
	v_mul_f32_e32 v0, 0xbf38aa3b, v0
	v_exp_f32_e32 v0, v0
	v_fmaak_f32 v6, v4, v6, 0x3e027906
	v_mul_f32_e32 v4, v4, v6
	v_fma_f32 v6, |v3|, s84, 1.0
	v_rcp_f32_e32 v6, v6
	v_mul_f32_e32 v0, v0, v4
	v_mul_f32_e32 v4, v2, v0
	v_fma_f32 v0, -v2, v0, v2
	v_cmp_gt_f32_e32 vcc, 0, v2
	v_mul_f32_e32 v1, 0xbf38aa3b, v1
	v_exp_f32_e32 v1, v1
	v_cndmask_b32_e32 v0, v0, v4, vcc
	v_mul_f32_e32 v4, v68, v0
	v_fmamk_f32 v0, v6, 0x3f07dc22, v241
	v_fmaak_f32 v0, v6, v0, 0x3f35f0e3
	v_fmaak_f32 v0, v6, v0, 0xbe11a98e
	v_fmaak_f32 v0, v6, v0, 0x3e027906
	v_mul_f32_e32 v0, v6, v0
	v_mul_f32_e32 v0, v1, v0
	v_mul_f32_e32 v1, v3, v0
	v_fma_f32 v0, -v3, v0, v3
	v_cmp_gt_f32_e32 vcc, 0, v3
	v_cvt_pk_bf16_f32 v2, v66, v5
	s_nop 1
	v_cndmask_b32_e32 v0, v0, v1, vcc
	v_mul_f32_e32 v3, v69, v0
	v_cvt_pk_bf16_f32 v0, v130, v114
	v_cvt_pk_bf16_f32 v1, v115, v104
	v_cvt_pk_bf16_f32 v3, v4, v3
	global_store_dwordx4 v[160:161], v[0:3], off offset:256
	s_waitcnt vmcnt(1)
;     static __device__ __forceinline__ void unpack8(const u32x4 q, float (&x)[8]) { x[0] = bflo(q.x); x[1] = bfhi(q.x); x[2] = bflo(q.y); x[3] = bfhi(q.y); x[4] = bflo(q.z); x[5] = bfhi(q.z); x[6] = bflo(q.w); x[7] = bfhi(q.w); }
;     __device__ __forceinline__ void operator()(EPI_ARGS) const {
;     ...
;                         q2[t] = *(const u32x4*)(up + (size_t)row * DFF + col); q1[t] = *(const u32x4*)(up + (size_t)r1 * DFF + col); q0[t] = *(const u32x4*)(up + (size_t)r2 * DFF + col); }
;                     __builtin_amdgcn_sched_barrier(0);
; #pragma unroll
;                     for (int t = 0; t < 1; ++t) { const int m = mp + t, row = row0 + ai * 128 + m * 16;
;                         const int i = row < TP ? row : ((row - TP) & 15); const int sidx = row < TP ? 0 : ((row - TP) >> 4);
;                         float x0[8], x1[8], x2[8]; unpack8(q0[t], x0); unpack8(q1[t], x1); unpack8(q2[t], x2);
;                         if (i < 2) {
;                             const bool smp = row >= TP; const float* p0 = cs + ((size_t)sidx * 2 + i) * DFF + col; const float* p1 = cs + ((size_t)sidx * 2 + 1) * DFF + col;
; #pragma unroll
;                             for (int e = 0; e < 8; ++e) { x0[e] = smp ? p0[e] : 0.f; if (i == 0) x1[e] = smp ? p1[e] : 0.f; } }
	v_mov_b64_e32 v[66:67], v[196:197]
	v_mov_b64_e32 v[68:69], v[198:199]
	v_mov_b64_e32 v[4:5], v[200:201]
	v_mov_b64_e32 v[6:7], v[202:203]
	v_mov_b64_e32 v[0:1], v[242:243]
	v_mov_b64_e32 v[2:3], v[244:245]
	v_lshlrev_b32_e32 v98, 16, v0
	v_and_b32_e32 v99, 0xffff0000, v0
	v_lshlrev_b32_e32 v100, 16, v1
	v_and_b32_e32 v101, 0xffff0000, v1
	v_lshlrev_b32_e32 v104, 16, v2
	v_and_b32_e32 v105, 0xffff0000, v2
	v_lshlrev_b32_e32 v108, 16, v3
	v_and_b32_e32 v109, 0xffff0000, v3
	v_lshlrev_b32_e32 v0, 16, v4
	v_and_b32_e32 v1, 0xffff0000, v4
	v_lshlrev_b32_e32 v2, 16, v5
	v_and_b32_e32 v3, 0xffff0000, v5
	v_lshlrev_b32_e32 v4, 16, v6
	v_and_b32_e32 v5, 0xffff0000, v6
	v_lshlrev_b32_e32 v6, 16, v7
	v_and_b32_e32 v7, 0xffff0000, v7
	s_and_saveexec_b64 s[0:1], s[60:61]
	s_cbranch_execz .LBB0_1625
	s_add_i32 s14, s5, 0xffffe010
	s_ashr_i32 s14, s14, 4
	v_mov_b32_e32 v98, s14
	v_cndmask_b32_e64 v100, v98, 0, s[54:55]
	v_ashrrev_i32_e32 v101, 31, v100
	v_lshl_add_u64 v[98:99], v[100:101], 1, v[158:159]
	v_mov_b64_e32 v[104:105], s[68:69]
	v_mad_u64_u32 v[104:105], s[14:15], v98, s13, v[104:105]
	v_mad_i32_i24 v105, v99, s13, v105
	v_lshl_add_u64 v[114:115], v[184:185], 2, v[104:105]
	v_mov_b32_e32 v98, 0
	s_and_saveexec_b64 s[14:15], s[40:41]
	s_cbranch_execz .LBB0_1578
	global_load_dword v98, v[114:115], off offset:512

; __device__ __forceinline__ unsigned pk2(float lo, float hi) { unsigned r; asm("v_cvt_pk_bf16_f32 %0, %1, %2" : "=v"(r) : "v"(lo), "v"(hi)); return r; }
;     static __device__ __forceinline__ void unpack8(const u32x4 q, float (&x)[8]) { x[0] = bflo(q.x); x[1] = bfhi(q.x); x[2] = bflo(q.y); x[3] = bfhi(q.y); x[4] = bflo(q.z); x[5] = bfhi(q.z); x[6] = bflo(q.w); x[7] = bfhi(q.w); }
;     __device__ __forceinline__ void operator()(EPI_ARGS) const {
;     ...
;                     for (int t = 0; t < 1; ++t) { const int row = row0 + ai * 128 + (mp + t) * 16; const int r1 = row > 0 ? row - 1 : 0, r2 = row > 1 ? row - 2 : 0;
;                         q2[t] = *(const u32x4*)(up + (size_t)row * DFF + col); q1[t] = *(const u32x4*)(up + (size_t)r1 * DFF + col); q0[t] = *(const u32x4*)(up + (size_t)r2 * DFF + col); }
;                     __builtin_amdgcn_sched_barrier(0);
; #pragma unroll
;                     for (int t = 0; t < 1; ++t) { const int m = mp + t, row = row0 + ai * 128 + m * 16;
;                         const int i = row < TP ? row : ((row - TP) & 15); const int sidx = row < TP ? 0 : ((row - TP) >> 4);
;                         float x0[8], x1[8], x2[8]; unpack8(q0[t], x0); unpack8(q1[t], x1); unpack8(q2[t], x2);
;                         if (i < 2) {
;                             const bool smp = row >= TP; const float* p0 = cs + ((size_t)sidx * 2 + i) * DFF + col; const float* p1 = cs + ((size_t)sidx * 2 + 1) * DFF + col;
; #pragma unroll
;                             for (int e = 0; e < 8; ++e) { x0[e] = smp ? p0[e] : 0.f; if (i == 0) x1[e] = smp ? p1[e] : 0.f; } }
;                         float r[8];
; #pragma unroll
;                         for (int e = 0; e < 8; ++e) { const float cv = bb[e] + x0[e] * w0[e] + x1[e] * w1[e] + x2[e] * w2[e]; r[e] = gelu_f(cv) * acc[ai][bj][m][e >> 2][e & 3]; }
;                         u32x4 w; w.x = pk2(r[0], r[1]); w.y = pk2(r[2], r[3]); w.z = pk2(r[4], r[5]); w.w = pk2(r[6], r[7]);
;                         *(u32x4*)(act + (size_t)row * DFF + col) = w; } } } }
.LBB0_1623:
	s_or_b64 exec, exec, s[18:19]
.LBB0_1624:
	s_or_b64 exec, exec, s[14:15]
	s_waitcnt vmcnt(0)
.LBB0_1625:
	s_or_b64 exec, exec, s[0:1]
	v_lshlrev_b32_e32 v112, 16, v66
	v_and_b32_e32 v66, 0xffff0000, v66
	v_lshlrev_b32_e32 v114, 16, v67
	v_and_b32_e32 v116, 0xffff0000, v67
	s_waitcnt vmcnt(1)
	v_add_u32_e32 v240, 32, v232
	v_mov_b64_e32 v[238:239], s[30:31]
	v_mad_i64_i32 v[238:239], s[0:1], v240, s76, v[238:239]
	v_lshl_add_u64 v[238:239], v[238:239], 0, v[186:187]
	global_load_dwordx4 v[196:199], v[238:239], off offset:256
	v_add_u32_e32 v240, -1, v240
	v_mov_b64_e32 v[246:247], s[30:31]
	v_mad_i64_i32 v[246:247], s[0:1], v240, s76, v[246:247]
	v_lshl_add_u64 v[246:247], v[246:247], 0, v[186:187]
	global_load_dwordx4 v[200:203], v[246:247], off offset:256
	v_add_u32_e32 v240, -1, v240
	v_mov_b64_e32 v[238:239], s[30:31]
	v_mad_i64_i32 v[238:239], s[0:1], v240, s76, v[238:239]
	v_lshl_add_u64 v[238:239], v[238:239], 0, v[186:187]
	global_load_dwordx4 v[242:245], v[238:239], off offset:256
	v_mov_b32_e32 v113, v0
	v_mov_b32_e32 v67, v1
	v_pk_mul_f32 v[112:113], v[106:107], v[112:113]
	v_pk_mul_f32 v[0:1], v[90:91], v[66:67]
	v_pk_fma_f32 v[66:67], v[86:87], v[98:99], v[94:95]
	v_mov_b32_e32 v98, v113
	v_mov_b32_e32 v99, v1
	v_pk_add_f32 v[66:67], v[98:99], v[66:67]
	v_mov_b32_e32 v113, v0
	v_pk_add_f32 v[0:1], v[112:113], v[66:67]
	v_lshlrev_b32_e32 v118, 16, v68
	v_fma_f32 v66, |v0|, s84, 1.0
	v_rcp_f32_e32 v67, v66
	v_pk_mul_f32 v[112:113], v[0:1], v[0:1]
	v_and_b32_e32 v66, 0xffff0000, v68
	v_lshlrev_b32_e32 v68, 16, v69
	v_and_b32_e32 v98, 0xffff0000, v69
	v_fmamk_f32 v69, v67, 0x3f07dc22, v241
	v_mul_f32_e32 v99, 0xbf38aa3b, v112
	v_fmaak_f32 v69, v67, v69, 0x3f35f0e3
	v_exp_f32_e32 v99, v99
	v_fmaak_f32 v69, v67, v69, 0xbe11a98e
	v_fmaak_f32 v69, v67, v69, 0x3e027906
	v_mul_f32_e32 v67, v67, v69
	v_mul_f32_e32 v67, v99, v67
	v_fma_f32 v99, |v1|, s84, 1.0
	v_rcp_f32_e32 v99, v99
	v_mul_f32_e32 v69, v0, v67
	v_fma_f32 v67, -v0, v67, v0
	v_cmp_gt_f32_e32 vcc, 0, v0
	v_mov_b32_e32 v115, v2
	v_mov_b32_e32 v117, v3
	v_cndmask_b32_e32 v0, v67, v69, vcc
	v_mul_f32_e32 v120, v62, v0
	v_mul_f32_e32 v62, 0xbf38aa3b, v113
	v_pk_mul_f32 v[112:113], v[102:103], v[114:115]
	v_pk_mul_f32 v[2:3], v[92:93], v[116:117]
	v_fmamk_f32 v0, v99, 0x3f07dc22, v241
	v_pk_fma_f32 v[100:101], v[88:89], v[100:101], v[96:97]
	v_mov_b32_e32 v114, v113
	v_mov_b32_e32 v115, v3
	v_fmaak_f32 v0, v99, v0, 0x3f35f0e3
	v_exp_f32_e32 v62, v62
	v_pk_add_f32 v[100:101], v[114:115], v[100:101]
	v_mov_b32_e32 v113, v2
	v_fmaak_f32 v0, v99, v0, 0xbe11a98e
	v_pk_add_f32 v[2:3], v[112:113], v[100:101]
	v_fmaak_f32 v0, v99, v0, 0x3e027906
	v_fma_f32 v67, |v2|, s84, 1.0
	v_mul_f32_e32 v0, v99, v0
	v_rcp_f32_e32 v67, v67
	v_mul_f32_e32 v0, v62, v0
	v_mul_f32_e32 v62, v1, v0
	v_fma_f32 v0, -v1, v0, v1
	v_cmp_gt_f32_e32 vcc, 0, v1
	v_mov_b32_e32 v119, v4
	v_mov_b32_e32 v99, v7
	v_cndmask_b32_e32 v0, v0, v62, vcc
	v_mul_f32_e32 v100, v63, v0
	v_fmamk_f32 v0, v67, 0x3f07dc22, v241
	v_fmaak_f32 v62, v67, v0, 0x3f35f0e3
	v_pk_mul_f32 v[0:1], v[2:3], v[2:3]
	v_fmaak_f32 v62, v67, v62, 0xbe11a98e
	v_mul_f32_e32 v0, 0xbf38aa3b, v0
	v_exp_f32_e32 v0, v0
	v_fmaak_f32 v62, v67, v62, 0x3e027906
	v_fma_f32 v63, |v3|, s84, 1.0
	v_mul_f32_e32 v62, v67, v62
	v_rcp_f32_e32 v63, v63
	v_mul_f32_e32 v0, v0, v62
	v_mul_f32_e32 v62, v2, v0
	v_fma_f32 v0, -v2, v0, v2
	v_cmp_gt_f32_e32 vcc, 0, v2
	v_mul_f32_e32 v1, 0xbf38aa3b, v1
	v_exp_f32_e32 v1, v1
	v_cndmask_b32_e32 v0, v0, v62, vcc
	v_mul_f32_e32 v64, v64, v0
	v_fmamk_f32 v0, v63, 0x3f07dc22, v241
	v_fmaak_f32 v0, v63, v0, 0x3f35f0e3
	v_fmaak_f32 v0, v63, v0, 0xbe11a98e
	v_fmaak_f32 v0, v63, v0, 0x3e027906
	v_mul_f32_e32 v0, v63, v0
	v_mul_f32_e32 v0, v1, v0
	v_mov_b32_e32 v67, v5
	v_mul_f32_e32 v2, v3, v0
	v_fma_f32 v69, -v3, v0, v3
	v_pk_mul_f32 v[0:1], v[70:71], v[118:119]
	v_pk_mul_f32 v[4:5], v[78:79], v[66:67]
	v_pk_fma_f32 v[62:63], v[74:75], v[104:105], v[82:83]
	v_mov_b32_e32 v66, v1
	v_mov_b32_e32 v67, v5
	v_pk_add_f32 v[62:63], v[66:67], v[62:63]
	v_mov_b32_e32 v1, v4
	v_pk_add_f32 v[0:1], v[0:1], v[62:63]
	v_cmp_gt_f32_e32 vcc, 0, v3
	v_fma_f32 v4, |v0|, s84, 1.0
	v_rcp_f32_e32 v4, v4
	v_cndmask_b32_e32 v2, v69, v2, vcc
	v_mul_f32_e32 v65, v65, v2
	v_cmp_gt_f32_e32 vcc, 0, v0
	v_fmamk_f32 v2, v4, 0x3f07dc22, v241
	v_fmaak_f32 v5, v4, v2, 0x3f35f0e3
	v_pk_mul_f32 v[2:3], v[0:1], v[0:1]
	v_fmaak_f32 v5, v4, v5, 0xbe11a98e
	v_mul_f32_e32 v2, 0xbf38aa3b, v2
	v_exp_f32_e32 v2, v2
	v_fmaak_f32 v5, v4, v5, 0x3e027906
	v_mul_f32_e32 v4, v4, v5
	v_fma_f32 v5, |v1|, s84, 1.0
	v_rcp_f32_e32 v5, v5
	v_mul_f32_e32 v2, v2, v4
	v_mul_f32_e32 v4, v0, v2
	v_fma_f32 v2, -v0, v2, v0
	v_cndmask_b32_e32 v0, v2, v4, vcc
	v_mul_f32_e32 v58, v58, v0
	v_fmamk_f32 v0, v5, 0x3f07dc22, v241
	v_mul_f32_e32 v2, 0xbf38aa3b, v3
	v_fmaak_f32 v0, v5, v0, 0x3f35f0e3
	v_exp_f32_e32 v2, v2
	v_fmaak_f32 v0, v5, v0, 0xbe11a98e
	v_fmaak_f32 v0, v5, v0, 0x3e027906
	v_mul_f32_e32 v0, v5, v0
	v_mov_b32_e32 v69, v6
	v_mul_f32_e32 v0, v2, v0
	v_pk_mul_f32 v[2:3], v[72:73], v[68:69]
	v_pk_mul_f32 v[4:5], v[80:81], v[98:99]
	v_pk_fma_f32 v[6:7], v[76:77], v[108:109], v[84:85]
	v_mov_b32_e32 v62, v3
	v_mov_b32_e32 v63, v5
	v_pk_add_f32 v[6:7], v[62:63], v[6:7]
	v_mov_b32_e32 v3, v4
	v_pk_add_f32 v[2:3], v[2:3], v[6:7]
	v_mul_f32_e32 v66, v1, v0
	v_fma_f32 v4, |v2|, s84, 1.0
	v_rcp_f32_e32 v4, v4
	v_fma_f32 v0, -v1, v0, v1
	v_cmp_gt_f32_e32 vcc, 0, v1
	s_nop 1
	v_cndmask_b32_e32 v0, v0, v66, vcc
	v_mul_f32_e32 v5, v59, v0
	v_fmamk_f32 v0, v4, 0x3f07dc22, v241
	v_fmaak_f32 v6, v4, v0, 0x3f35f0e3
	v_pk_mul_f32 v[0:1], v[2:3], v[2:3]
	v_fmaak_f32 v6, v4, v6, 0xbe11a98e
	v_mul_f32_e32 v0, 0xbf38aa3b, v0
	v_exp_f32_e32 v0, v0
	v_fmaak_f32 v6, v4, v6, 0x3e027906
	v_mul_f32_e32 v4, v4, v6
	v_fma_f32 v6, |v3|, s84, 1.0
	v_rcp_f32_e32 v6, v6
	v_mul_f32_e32 v0, v0, v4
	v_mul_f32_e32 v4, v2, v0
	v_fma_f32 v0, -v2, v0, v2
	v_cmp_gt_f32_e32 vcc, 0, v2
	v_mul_f32_e32 v1, 0xbf38aa3b, v1
	v_exp_f32_e32 v1, v1
	v_cndmask_b32_e32 v0, v0, v4, vcc
	v_mul_f32_e32 v4, v60, v0
	v_fmamk_f32 v0, v6, 0x3f07dc22, v241
	v_fmaak_f32 v0, v6, v0, 0x3f35f0e3
	v_fmaak_f32 v0, v6, v0, 0xbe11a98e
	v_fmaak_f32 v0, v6, v0, 0x3e027906
	v_mul_f32_e32 v0, v6, v0
	v_mul_f32_e32 v0, v1, v0
	v_mul_f32_e32 v1, v3, v0
	v_fma_f32 v0, -v3, v0, v3
	v_cmp_gt_f32_e32 vcc, 0, v3
	v_cvt_pk_bf16_f32 v2, v58, v5
	s_nop 1
	v_cndmask_b32_e32 v0, v0, v1, vcc
	v_mul_f32_e32 v3, v61, v0
	v_cvt_pk_bf16_f32 v0, v120, v100
	v_cvt_pk_bf16_f32 v1, v64, v65
	v_cvt_pk_bf16_f32 v3, v4, v3
	global_store_dwordx4 v[152:153], v[0:3], off offset:256
	s_waitcnt vmcnt(1)
;     static __device__ __forceinline__ void unpack8(const u32x4 q, float (&x)[8]) { x[0] = bflo(q.x); x[1] = bfhi(q.x); x[2] = bflo(q.y); x[3] = bfhi(q.y); x[4] = bflo(q.z); x[5] = bfhi(q.z); x[6] = bflo(q.w); x[7] = bfhi(q.w); }
;     __device__ __forceinline__ void operator()(EPI_ARGS) const {
;     ...
;                         q2[t] = *(const u32x4*)(up + (size_t)row * DFF + col); q1[t] = *(const u32x4*)(up + (size_t)r1 * DFF + col); q0[t] = *(const u32x4*)(up + (size_t)r2 * DFF + col); }
;                     __builtin_amdgcn_sched_barrier(0);
; #pragma unroll
;                     for (int t = 0; t < 1; ++t) { const int m = mp + t, row = row0 + ai * 128 + m * 16;
;                         const int i = row < TP ? row : ((row - TP) & 15); const int sidx = row < TP ? 0 : ((row - TP) >> 4);
;                         float x0[8], x1[8], x2[8]; unpack8(q0[t], x0); unpack8(q1[t], x1); unpack8(q2[t], x2);
;                         if (i < 2) {
;                             const bool smp = row >= TP; const float* p0 = cs + ((size_t)sidx * 2 + i) * DFF + col; const float* p1 = cs + ((size_t)sidx * 2 + 1) * DFF + col;
; #pragma unroll
;                             for (int e = 0; e < 8; ++e) { x0[e] = smp ? p0[e] : 0.f; if (i == 0) x1[e] = smp ? p1[e] : 0.f; } }
	v_mov_b64_e32 v[58:59], v[196:197]
	v_mov_b64_e32 v[60:61], v[198:199]
	v_mov_b64_e32 v[4:5], v[200:201]
	v_mov_b64_e32 v[6:7], v[202:203]
	v_mov_b64_e32 v[0:1], v[242:243]
	v_mov_b64_e32 v[2:3], v[244:245]
	v_lshlrev_b32_e32 v62, 16, v0
	v_and_b32_e32 v63, 0xffff0000, v0
	v_lshlrev_b32_e32 v64, 16, v1
	v_and_b32_e32 v65, 0xffff0000, v1
	v_lshlrev_b32_e32 v66, 16, v2
	v_and_b32_e32 v67, 0xffff0000, v2
	v_lshlrev_b32_e32 v68, 16, v3
	v_and_b32_e32 v69, 0xffff0000, v3
	v_lshlrev_b32_e32 v0, 16, v4
	v_and_b32_e32 v1, 0xffff0000, v4
	v_lshlrev_b32_e32 v2, 16, v5
	v_and_b32_e32 v3, 0xffff0000, v5
	v_lshlrev_b32_e32 v4, 16, v6
	v_and_b32_e32 v5, 0xffff0000, v6
	v_lshlrev_b32_e32 v6, 16, v7
	v_and_b32_e32 v7, 0xffff0000, v7
	s_and_saveexec_b64 s[0:1], s[64:65]
	s_mov_b32 s97, 0x7f807f81
	s_movk_i32 s90, 0xfeff
	s_movk_i32 s42, 0x410
	s_cbranch_execz .LBB0_1675
	s_add_i32 s14, s5, 0xffffe020
	s_ashr_i32 s14, s14, 4
	v_mov_b32_e32 v62, s14
	v_cndmask_b32_e64 v64, v62, 0, s[58:59]
	v_ashrrev_i32_e32 v65, 31, v64
	v_lshl_add_u64 v[62:63], v[64:65], 1, v[150:151]
	v_mov_b64_e32 v[66:67], s[68:69]
	v_mad_u64_u32 v[66:67], s[14:15], v62, s13, v[66:67]
	v_mad_i32_i24 v67, v63, s13, v67
	v_lshl_add_u64 v[100:101], v[184:185], 2, v[66:67]
	v_mov_b32_e32 v62, 0
	s_and_saveexec_b64 s[14:15], s[44:45]
	s_cbranch_execz .LBB0_1628
	global_load_dword v62, v[100:101], off offset:512

; __device__ __forceinline__ unsigned pk2(float lo, float hi) { unsigned r; asm("v_cvt_pk_bf16_f32 %0, %1, %2" : "=v"(r) : "v"(lo), "v"(hi)); return r; }
;     static __device__ __forceinline__ void unpack8(const u32x4 q, float (&x)[8]) { x[0] = bflo(q.x); x[1] = bfhi(q.x); x[2] = bflo(q.y); x[3] = bfhi(q.y); x[4] = bflo(q.z); x[5] = bfhi(q.z); x[6] = bflo(q.w); x[7] = bfhi(q.w); }
;     __device__ __forceinline__ void operator()(EPI_ARGS) const {
;     ...
;                     for (int t = 0; t < 1; ++t) { const int row = row0 + ai * 128 + (mp + t) * 16; const int r1 = row > 0 ? row - 1 : 0, r2 = row > 1 ? row - 2 : 0;
;                         q2[t] = *(const u32x4*)(up + (size_t)row * DFF + col); q1[t] = *(const u32x4*)(up + (size_t)r1 * DFF + col); q0[t] = *(const u32x4*)(up + (size_t)r2 * DFF + col); }
;                     __builtin_amdgcn_sched_barrier(0);
; #pragma unroll
;                     for (int t = 0; t < 1; ++t) { const int m = mp + t, row = row0 + ai * 128 + m * 16;
;                         const int i = row < TP ? row : ((row - TP) & 15); const int sidx = row < TP ? 0 : ((row - TP) >> 4);
;                         float x0[8], x1[8], x2[8]; unpack8(q0[t], x0); unpack8(q1[t], x1); unpack8(q2[t], x2);
;                         if (i < 2) {
;                             const bool smp = row >= TP; const float* p0 = cs + ((size_t)sidx * 2 + i) * DFF + col; const float* p1 = cs + ((size_t)sidx * 2 + 1) * DFF + col;
; #pragma unroll
;                             for (int e = 0; e < 8; ++e) { x0[e] = smp ? p0[e] : 0.f; if (i == 0) x1[e] = smp ? p1[e] : 0.f; } }
;                         float r[8];
; #pragma unroll
;                         for (int e = 0; e < 8; ++e) { const float cv = bb[e] + x0[e] * w0[e] + x1[e] * w1[e] + x2[e] * w2[e]; r[e] = gelu_f(cv) * acc[ai][bj][m][e >> 2][e & 3]; }
;                         u32x4 w; w.x = pk2(r[0], r[1]); w.y = pk2(r[2], r[3]); w.z = pk2(r[4], r[5]); w.w = pk2(r[6], r[7]);
;                         *(u32x4*)(act + (size_t)row * DFF + col) = w; } } } }
.LBB0_1673:
	s_or_b64 exec, exec, s[18:19]
.LBB0_1674:
	s_or_b64 exec, exec, s[14:15]
	s_waitcnt vmcnt(0)
.LBB0_1675:
	s_or_b64 exec, exec, s[0:1]
	v_lshlrev_b32_e32 v98, 16, v58
	v_and_b32_e32 v58, 0xffff0000, v58
	v_lshlrev_b32_e32 v100, 16, v59
	v_and_b32_e32 v104, 0xffff0000, v59
	s_waitcnt vmcnt(1)
	v_add_u32_e32 v240, 48, v232
	v_mov_b64_e32 v[238:239], s[30:31]
	v_mad_i64_i32 v[238:239], s[0:1], v240, s76, v[238:239]
	v_lshl_add_u64 v[238:239], v[238:239], 0, v[186:187]
	global_load_dwordx4 v[196:199], v[238:239], off offset:256
	v_add_u32_e32 v240, -1, v240
	v_mov_b64_e32 v[246:247], s[30:31]
	v_mad_i64_i32 v[246:247], s[0:1], v240, s76, v[246:247]
	v_lshl_add_u64 v[246:247], v[246:247], 0, v[186:187]
	global_load_dwordx4 v[200:203], v[246:247], off offset:256
	v_add_u32_e32 v240, -1, v240
	v_mov_b64_e32 v[238:239], s[30:31]
	v_mad_i64_i32 v[238:239], s[0:1], v240, s76, v[238:239]
	v_lshl_add_u64 v[238:239], v[238:239], 0, v[186:187]
	global_load_dwordx4 v[242:245], v[238:239], off offset:256
	v_mov_b32_e32 v99, v0
	v_mov_b32_e32 v59, v1
	v_pk_mul_f32 v[98:99], v[106:107], v[98:99]
	v_pk_mul_f32 v[0:1], v[90:91], v[58:59]
	v_pk_fma_f32 v[58:59], v[86:87], v[62:63], v[94:95]
	v_mov_b32_e32 v62, v99
	v_mov_b32_e32 v63, v1
	v_pk_add_f32 v[58:59], v[62:63], v[58:59]
	v_mov_b32_e32 v99, v0
	v_pk_add_f32 v[0:1], v[98:99], v[58:59]
	v_lshlrev_b32_e32 v108, 16, v60
	v_fma_f32 v58, |v0|, s84, 1.0
	v_rcp_f32_e32 v59, v58
	v_pk_mul_f32 v[98:99], v[0:1], v[0:1]
	v_and_b32_e32 v58, 0xffff0000, v60
	v_lshlrev_b32_e32 v60, 16, v61
	v_and_b32_e32 v62, 0xffff0000, v61
	v_fmamk_f32 v61, v59, 0x3f07dc22, v241
	v_mul_f32_e32 v63, 0xbf38aa3b, v98
	v_fmaak_f32 v61, v59, v61, 0x3f35f0e3
	v_exp_f32_e32 v63, v63
	v_fmaak_f32 v61, v59, v61, 0xbe11a98e
	v_fmaak_f32 v61, v59, v61, 0x3e027906
	v_mul_f32_e32 v59, v59, v61
	v_mul_f32_e32 v59, v63, v59
	v_fma_f32 v63, |v1|, s84, 1.0
	v_rcp_f32_e32 v63, v63
	v_mul_f32_e32 v61, v0, v59
	v_fma_f32 v59, -v0, v59, v0
	v_cmp_gt_f32_e32 vcc, 0, v0
	v_mov_b32_e32 v101, v2
	v_mov_b32_e32 v105, v3
	v_cndmask_b32_e32 v0, v59, v61, vcc
	v_mul_f32_e32 v112, v54, v0
	v_mul_f32_e32 v54, 0xbf38aa3b, v99
	v_pk_mul_f32 v[98:99], v[102:103], v[100:101]
	v_pk_mul_f32 v[2:3], v[92:93], v[104:105]
	v_fmamk_f32 v0, v63, 0x3f07dc22, v241
	v_pk_fma_f32 v[64:65], v[88:89], v[64:65], v[96:97]
	v_mov_b32_e32 v100, v99
	v_mov_b32_e32 v101, v3
	v_fmaak_f32 v0, v63, v0, 0x3f35f0e3
	v_exp_f32_e32 v54, v54
	v_pk_add_f32 v[64:65], v[100:101], v[64:65]
	v_mov_b32_e32 v99, v2
	v_fmaak_f32 v0, v63, v0, 0xbe11a98e
	v_pk_add_f32 v[2:3], v[98:99], v[64:65]
	v_fmaak_f32 v0, v63, v0, 0x3e027906
	v_fma_f32 v59, |v2|, s84, 1.0
	v_mul_f32_e32 v0, v63, v0
	v_rcp_f32_e32 v59, v59
	v_mul_f32_e32 v0, v54, v0
	v_mul_f32_e32 v54, v1, v0
	v_fma_f32 v0, -v1, v0, v1
	v_cmp_gt_f32_e32 vcc, 0, v1
	v_mov_b32_e32 v109, v4
	v_mov_b32_e32 v63, v7
	v_cndmask_b32_e32 v0, v0, v54, vcc
	v_mul_f32_e32 v64, v55, v0
	v_fmamk_f32 v0, v59, 0x3f07dc22, v241
	v_fmaak_f32 v54, v59, v0, 0x3f35f0e3
	v_pk_mul_f32 v[0:1], v[2:3], v[2:3]
	v_fmaak_f32 v54, v59, v54, 0xbe11a98e
	v_mul_f32_e32 v0, 0xbf38aa3b, v0
	v_exp_f32_e32 v0, v0
	v_fmaak_f32 v54, v59, v54, 0x3e027906
	v_fma_f32 v55, |v3|, s84, 1.0
	v_mul_f32_e32 v54, v59, v54
	v_rcp_f32_e32 v55, v55
	v_mul_f32_e32 v0, v0, v54
	v_mul_f32_e32 v54, v2, v0
	v_fma_f32 v0, -v2, v0, v2
	v_cmp_gt_f32_e32 vcc, 0, v2
	v_mul_f32_e32 v1, 0xbf38aa3b, v1
	v_exp_f32_e32 v1, v1
	v_cndmask_b32_e32 v0, v0, v54, vcc
	v_mul_f32_e32 v56, v56, v0
	v_fmamk_f32 v0, v55, 0x3f07dc22, v241
	v_fmaak_f32 v0, v55, v0, 0x3f35f0e3
	v_fmaak_f32 v0, v55, v0, 0xbe11a98e
	v_fmaak_f32 v0, v55, v0, 0x3e027906
	v_mul_f32_e32 v0, v55, v0
	v_mul_f32_e32 v0, v1, v0
	v_mov_b32_e32 v59, v5
	v_mul_f32_e32 v2, v3, v0
	v_fma_f32 v61, -v3, v0, v3
	v_pk_mul_f32 v[0:1], v[70:71], v[108:109]
	v_pk_mul_f32 v[4:5], v[78:79], v[58:59]
	v_pk_fma_f32 v[54:55], v[74:75], v[66:67], v[82:83]
	v_mov_b32_e32 v58, v1
	v_mov_b32_e32 v59, v5
	v_pk_add_f32 v[54:55], v[58:59], v[54:55]
	v_mov_b32_e32 v1, v4
	v_pk_add_f32 v[0:1], v[0:1], v[54:55]
	v_cmp_gt_f32_e32 vcc, 0, v3
	v_fma_f32 v4, |v0|, s84, 1.0
	v_rcp_f32_e32 v4, v4
	v_cndmask_b32_e32 v2, v61, v2, vcc
	v_mul_f32_e32 v57, v57, v2
	v_cmp_gt_f32_e32 vcc, 0, v0
	v_fmamk_f32 v2, v4, 0x3f07dc22, v241
	v_fmaak_f32 v5, v4, v2, 0x3f35f0e3
	v_pk_mul_f32 v[2:3], v[0:1], v[0:1]
	v_fmaak_f32 v5, v4, v5, 0xbe11a98e
	v_mul_f32_e32 v2, 0xbf38aa3b, v2
	v_exp_f32_e32 v2, v2
	v_fmaak_f32 v5, v4, v5, 0x3e027906
	v_mul_f32_e32 v4, v4, v5
	v_fma_f32 v5, |v1|, s84, 1.0
	v_rcp_f32_e32 v5, v5
	v_mul_f32_e32 v2, v2, v4
	v_mul_f32_e32 v4, v0, v2
	v_fma_f32 v2, -v0, v2, v0
	v_cndmask_b32_e32 v0, v2, v4, vcc
	v_mul_f32_e32 v50, v50, v0
	v_fmamk_f32 v0, v5, 0x3f07dc22, v241
	v_mul_f32_e32 v2, 0xbf38aa3b, v3
	v_fmaak_f32 v0, v5, v0, 0x3f35f0e3
	v_exp_f32_e32 v2, v2
	v_fmaak_f32 v0, v5, v0, 0xbe11a98e
	v_fmaak_f32 v0, v5, v0, 0x3e027906
	v_mul_f32_e32 v0, v5, v0
	v_mov_b32_e32 v61, v6
	v_mul_f32_e32 v0, v2, v0
	v_pk_mul_f32 v[2:3], v[72:73], v[60:61]
	v_pk_mul_f32 v[4:5], v[80:81], v[62:63]
	v_pk_fma_f32 v[6:7], v[76:77], v[68:69], v[84:85]
	v_mov_b32_e32 v54, v3
	v_mov_b32_e32 v55, v5
	v_pk_add_f32 v[6:7], v[54:55], v[6:7]
	v_mov_b32_e32 v3, v4
	v_pk_add_f32 v[2:3], v[2:3], v[6:7]
	v_mul_f32_e32 v58, v1, v0
	v_fma_f32 v4, |v2|, s84, 1.0
	v_rcp_f32_e32 v4, v4
	v_fma_f32 v0, -v1, v0, v1
	v_cmp_gt_f32_e32 vcc, 0, v1
	s_nop 1
	v_cndmask_b32_e32 v0, v0, v58, vcc
	v_mul_f32_e32 v5, v51, v0
	v_fmamk_f32 v0, v4, 0x3f07dc22, v241
	v_fmaak_f32 v6, v4, v0, 0x3f35f0e3
	v_pk_mul_f32 v[0:1], v[2:3], v[2:3]
	v_fmaak_f32 v6, v4, v6, 0xbe11a98e
	v_mul_f32_e32 v0, 0xbf38aa3b, v0
	v_exp_f32_e32 v0, v0
	v_fmaak_f32 v6, v4, v6, 0x3e027906
	v_mul_f32_e32 v4, v4, v6
	v_fma_f32 v6, |v3|, s84, 1.0
	v_rcp_f32_e32 v6, v6
	v_mul_f32_e32 v0, v0, v4
	v_mul_f32_e32 v4, v2, v0
	v_fma_f32 v0, -v2, v0, v2
	v_cmp_gt_f32_e32 vcc, 0, v2
	v_mul_f32_e32 v1, 0xbf38aa3b, v1
	v_exp_f32_e32 v1, v1
	v_cndmask_b32_e32 v0, v0, v4, vcc
	v_mul_f32_e32 v4, v52, v0
	v_fmamk_f32 v0, v6, 0x3f07dc22, v241
	v_fmaak_f32 v0, v6, v0, 0x3f35f0e3
	v_fmaak_f32 v0, v6, v0, 0xbe11a98e
	v_fmaak_f32 v0, v6, v0, 0x3e027906
	v_mul_f32_e32 v0, v6, v0
	v_mul_f32_e32 v0, v1, v0
	v_mul_f32_e32 v1, v3, v0
	v_fma_f32 v0, -v3, v0, v3
	v_cmp_gt_f32_e32 vcc, 0, v3
	v_cvt_pk_bf16_f32 v2, v50, v5
	s_nop 1
	v_cndmask_b32_e32 v0, v0, v1, vcc
	v_mul_f32_e32 v3, v53, v0
	v_cvt_pk_bf16_f32 v0, v112, v64
	v_cvt_pk_bf16_f32 v1, v56, v57
	v_cvt_pk_bf16_f32 v3, v4, v3
	global_store_dwordx4 v[144:145], v[0:3], off offset:256
	s_waitcnt vmcnt(1)
;     static __device__ __forceinline__ void unpack8(const u32x4 q, float (&x)[8]) { x[0] = bflo(q.x); x[1] = bfhi(q.x); x[2] = bflo(q.y); x[3] = bfhi(q.y); x[4] = bflo(q.z); x[5] = bfhi(q.z); x[6] = bflo(q.w); x[7] = bfhi(q.w); }
;     __device__ __forceinline__ void operator()(EPI_ARGS) const {
;     ...
;                         q2[t] = *(const u32x4*)(up + (size_t)row * DFF + col); q1[t] = *(const u32x4*)(up + (size_t)r1 * DFF + col); q0[t] = *(const u32x4*)(up + (size_t)r2 * DFF + col); }
;                     __builtin_amdgcn_sched_barrier(0);
; #pragma unroll
;                     for (int t = 0; t < 1; ++t) { const int m = mp + t, row = row0 + ai * 128 + m * 16;
;                         const int i = row < TP ? row : ((row - TP) & 15); const int sidx = row < TP ? 0 : ((row - TP) >> 4);
;                         float x0[8], x1[8], x2[8]; unpack8(q0[t], x0); unpack8(q1[t], x1); unpack8(q2[t], x2);
;                         if (i < 2) {
;                             const bool smp = row >= TP; const float* p0 = cs + ((size_t)sidx * 2 + i) * DFF + col; const float* p1 = cs + ((size_t)sidx * 2 + 1) * DFF + col;
; #pragma unroll
;                             for (int e = 0; e < 8; ++e) { x0[e] = smp ? p0[e] : 0.f; if (i == 0) x1[e] = smp ? p1[e] : 0.f; } }
	v_mov_b64_e32 v[50:51], v[196:197]
	v_mov_b64_e32 v[52:53], v[198:199]
	v_mov_b64_e32 v[4:5], v[200:201]
	v_mov_b64_e32 v[6:7], v[202:203]
	v_mov_b64_e32 v[0:1], v[242:243]
	v_mov_b64_e32 v[2:3], v[244:245]
	v_lshlrev_b32_e32 v54, 16, v0
	v_and_b32_e32 v55, 0xffff0000, v0
	v_lshlrev_b32_e32 v56, 16, v1
	v_and_b32_e32 v57, 0xffff0000, v1
	v_lshlrev_b32_e32 v58, 16, v2
	v_and_b32_e32 v59, 0xffff0000, v2
	v_lshlrev_b32_e32 v60, 16, v3
	v_and_b32_e32 v61, 0xffff0000, v3
	v_lshlrev_b32_e32 v0, 16, v4
	v_and_b32_e32 v1, 0xffff0000, v4
	v_lshlrev_b32_e32 v2, 16, v5
	v_and_b32_e32 v3, 0xffff0000, v5
	v_lshlrev_b32_e32 v4, 16, v6
	v_and_b32_e32 v5, 0xffff0000, v6
	v_lshlrev_b32_e32 v6, 16, v7
	v_and_b32_e32 v7, 0xffff0000, v7
	s_and_saveexec_b64 s[0:1], s[66:67]
	s_cbranch_execz .LBB0_1725
	s_add_i32 s14, s5, 0xffffe030
	s_ashr_i32 s14, s14, 4
	v_mov_b32_e32 v54, s14
	v_cndmask_b32_e64 v56, v54, 0, s[62:63]
	v_ashrrev_i32_e32 v57, 31, v56
	v_lshl_add_u64 v[54:55], v[56:57], 1, v[142:143]
	v_mov_b64_e32 v[58:59], s[68:69]
	v_mad_u64_u32 v[58:59], s[14:15], v54, s13, v[58:59]
	v_mad_i32_i24 v59, v55, s13, v59
	v_lshl_add_u64 v[64:65], v[184:185], 2, v[58:59]
	v_mov_b32_e32 v54, 0
	s_and_saveexec_b64 s[14:15], s[48:49]
	s_cbranch_execz .LBB0_1678
	global_load_dword v54, v[64:65], off offset:512

; __device__ __forceinline__ unsigned pk2(float lo, float hi) { unsigned r; asm("v_cvt_pk_bf16_f32 %0, %1, %2" : "=v"(r) : "v"(lo), "v"(hi)); return r; }
;     static __device__ __forceinline__ void unpack8(const u32x4 q, float (&x)[8]) { x[0] = bflo(q.x); x[1] = bfhi(q.x); x[2] = bflo(q.y); x[3] = bfhi(q.y); x[4] = bflo(q.z); x[5] = bfhi(q.z); x[6] = bflo(q.w); x[7] = bfhi(q.w); }
;     __device__ __forceinline__ void operator()(EPI_ARGS) const {
;     ...
;                 if (u.pm == 32 && ai == 1) continue;
; #pragma unroll
;                 for (int mp = 0; mp < 4; ++mp) {
;                     u32x4 q2[1], q1[1], q0[1];
; #pragma unroll
;                     for (int t = 0; t < 1; ++t) { const int row = row0 + ai * 128 + (mp + t) * 16; const int r1 = row > 0 ? row - 1 : 0, r2 = row > 1 ? row - 2 : 0;
;                         q2[t] = *(const u32x4*)(up + (size_t)row * DFF + col); q1[t] = *(const u32x4*)(up + (size_t)r1 * DFF + col); q0[t] = *(const u32x4*)(up + (size_t)r2 * DFF + col); }
;                     __builtin_amdgcn_sched_barrier(0);
; #pragma unroll
;                     for (int t = 0; t < 1; ++t) { const int m = mp + t, row = row0 + ai * 128 + m * 16;
;                         const int i = row < TP ? row : ((row - TP) & 15); const int sidx = row < TP ? 0 : ((row - TP) >> 4);
;                         float x0[8], x1[8], x2[8]; unpack8(q0[t], x0); unpack8(q1[t], x1); unpack8(q2[t], x2);
;                         if (i < 2) {
;                             const bool smp = row >= TP; const float* p0 = cs + ((size_t)sidx * 2 + i) * DFF + col; const float* p1 = cs + ((size_t)sidx * 2 + 1) * DFF + col;
; #pragma unroll
;                             for (int e = 0; e < 8; ++e) { x0[e] = smp ? p0[e] : 0.f; if (i == 0) x1[e] = smp ? p1[e] : 0.f; } }
;                         float r[8];
; #pragma unroll
;                         for (int e = 0; e < 8; ++e) { const float cv = bb[e] + x0[e] * w0[e] + x1[e] * w1[e] + x2[e] * w2[e]; r[e] = gelu_f(cv) * acc[ai][bj][m][e >> 2][e & 3]; }
;                         u32x4 w; w.x = pk2(r[0], r[1]); w.y = pk2(r[2], r[3]); w.z = pk2(r[4], r[5]); w.w = pk2(r[6], r[7]);
;                         *(u32x4*)(act + (size_t)row * DFF + col) = w; } } } }
.LBB0_1723:
	s_or_b64 exec, exec, s[18:19]
.LBB0_1724:
	s_or_b64 exec, exec, s[14:15]
	s_waitcnt vmcnt(0)
.LBB0_1725:
	s_or_b64 exec, exec, s[0:1]
	v_lshlrev_b32_e32 v62, 16, v50
	v_and_b32_e32 v50, 0xffff0000, v50
	v_lshlrev_b32_e32 v64, 16, v51
	v_and_b32_e32 v66, 0xffff0000, v51
	s_waitcnt vmcnt(1)
	v_mov_b32_e32 v63, v0
	v_mov_b32_e32 v51, v1
	v_pk_mul_f32 v[62:63], v[106:107], v[62:63]
	v_pk_mul_f32 v[0:1], v[90:91], v[50:51]
	v_pk_fma_f32 v[50:51], v[86:87], v[54:55], v[94:95]
	v_mov_b32_e32 v54, v63
	v_mov_b32_e32 v55, v1
	v_pk_add_f32 v[50:51], v[54:55], v[50:51]
	v_mov_b32_e32 v63, v0
	v_pk_add_f32 v[0:1], v[62:63], v[50:51]
	v_lshlrev_b32_e32 v68, 16, v52
	v_fma_f32 v50, |v0|, s84, 1.0
	v_rcp_f32_e32 v51, v50
	v_pk_mul_f32 v[62:63], v[0:1], v[0:1]
	v_and_b32_e32 v50, 0xffff0000, v52
	v_lshlrev_b32_e32 v52, 16, v53
	v_and_b32_e32 v54, 0xffff0000, v53
	v_fmamk_f32 v53, v51, 0x3f07dc22, v241
	v_mul_f32_e32 v55, 0xbf38aa3b, v62
	v_fmaak_f32 v53, v51, v53, 0x3f35f0e3
	v_exp_f32_e32 v55, v55
	v_fmaak_f32 v53, v51, v53, 0xbe11a98e
	v_fmaak_f32 v53, v51, v53, 0x3e027906
	v_mul_f32_e32 v51, v51, v53
	v_mul_f32_e32 v51, v55, v51
	v_fma_f32 v55, |v1|, s84, 1.0
	v_rcp_f32_e32 v55, v55
	v_mul_f32_e32 v53, v0, v51
	v_fma_f32 v51, -v0, v51, v0
	v_cmp_gt_f32_e32 vcc, 0, v0
	v_mov_b32_e32 v65, v2
	v_mov_b32_e32 v67, v3
	v_cndmask_b32_e32 v0, v51, v53, vcc
	v_mul_f32_e32 v98, v46, v0
	v_mul_f32_e32 v46, 0xbf38aa3b, v63
	v_pk_mul_f32 v[62:63], v[102:103], v[64:65]
	v_pk_mul_f32 v[2:3], v[92:93], v[66:67]
	v_fmamk_f32 v0, v55, 0x3f07dc22, v241
	v_pk_fma_f32 v[56:57], v[88:89], v[56:57], v[96:97]
	v_mov_b32_e32 v64, v63
	v_mov_b32_e32 v65, v3
	v_fmaak_f32 v0, v55, v0, 0x3f35f0e3
	v_exp_f32_e32 v46, v46
	v_pk_add_f32 v[56:57], v[64:65], v[56:57]
	v_mov_b32_e32 v63, v2
	v_fmaak_f32 v0, v55, v0, 0xbe11a98e
	v_pk_add_f32 v[2:3], v[62:63], v[56:57]
	v_fmaak_f32 v0, v55, v0, 0x3e027906
	v_fma_f32 v51, |v2|, s84, 1.0
	v_mul_f32_e32 v0, v55, v0
	v_rcp_f32_e32 v51, v51
	v_mul_f32_e32 v0, v46, v0
	v_mul_f32_e32 v46, v1, v0
	v_fma_f32 v0, -v1, v0, v1
	v_cmp_gt_f32_e32 vcc, 0, v1
	v_mov_b32_e32 v69, v4
	v_mov_b32_e32 v55, v7
	v_cndmask_b32_e32 v0, v0, v46, vcc
	v_mul_f32_e32 v56, v47, v0
	v_fmamk_f32 v0, v51, 0x3f07dc22, v241
	v_fmaak_f32 v46, v51, v0, 0x3f35f0e3
	v_pk_mul_f32 v[0:1], v[2:3], v[2:3]
	v_fmaak_f32 v46, v51, v46, 0xbe11a98e
	v_mul_f32_e32 v0, 0xbf38aa3b, v0
	v_exp_f32_e32 v0, v0
	v_fmaak_f32 v46, v51, v46, 0x3e027906
	v_fma_f32 v47, |v3|, s84, 1.0
	v_mul_f32_e32 v46, v51, v46
	v_rcp_f32_e32 v47, v47
	v_mul_f32_e32 v0, v0, v46
	v_mul_f32_e32 v46, v2, v0
	v_fma_f32 v0, -v2, v0, v2
	v_cmp_gt_f32_e32 vcc, 0, v2
	v_mul_f32_e32 v1, 0xbf38aa3b, v1
	v_exp_f32_e32 v1, v1
	v_cndmask_b32_e32 v0, v0, v46, vcc
	v_mul_f32_e32 v48, v48, v0
	v_fmamk_f32 v0, v47, 0x3f07dc22, v241
	v_fmaak_f32 v0, v47, v0, 0x3f35f0e3
	v_fmaak_f32 v0, v47, v0, 0xbe11a98e
	v_fmaak_f32 v0, v47, v0, 0x3e027906
	v_mul_f32_e32 v0, v47, v0
	v_mul_f32_e32 v0, v1, v0
	v_mov_b32_e32 v51, v5
	v_mul_f32_e32 v2, v3, v0
	v_fma_f32 v53, -v3, v0, v3
	v_pk_mul_f32 v[0:1], v[70:71], v[68:69]
	v_pk_mul_f32 v[4:5], v[78:79], v[50:51]
	v_pk_fma_f32 v[46:47], v[74:75], v[58:59], v[82:83]
	v_mov_b32_e32 v50, v1
	v_mov_b32_e32 v51, v5
	v_pk_add_f32 v[46:47], v[50:51], v[46:47]
	v_mov_b32_e32 v1, v4
	v_pk_add_f32 v[0:1], v[0:1], v[46:47]
	v_cmp_gt_f32_e32 vcc, 0, v3
	v_fma_f32 v4, |v0|, s84, 1.0
	v_rcp_f32_e32 v4, v4
	v_cndmask_b32_e32 v2, v53, v2, vcc
	v_mul_f32_e32 v49, v49, v2
	v_cmp_gt_f32_e32 vcc, 0, v0
	v_fmamk_f32 v2, v4, 0x3f07dc22, v241
	v_fmaak_f32 v5, v4, v2, 0x3f35f0e3
	v_pk_mul_f32 v[2:3], v[0:1], v[0:1]
	v_fmaak_f32 v5, v4, v5, 0xbe11a98e
	v_mul_f32_e32 v2, 0xbf38aa3b, v2
	v_exp_f32_e32 v2, v2
	v_fmaak_f32 v5, v4, v5, 0x3e027906
	v_mul_f32_e32 v4, v4, v5
	v_fma_f32 v5, |v1|, s84, 1.0
	v_rcp_f32_e32 v5, v5
	v_mul_f32_e32 v2, v2, v4
	v_mul_f32_e32 v4, v0, v2
	v_fma_f32 v2, -v0, v2, v0
	v_cndmask_b32_e32 v0, v2, v4, vcc
	v_mul_f32_e32 v42, v42, v0
	v_fmamk_f32 v0, v5, 0x3f07dc22, v241
	v_mul_f32_e32 v2, 0xbf38aa3b, v3
	v_fmaak_f32 v0, v5, v0, 0x3f35f0e3
	v_exp_f32_e32 v2, v2
	v_fmaak_f32 v0, v5, v0, 0xbe11a98e
	v_fmaak_f32 v0, v5, v0, 0x3e027906
	v_mul_f32_e32 v0, v5, v0
	v_mov_b32_e32 v53, v6
	v_mul_f32_e32 v0, v2, v0
	v_pk_mul_f32 v[2:3], v[72:73], v[52:53]
	v_pk_mul_f32 v[4:5], v[80:81], v[54:55]
	v_pk_fma_f32 v[6:7], v[76:77], v[60:61], v[84:85]
	v_mov_b32_e32 v46, v3
	v_mov_b32_e32 v47, v5
	v_pk_add_f32 v[6:7], v[46:47], v[6:7]
	v_mov_b32_e32 v3, v4
	v_pk_add_f32 v[2:3], v[2:3], v[6:7]
	v_mul_f32_e32 v50, v1, v0
	v_fma_f32 v4, |v2|, s84, 1.0
	v_rcp_f32_e32 v4, v4
	v_fma_f32 v0, -v1, v0, v1
	v_cmp_gt_f32_e32 vcc, 0, v1
	v_readlane_b32 s48, v252, 16
	v_readlane_b32 s49, v252, 17
	v_cndmask_b32_e32 v0, v0, v50, vcc
	v_mul_f32_e32 v5, v43, v0
	v_fmamk_f32 v0, v4, 0x3f07dc22, v241
	v_fmaak_f32 v6, v4, v0, 0x3f35f0e3
	v_pk_mul_f32 v[0:1], v[2:3], v[2:3]
	v_fmaak_f32 v6, v4, v6, 0xbe11a98e
	v_mul_f32_e32 v0, 0xbf38aa3b, v0
	v_exp_f32_e32 v0, v0
	v_fmaak_f32 v6, v4, v6, 0x3e027906
	v_mul_f32_e32 v4, v4, v6
	v_fma_f32 v6, |v3|, s84, 1.0
	v_rcp_f32_e32 v6, v6
	v_mul_f32_e32 v0, v0, v4
	v_mul_f32_e32 v4, v2, v0
	v_fma_f32 v0, -v2, v0, v2
	v_cmp_gt_f32_e32 vcc, 0, v2
	v_mul_f32_e32 v1, 0xbf38aa3b, v1
	v_exp_f32_e32 v1, v1
	v_cndmask_b32_e32 v0, v0, v4, vcc
	v_mul_f32_e32 v4, v44, v0
	v_fmamk_f32 v0, v6, 0x3f07dc22, v241
	v_fmaak_f32 v0, v6, v0, 0x3f35f0e3
	v_fmaak_f32 v0, v6, v0, 0xbe11a98e
	v_fmaak_f32 v0, v6, v0, 0x3e027906
	v_mul_f32_e32 v0, v6, v0
	v_mul_f32_e32 v0, v1, v0
	v_mul_f32_e32 v1, v3, v0
	v_fma_f32 v0, -v3, v0, v3
	v_cmp_gt_f32_e32 vcc, 0, v3
	v_readlane_b32 s50, v252, 18
	v_readlane_b32 s51, v252, 19
	v_cndmask_b32_e32 v0, v0, v1, vcc
	v_mul_f32_e32 v3, v45, v0
	s_andn2_b64 vcc, exec, s[8:9]
	v_readlane_b32 s52, v252, 20
	v_readlane_b32 s53, v252, 21
	v_readlane_b32 s56, v252, 24
	v_readlane_b32 s57, v252, 25
	v_readlane_b32 s58, v252, 26
	v_readlane_b32 s59, v252, 27
	v_readlane_b32 s60, v252, 28
	v_readlane_b32 s61, v252, 29
	v_readlane_b32 s62, v252, 30
	v_readlane_b32 s63, v252, 31
	v_cvt_pk_bf16_f32 v0, v98, v56
	v_cvt_pk_bf16_f32 v1, v48, v49
	v_cvt_pk_bf16_f32 v2, v42, v5
	v_cvt_pk_bf16_f32 v3, v4, v3
	global_store_dwordx4 v[134:135], v[0:3], off offset:256
	v_readlane_b32 s54, v252, 22
	v_readlane_b32 s55, v252, 23
	s_cbranch_vccnz .LBB0_1927
;     static __device__ __forceinline__ void unpack8(const u32x4 q, float (&x)[8]) { x[0] = bflo(q.x); x[1] = bfhi(q.x); x[2] = bflo(q.y); x[3] = bfhi(q.y); x[4] = bflo(q.z); x[5] = bfhi(q.z); x[6] = bflo(q.w); x[7] = bfhi(q.w); }
;     __device__ __forceinline__ void operator()(EPI_ARGS) const {
;     ...
;                 if (u.pm == 32 && ai == 1) continue;
; #pragma unroll
;                 for (int mp = 0; mp < 4; ++mp) {
;                     u32x4 q2[1], q1[1], q0[1];
; #pragma unroll
;                     for (int t = 0; t < 1; ++t) { const int row = row0 + ai * 128 + (mp + t) * 16; const int r1 = row > 0 ? row - 1 : 0, r2 = row > 1 ? row - 2 : 0;
;                         q2[t] = *(const u32x4*)(up + (size_t)row * DFF + col); q1[t] = *(const u32x4*)(up + (size_t)r1 * DFF + col); q0[t] = *(const u32x4*)(up + (size_t)r2 * DFF + col); }
;                     __builtin_amdgcn_sched_barrier(0);
; #pragma unroll
;                     for (int t = 0; t < 1; ++t) { const int m = mp + t, row = row0 + ai * 128 + m * 16;
;                         const int i = row < TP ? row : ((row - TP) & 15); const int sidx = row < TP ? 0 : ((row - TP) >> 4);
;                         float x0[8], x1[8], x2[8]; unpack8(q0[t], x0); unpack8(q1[t], x1); unpack8(q2[t], x2);
;                         if (i < 2) {
;                             const bool smp = row >= TP; const float* p0 = cs + ((size_t)sidx * 2 + i) * DFF + col; const float* p1 = cs + ((size_t)sidx * 2 + 1) * DFF + col;
; #pragma unroll
;                             for (int e = 0; e < 8; ++e) { x0[e] = smp ? p0[e] : 0.f; if (i == 0) x1[e] = smp ? p1[e] : 0.f; } }
	v_add_u32_e32 v4, -1, v225
	v_add_u32_e32 v46, -2, v226
	v_mov_b64_e32 v[0:1], s[30:31]
	v_mad_i64_i32 v[2:3], s[0:1], v224, s76, v[0:1]
	v_mad_u64_u32 v[4:5], s[0:1], v4, s76, v[0:1]
	v_mad_u64_u32 v[0:1], s[0:1], v46, s76, v[0:1]
	v_lshl_add_u64 v[2:3], v[2:3], 0, v[186:187]
	v_lshl_add_u64 v[4:5], v[4:5], 0, v[186:187]
	v_lshl_add_u64 v[0:1], v[0:1], 0, v[186:187]
	global_load_dwordx4 v[42:45], v[2:3], off offset:256
	s_nop 0
	global_load_dwordx4 v[4:7], v[4:5], off offset:256
	s_nop 0
	global_load_dwordx4 v[0:3], v[0:1], off offset:256
	s_movk_i32 s0, 0x1f80
	v_cmp_gt_i32_e64 s[0:1], s0, v232
	s_waitcnt vmcnt(0)
	v_lshlrev_b32_e32 v46, 16, v0
	v_and_b32_e32 v47, 0xffff0000, v0
	v_cndmask_b32_e64 v58, v228, v224, s[0:1]
	v_lshlrev_b32_e32 v48, 16, v1
	v_and_b32_e32 v49, 0xffff0000, v1
	v_lshlrev_b32_e32 v50, 16, v2
	v_and_b32_e32 v51, 0xffff0000, v2
	v_lshlrev_b32_e32 v52, 16, v3
	v_and_b32_e32 v53, 0xffff0000, v3
	v_lshlrev_b32_e32 v0, 16, v4
	v_and_b32_e32 v1, 0xffff0000, v4
	v_lshlrev_b32_e32 v2, 16, v5
	v_and_b32_e32 v3, 0xffff0000, v5
	v_lshlrev_b32_e32 v4, 16, v6
	v_and_b32_e32 v5, 0xffff0000, v6
	v_lshlrev_b32_e32 v6, 16, v7
	v_and_b32_e32 v7, 0xffff0000, v7
	v_cmp_gt_i32_e32 vcc, 2, v58
	s_and_saveexec_b64 s[8:9], vcc
	s_cbranch_execz .LBB0_1776
	s_movk_i32 s14, 0x1f7f
	v_cmp_lt_i32_e32 vcc, s14, v232
	s_add_i32 s14, s5, 0xffffe080
	s_ashr_i32 s14, s14, 4
	v_mov_b32_e32 v46, s14
	v_cndmask_b32_e64 v48, v46, 0, s[0:1]
	v_ashrrev_i32_e32 v49, 31, v48
	v_ashrrev_i32_e32 v59, 31, v58
	v_lshl_add_u64 v[46:47], v[48:49], 1, v[58:59]
	v_mov_b64_e32 v[50:51], s[68:69]
	v_mad_u64_u32 v[50:51], s[0:1], v46, s13, v[50:51]
	v_mad_i32_i24 v51, v47, s13, v51
	v_lshl_add_u64 v[56:57], v[184:185], 2, v[50:51]
	v_mov_b32_e32 v46, 0
	s_and_saveexec_b64 s[0:1], vcc
	s_cbranch_execz .LBB0_1729
	global_load_dword v46, v[56:57], off offset:512

;     static __device__ __forceinline__ void unpack8(const u32x4 q, float (&x)[8]) { x[0] = bflo(q.x); x[1] = bfhi(q.x); x[2] = bflo(q.y); x[3] = bfhi(q.y); x[4] = bflo(q.z); x[5] = bfhi(q.z); x[6] = bflo(q.w); x[7] = bfhi(q.w); }
;     __device__ __forceinline__ void operator()(EPI_ARGS) const {
;     ...
;                     for (int t = 0; t < 1; ++t) { const int row = row0 + ai * 128 + (mp + t) * 16; const int r1 = row > 0 ? row - 1 : 0, r2 = row > 1 ? row - 2 : 0;
;                         q2[t] = *(const u32x4*)(up + (size_t)row * DFF + col); q1[t] = *(const u32x4*)(up + (size_t)r1 * DFF + col); q0[t] = *(const u32x4*)(up + (size_t)r2 * DFF + col); }
;                     __builtin_amdgcn_sched_barrier(0);
; #pragma unroll
;                     for (int t = 0; t < 1; ++t) { const int m = mp + t, row = row0 + ai * 128 + m * 16;
;                         const int i = row < TP ? row : ((row - TP) & 15); const int sidx = row < TP ? 0 : ((row - TP) >> 4);
;                         float x0[8], x1[8], x2[8]; unpack8(q0[t], x0); unpack8(q1[t], x1); unpack8(q2[t], x2);
;                         if (i < 2) {
;                             const bool smp = row >= TP; const float* p0 = cs + ((size_t)sidx * 2 + i) * DFF + col; const float* p1 = cs + ((size_t)sidx * 2 + 1) * DFF + col;
; #pragma unroll
;                             for (int e = 0; e < 8; ++e) { x0[e] = smp ? p0[e] : 0.f; if (i == 0) x1[e] = smp ? p1[e] : 0.f; } }
;                         float r[8];
; #pragma unroll
;                         for (int e = 0; e < 8; ++e) { const float cv = bb[e] + x0[e] * w0[e] + x1[e] * w1[e] + x2[e] * w2[e]; r[e] = gelu_f(cv) * acc[ai][bj][m][e >> 2][e & 3]; }
.LBB0_1776:
	s_or_b64 exec, exec, s[8:9]
	v_lshlrev_b32_e32 v56, 16, v42
	v_and_b32_e32 v42, 0xffff0000, v42
	v_lshlrev_b32_e32 v58, 16, v43
	v_and_b32_e32 v60, 0xffff0000, v43
	s_waitcnt vmcnt(0)
	v_add_u32_e32 v240, 144, v232
	v_mov_b64_e32 v[238:239], s[30:31]
	v_mad_i64_i32 v[238:239], s[0:1], v240, s76, v[238:239]
	v_lshl_add_u64 v[238:239], v[238:239], 0, v[186:187]
	global_load_dwordx4 v[196:199], v[238:239], off offset:256
	v_add_u32_e32 v240, -1, v240
	v_mov_b64_e32 v[246:247], s[30:31]
	v_mad_i64_i32 v[246:247], s[0:1], v240, s76, v[246:247]
	v_lshl_add_u64 v[246:247], v[246:247], 0, v[186:187]
	global_load_dwordx4 v[200:203], v[246:247], off offset:256
	v_add_u32_e32 v240, -1, v240
	v_mov_b64_e32 v[238:239], s[30:31]
	v_mad_i64_i32 v[238:239], s[0:1], v240, s76, v[238:239]
	v_lshl_add_u64 v[238:239], v[238:239], 0, v[186:187]
	global_load_dwordx4 v[242:245], v[238:239], off offset:256
	v_mov_b32_e32 v57, v0
	v_mov_b32_e32 v43, v1
	v_pk_mul_f32 v[56:57], v[106:107], v[56:57]
	v_pk_mul_f32 v[0:1], v[90:91], v[42:43]
	v_pk_fma_f32 v[42:43], v[86:87], v[46:47], v[94:95]
	v_mov_b32_e32 v46, v57
	v_mov_b32_e32 v47, v1
	v_pk_add_f32 v[42:43], v[46:47], v[42:43]
	v_mov_b32_e32 v57, v0
	v_pk_add_f32 v[0:1], v[56:57], v[42:43]
	v_lshlrev_b32_e32 v62, 16, v44
	v_fma_f32 v42, |v0|, s84, 1.0
	v_rcp_f32_e32 v43, v42
	v_pk_mul_f32 v[56:57], v[0:1], v[0:1]
	v_and_b32_e32 v42, 0xffff0000, v44
	v_lshlrev_b32_e32 v44, 16, v45
	v_and_b32_e32 v46, 0xffff0000, v45
	v_fmamk_f32 v45, v43, 0x3f07dc22, v241
	v_mul_f32_e32 v47, 0xbf38aa3b, v56
	v_fmaak_f32 v45, v43, v45, 0x3f35f0e3
	v_exp_f32_e32 v47, v47
	v_fmaak_f32 v45, v43, v45, 0xbe11a98e
	v_fmaak_f32 v45, v43, v45, 0x3e027906
	v_mul_f32_e32 v43, v43, v45
	v_mul_f32_e32 v43, v47, v43
	v_fma_f32 v47, |v1|, s84, 1.0
	v_rcp_f32_e32 v47, v47
	v_mul_f32_e32 v45, v0, v43
	v_fma_f32 v43, -v0, v43, v0
	v_cmp_gt_f32_e32 vcc, 0, v0
	v_mov_b32_e32 v59, v2
	v_mov_b32_e32 v61, v3
	v_cndmask_b32_e32 v0, v43, v45, vcc
	v_mul_f32_e32 v64, v38, v0
	v_mul_f32_e32 v38, 0xbf38aa3b, v57
	v_pk_mul_f32 v[56:57], v[102:103], v[58:59]
	v_pk_mul_f32 v[2:3], v[92:93], v[60:61]
	v_fmamk_f32 v0, v47, 0x3f07dc22, v241
	v_pk_fma_f32 v[48:49], v[88:89], v[48:49], v[96:97]
	v_mov_b32_e32 v58, v57
	v_mov_b32_e32 v59, v3
	v_fmaak_f32 v0, v47, v0, 0x3f35f0e3
	v_exp_f32_e32 v38, v38
	v_pk_add_f32 v[48:49], v[58:59], v[48:49]
	v_mov_b32_e32 v57, v2
	v_fmaak_f32 v0, v47, v0, 0xbe11a98e
	v_pk_add_f32 v[2:3], v[56:57], v[48:49]
	v_fmaak_f32 v0, v47, v0, 0x3e027906
	v_fma_f32 v43, |v2|, s84, 1.0
	v_mul_f32_e32 v0, v47, v0
	v_rcp_f32_e32 v43, v43
	v_mul_f32_e32 v0, v38, v0
	v_mul_f32_e32 v38, v1, v0
	v_fma_f32 v0, -v1, v0, v1
	v_cmp_gt_f32_e32 vcc, 0, v1
	v_mov_b32_e32 v63, v4
	v_mov_b32_e32 v47, v7
	v_cndmask_b32_e32 v0, v0, v38, vcc
	v_mul_f32_e32 v48, v39, v0
	v_fmamk_f32 v0, v43, 0x3f07dc22, v241
	v_fmaak_f32 v38, v43, v0, 0x3f35f0e3
	v_pk_mul_f32 v[0:1], v[2:3], v[2:3]
	v_fmaak_f32 v38, v43, v38, 0xbe11a98e
	v_mul_f32_e32 v0, 0xbf38aa3b, v0
	v_exp_f32_e32 v0, v0
	v_fmaak_f32 v38, v43, v38, 0x3e027906
	v_fma_f32 v39, |v3|, s84, 1.0
	v_mul_f32_e32 v38, v43, v38
	v_rcp_f32_e32 v39, v39
	v_mul_f32_e32 v0, v0, v38
	v_mul_f32_e32 v38, v2, v0
	v_fma_f32 v0, -v2, v0, v2
	v_cmp_gt_f32_e32 vcc, 0, v2
	v_mul_f32_e32 v1, 0xbf38aa3b, v1
	v_exp_f32_e32 v1, v1
	v_cndmask_b32_e32 v0, v0, v38, vcc
	v_mul_f32_e32 v40, v40, v0
	v_fmamk_f32 v0, v39, 0x3f07dc22, v241
	v_fmaak_f32 v0, v39, v0, 0x3f35f0e3
	v_fmaak_f32 v0, v39, v0, 0xbe11a98e
	v_fmaak_f32 v0, v39, v0, 0x3e027906
	v_mul_f32_e32 v0, v39, v0
	v_mul_f32_e32 v0, v1, v0
	v_mov_b32_e32 v43, v5
	v_mul_f32_e32 v2, v3, v0
	v_fma_f32 v45, -v3, v0, v3
	v_pk_mul_f32 v[0:1], v[70:71], v[62:63]
	v_pk_mul_f32 v[4:5], v[78:79], v[42:43]
	v_pk_fma_f32 v[38:39], v[74:75], v[50:51], v[82:83]
	v_mov_b32_e32 v42, v1
	v_mov_b32_e32 v43, v5
	v_pk_add_f32 v[38:39], v[42:43], v[38:39]
	v_mov_b32_e32 v1, v4
	v_pk_add_f32 v[0:1], v[0:1], v[38:39]
	v_cmp_gt_f32_e32 vcc, 0, v3
	v_fma_f32 v4, |v0|, s84, 1.0
	v_rcp_f32_e32 v4, v4
	v_cndmask_b32_e32 v2, v45, v2, vcc
	v_mul_f32_e32 v41, v41, v2
	v_cmp_gt_f32_e32 vcc, 0, v0
	v_fmamk_f32 v2, v4, 0x3f07dc22, v241
	v_fmaak_f32 v5, v4, v2, 0x3f35f0e3
	v_pk_mul_f32 v[2:3], v[0:1], v[0:1]
	v_fmaak_f32 v5, v4, v5, 0xbe11a98e
; __device__ __forceinline__ unsigned pk2(float lo, float hi) { unsigned r; asm("v_cvt_pk_bf16_f32 %0, %1, %2" : "=v"(r) : "v"(lo), "v"(hi)); return r; }
;     static __device__ __forceinline__ void unpack8(const u32x4 q, float (&x)[8]) { x[0] = bflo(q.x); x[1] = bfhi(q.x); x[2] = bflo(q.y); x[3] = bfhi(q.y); x[4] = bflo(q.z); x[5] = bfhi(q.z); x[6] = bflo(q.w); x[7] = bfhi(q.w); }
;     __device__ __forceinline__ void operator()(EPI_ARGS) const {
;     ...
;                     for (int t = 0; t < 1; ++t) { const int row = row0 + ai * 128 + (mp + t) * 16; const int r1 = row > 0 ? row - 1 : 0, r2 = row > 1 ? row - 2 : 0;
;                         q2[t] = *(const u32x4*)(up + (size_t)row * DFF + col); q1[t] = *(const u32x4*)(up + (size_t)r1 * DFF + col); q0[t] = *(const u32x4*)(up + (size_t)r2 * DFF + col); }
;                     __builtin_amdgcn_sched_barrier(0);
; #pragma unroll
;                     for (int t = 0; t < 1; ++t) { const int m = mp + t, row = row0 + ai * 128 + m * 16;
;                         const int i = row < TP ? row : ((row - TP) & 15); const int sidx = row < TP ? 0 : ((row - TP) >> 4);
;                         float x0[8], x1[8], x2[8]; unpack8(q0[t], x0); unpack8(q1[t], x1); unpack8(q2[t], x2);
;                         if (i < 2) {
;                             const bool smp = row >= TP; const float* p0 = cs + ((size_t)sidx * 2 + i) * DFF + col; const float* p1 = cs + ((size_t)sidx * 2 + 1) * DFF + col;
; #pragma unroll
;                             for (int e = 0; e < 8; ++e) { x0[e] = smp ? p0[e] : 0.f; if (i == 0) x1[e] = smp ? p1[e] : 0.f; } }
;     ...
;                         for (int e = 0; e < 8; ++e) { const float cv = bb[e] + x0[e] * w0[e] + x1[e] * w1[e] + x2[e] * w2[e]; r[e] = gelu_f(cv) * acc[ai][bj][m][e >> 2][e & 3]; }
;                         u32x4 w; w.x = pk2(r[0], r[1]); w.y = pk2(r[2], r[3]); w.z = pk2(r[4], r[5]); w.w = pk2(r[6], r[7]);
;                         *(u32x4*)(act + (size_t)row * DFF + col) = w; } } } }
	v_mul_f32_e32 v2, 0xbf38aa3b, v2
	v_exp_f32_e32 v2, v2
	v_fmaak_f32 v5, v4, v5, 0x3e027906
	v_mul_f32_e32 v4, v4, v5
	v_fma_f32 v5, |v1|, s84, 1.0
	v_rcp_f32_e32 v5, v5
	v_mul_f32_e32 v2, v2, v4
	v_mul_f32_e32 v4, v0, v2
	v_fma_f32 v2, -v0, v2, v0
	v_cndmask_b32_e32 v0, v2, v4, vcc
	v_mul_f32_e32 v34, v34, v0
	v_fmamk_f32 v0, v5, 0x3f07dc22, v241
	v_mul_f32_e32 v2, 0xbf38aa3b, v3
	v_fmaak_f32 v0, v5, v0, 0x3f35f0e3
	v_exp_f32_e32 v2, v2
	v_fmaak_f32 v0, v5, v0, 0xbe11a98e
	v_fmaak_f32 v0, v5, v0, 0x3e027906
	v_mul_f32_e32 v0, v5, v0
	v_mov_b32_e32 v45, v6
	v_mul_f32_e32 v0, v2, v0
	v_pk_mul_f32 v[2:3], v[72:73], v[44:45]
	v_pk_mul_f32 v[4:5], v[80:81], v[46:47]
	v_pk_fma_f32 v[6:7], v[76:77], v[52:53], v[84:85]
	v_mov_b32_e32 v38, v3
	v_mov_b32_e32 v39, v5
	v_pk_add_f32 v[6:7], v[38:39], v[6:7]
	v_mov_b32_e32 v3, v4
	v_pk_add_f32 v[2:3], v[2:3], v[6:7]
	v_mul_f32_e32 v42, v1, v0
	v_fma_f32 v4, |v2|, s84, 1.0
	v_rcp_f32_e32 v4, v4
	v_fma_f32 v0, -v1, v0, v1
	v_cmp_gt_f32_e32 vcc, 0, v1
	v_mad_i64_i32 v[54:55], s[0:1], v224, s76, 0
	s_nop 0
	v_cndmask_b32_e32 v0, v0, v42, vcc
	v_mul_f32_e32 v5, v35, v0
	v_fmamk_f32 v0, v4, 0x3f07dc22, v241
	v_fmaak_f32 v6, v4, v0, 0x3f35f0e3
	v_pk_mul_f32 v[0:1], v[2:3], v[2:3]
	v_fmaak_f32 v6, v4, v6, 0xbe11a98e
	v_mul_f32_e32 v0, 0xbf38aa3b, v0
	v_exp_f32_e32 v0, v0
	v_fmaak_f32 v6, v4, v6, 0x3e027906
	v_mul_f32_e32 v4, v4, v6
	v_fma_f32 v6, |v3|, s84, 1.0
	v_rcp_f32_e32 v6, v6
	v_mul_f32_e32 v0, v0, v4
	v_mul_f32_e32 v4, v2, v0
	v_fma_f32 v0, -v2, v0, v2
	v_cmp_gt_f32_e32 vcc, 0, v2
	v_mul_f32_e32 v1, 0xbf38aa3b, v1
	v_exp_f32_e32 v1, v1
	v_cndmask_b32_e32 v0, v0, v4, vcc
	v_mul_f32_e32 v4, v36, v0
	v_fmamk_f32 v0, v6, 0x3f07dc22, v241
	v_fmaak_f32 v0, v6, v0, 0x3f35f0e3
	v_fmaak_f32 v0, v6, v0, 0xbe11a98e
	v_fmaak_f32 v0, v6, v0, 0x3e027906
	v_mul_f32_e32 v0, v6, v0
	v_mul_f32_e32 v0, v1, v0
	v_mul_f32_e32 v1, v3, v0
	v_fma_f32 v0, -v3, v0, v3
	v_cmp_gt_f32_e32 vcc, 0, v3
	v_cvt_pk_bf16_f32 v2, v34, v5
	v_add_u32_e32 v52, 0x90, v232
	s_nop 0
	v_cndmask_b32_e32 v0, v0, v1, vcc
	v_mul_f32_e32 v3, v37, v0
	v_cvt_pk_bf16_f32 v3, v4, v3
	v_lshl_add_u64 v[4:5], s[80:81], 0, v[54:55]
	v_cvt_pk_bf16_f32 v0, v64, v48
	v_lshl_add_u64 v[4:5], v[4:5], 0, v[186:187]
	v_cvt_pk_bf16_f32 v1, v40, v41
	global_store_dwordx4 v[4:5], v[0:3], off offset:256
	s_nop 1
	v_max_i32_e32 v0, 1, v52
	v_add_u32_e32 v4, -1, v0
	v_max_i32_e32 v0, 2, v52
	v_add_u32_e32 v38, -2, v0
	v_mov_b64_e32 v[0:1], s[30:31]
	v_mad_i64_i32 v[2:3], s[0:1], v52, s76, v[0:1]
	v_mad_u64_u32 v[4:5], s[0:1], v4, s76, v[0:1]
	v_mad_u64_u32 v[0:1], s[0:1], v38, s76, v[0:1]
	v_lshl_add_u64 v[2:3], v[2:3], 0, v[186:187]
	v_lshl_add_u64 v[4:5], v[4:5], 0, v[186:187]
	v_lshl_add_u64 v[0:1], v[0:1], 0, v[186:187]
	s_movk_i32 s0, 0x1f70
	v_cmp_gt_i32_e64 s[0:1], s0, v232
	s_waitcnt vmcnt(1)
	v_mov_b64_e32 v[34:35], v[196:197]
	v_mov_b64_e32 v[36:37], v[198:199]
	v_mov_b64_e32 v[4:5], v[200:201]
	v_mov_b64_e32 v[6:7], v[202:203]
	v_mov_b64_e32 v[0:1], v[242:243]
	v_mov_b64_e32 v[2:3], v[244:245]
	v_lshlrev_b32_e32 v38, 16, v0
	v_and_b32_e32 v39, 0xffff0000, v0
	v_cndmask_b32_e64 v50, v228, v52, s[0:1]
	v_lshlrev_b32_e32 v40, 16, v1
	v_and_b32_e32 v41, 0xffff0000, v1
	v_lshlrev_b32_e32 v42, 16, v2
	v_and_b32_e32 v43, 0xffff0000, v2
	v_lshlrev_b32_e32 v44, 16, v3
	v_and_b32_e32 v45, 0xffff0000, v3
	v_lshlrev_b32_e32 v0, 16, v4
	v_and_b32_e32 v1, 0xffff0000, v4
	v_lshlrev_b32_e32 v2, 16, v5
	v_and_b32_e32 v3, 0xffff0000, v5
	v_lshlrev_b32_e32 v4, 16, v6
	v_and_b32_e32 v5, 0xffff0000, v6
	v_lshlrev_b32_e32 v6, 16, v7
	v_and_b32_e32 v7, 0xffff0000, v7
	v_cmp_gt_i32_e32 vcc, 2, v50
	s_and_saveexec_b64 s[8:9], vcc
	s_cbranch_execz .LBB0_1826
	s_movk_i32 s14, 0x1f6f
	v_cmp_lt_i32_e32 vcc, s14, v232
	s_add_i32 s14, s5, 0xffffe090
	s_ashr_i32 s14, s14, 4
	v_mov_b32_e32 v38, s14
	v_cndmask_b32_e64 v40, v38, 0, s[0:1]
	v_ashrrev_i32_e32 v41, 31, v40
	v_ashrrev_i32_e32 v51, 31, v50
	v_lshl_add_u64 v[38:39], v[40:41], 1, v[50:51]
	v_mov_b64_e32 v[42:43], s[68:69]
	v_mad_u64_u32 v[42:43], s[0:1], v38, s13, v[42:43]
	v_mad_i32_i24 v43, v39, s13, v43
	v_lshl_add_u64 v[48:49], v[184:185], 2, v[42:43]
	v_mov_b32_e32 v38, 0
	s_and_saveexec_b64 s[0:1], vcc
	s_cbranch_execz .LBB0_1779
	global_load_dword v38, v[48:49], off offset:512

;     static __device__ __forceinline__ void unpack8(const u32x4 q, float (&x)[8]) { x[0] = bflo(q.x); x[1] = bfhi(q.x); x[2] = bflo(q.y); x[3] = bfhi(q.y); x[4] = bflo(q.z); x[5] = bfhi(q.z); x[6] = bflo(q.w); x[7] = bfhi(q.w); }
;     __device__ __forceinline__ void operator()(EPI_ARGS) const {
;     ...
;                     for (int t = 0; t < 1; ++t) { const int row = row0 + ai * 128 + (mp + t) * 16; const int r1 = row > 0 ? row - 1 : 0, r2 = row > 1 ? row - 2 : 0;
;                         q2[t] = *(const u32x4*)(up + (size_t)row * DFF + col); q1[t] = *(const u32x4*)(up + (size_t)r1 * DFF + col); q0[t] = *(const u32x4*)(up + (size_t)r2 * DFF + col); }
;                     __builtin_amdgcn_sched_barrier(0);
; #pragma unroll
;                     for (int t = 0; t < 1; ++t) { const int m = mp + t, row = row0 + ai * 128 + m * 16;
;                         const int i = row < TP ? row : ((row - TP) & 15); const int sidx = row < TP ? 0 : ((row - TP) >> 4);
;                         float x0[8], x1[8], x2[8]; unpack8(q0[t], x0); unpack8(q1[t], x1); unpack8(q2[t], x2);
;                         if (i < 2) {
;                             const bool smp = row >= TP; const float* p0 = cs + ((size_t)sidx * 2 + i) * DFF + col; const float* p1 = cs + ((size_t)sidx * 2 + 1) * DFF + col;
; #pragma unroll
;                             for (int e = 0; e < 8; ++e) { x0[e] = smp ? p0[e] : 0.f; if (i == 0) x1[e] = smp ? p1[e] : 0.f; } }
;                         float r[8];
; #pragma unroll
;                         for (int e = 0; e < 8; ++e) { const float cv = bb[e] + x0[e] * w0[e] + x1[e] * w1[e] + x2[e] * w2[e]; r[e] = gelu_f(cv) * acc[ai][bj][m][e >> 2][e & 3]; }
.LBB0_1824:
	s_or_b64 exec, exec, s[0:1]
.LBB0_1825:
	s_or_b64 exec, exec, s[14:15]
	s_waitcnt vmcnt(0)
.LBB0_1826:
	s_or_b64 exec, exec, s[8:9]
	v_mad_i64_i32 v[46:47], s[0:1], v52, s76, 0
	v_lshlrev_b32_e32 v48, 16, v34
	v_and_b32_e32 v34, 0xffff0000, v34
	v_lshlrev_b32_e32 v50, 16, v35
	v_and_b32_e32 v52, 0xffff0000, v35
	s_waitcnt vmcnt(1)
	v_add_u32_e32 v240, 160, v232
	v_mov_b64_e32 v[238:239], s[30:31]
	v_mad_i64_i32 v[238:239], s[0:1], v240, s76, v[238:239]
	v_lshl_add_u64 v[238:239], v[238:239], 0, v[186:187]
	global_load_dwordx4 v[196:199], v[238:239], off offset:256
	v_add_u32_e32 v240, -1, v240
	v_mov_b64_e32 v[246:247], s[30:31]
	v_mad_i64_i32 v[246:247], s[0:1], v240, s76, v[246:247]
	v_lshl_add_u64 v[246:247], v[246:247], 0, v[186:187]
	global_load_dwordx4 v[200:203], v[246:247], off offset:256
	v_add_u32_e32 v240, -1, v240
	v_mov_b64_e32 v[238:239], s[30:31]
	v_mad_i64_i32 v[238:239], s[0:1], v240, s76, v[238:239]
	v_lshl_add_u64 v[238:239], v[238:239], 0, v[186:187]
	global_load_dwordx4 v[242:245], v[238:239], off offset:256
	v_mov_b32_e32 v49, v0
	v_mov_b32_e32 v35, v1
	v_pk_mul_f32 v[48:49], v[106:107], v[48:49]
	v_pk_mul_f32 v[0:1], v[90:91], v[34:35]
	v_pk_fma_f32 v[34:35], v[86:87], v[38:39], v[94:95]
	v_mov_b32_e32 v38, v49
	v_mov_b32_e32 v39, v1
	v_pk_add_f32 v[34:35], v[38:39], v[34:35]
	v_mov_b32_e32 v49, v0
	v_pk_add_f32 v[0:1], v[48:49], v[34:35]
	v_lshlrev_b32_e32 v54, 16, v36
	v_fma_f32 v34, |v0|, s84, 1.0
	v_rcp_f32_e32 v35, v34
	v_pk_mul_f32 v[48:49], v[0:1], v[0:1]
	v_and_b32_e32 v34, 0xffff0000, v36
	v_lshlrev_b32_e32 v36, 16, v37
	v_and_b32_e32 v38, 0xffff0000, v37
	v_fmamk_f32 v37, v35, 0x3f07dc22, v241
	v_mul_f32_e32 v39, 0xbf38aa3b, v48
	v_fmaak_f32 v37, v35, v37, 0x3f35f0e3
	v_exp_f32_e32 v39, v39
	v_fmaak_f32 v37, v35, v37, 0xbe11a98e
	v_fmaak_f32 v37, v35, v37, 0x3e027906
	v_mul_f32_e32 v35, v35, v37
	v_mul_f32_e32 v35, v39, v35
	v_fma_f32 v39, |v1|, s84, 1.0
	v_rcp_f32_e32 v39, v39
	v_mul_f32_e32 v37, v0, v35
	v_fma_f32 v35, -v0, v35, v0
	v_cmp_gt_f32_e32 vcc, 0, v0
	v_mov_b32_e32 v51, v2
	v_mov_b32_e32 v53, v3
	v_cndmask_b32_e32 v0, v35, v37, vcc
	v_mul_f32_e32 v56, v30, v0
	v_mul_f32_e32 v30, 0xbf38aa3b, v49
	v_pk_mul_f32 v[48:49], v[102:103], v[50:51]
	v_pk_mul_f32 v[2:3], v[92:93], v[52:53]
	v_fmamk_f32 v0, v39, 0x3f07dc22, v241
	v_pk_fma_f32 v[40:41], v[88:89], v[40:41], v[96:97]
	v_mov_b32_e32 v50, v49
	v_mov_b32_e32 v51, v3
	v_fmaak_f32 v0, v39, v0, 0x3f35f0e3
	v_exp_f32_e32 v30, v30
	v_pk_add_f32 v[40:41], v[50:51], v[40:41]
	v_mov_b32_e32 v49, v2
	v_fmaak_f32 v0, v39, v0, 0xbe11a98e
	v_pk_add_f32 v[2:3], v[48:49], v[40:41]
	v_fmaak_f32 v0, v39, v0, 0x3e027906
	v_fma_f32 v35, |v2|, s84, 1.0
	v_mul_f32_e32 v0, v39, v0
	v_rcp_f32_e32 v35, v35
	v_mul_f32_e32 v0, v30, v0
	v_mul_f32_e32 v30, v1, v0
	v_fma_f32 v0, -v1, v0, v1
	v_cmp_gt_f32_e32 vcc, 0, v1
	v_mov_b32_e32 v55, v4
	v_mov_b32_e32 v39, v7
	v_cndmask_b32_e32 v0, v0, v30, vcc
	v_mul_f32_e32 v40, v31, v0
	v_fmamk_f32 v0, v35, 0x3f07dc22, v241
	v_fmaak_f32 v30, v35, v0, 0x3f35f0e3
	v_pk_mul_f32 v[0:1], v[2:3], v[2:3]
	v_fmaak_f32 v30, v35, v30, 0xbe11a98e
	v_mul_f32_e32 v0, 0xbf38aa3b, v0
	v_exp_f32_e32 v0, v0
	v_fmaak_f32 v30, v35, v30, 0x3e027906
	v_fma_f32 v31, |v3|, s84, 1.0
	v_mul_f32_e32 v30, v35, v30
	v_rcp_f32_e32 v31, v31
	v_mul_f32_e32 v0, v0, v30
	v_mul_f32_e32 v30, v2, v0
	v_fma_f32 v0, -v2, v0, v2
	v_cmp_gt_f32_e32 vcc, 0, v2
	v_mul_f32_e32 v1, 0xbf38aa3b, v1
	v_exp_f32_e32 v1, v1
	v_cndmask_b32_e32 v0, v0, v30, vcc
	v_mul_f32_e32 v32, v32, v0
	v_fmamk_f32 v0, v31, 0x3f07dc22, v241
	v_fmaak_f32 v0, v31, v0, 0x3f35f0e3
	v_fmaak_f32 v0, v31, v0, 0xbe11a98e
	v_fmaak_f32 v0, v31, v0, 0x3e027906
	v_mul_f32_e32 v0, v31, v0
	v_mul_f32_e32 v0, v1, v0
	v_mov_b32_e32 v35, v5
	v_mul_f32_e32 v2, v3, v0
	v_fma_f32 v37, -v3, v0, v3
	v_pk_mul_f32 v[0:1], v[70:71], v[54:55]
	v_pk_mul_f32 v[4:5], v[78:79], v[34:35]
	v_pk_fma_f32 v[30:31], v[74:75], v[42:43], v[82:83]
	v_mov_b32_e32 v34, v1
	v_mov_b32_e32 v35, v5
	v_pk_add_f32 v[30:31], v[34:35], v[30:31]
	v_mov_b32_e32 v1, v4
	v_pk_add_f32 v[0:1], v[0:1], v[30:31]
	v_cmp_gt_f32_e32 vcc, 0, v3
	v_fma_f32 v4, |v0|, s84, 1.0
	v_rcp_f32_e32 v4, v4
	v_cndmask_b32_e32 v2, v37, v2, vcc
	v_mul_f32_e32 v33, v33, v2
	v_cmp_gt_f32_e32 vcc, 0, v0
	v_fmamk_f32 v2, v4, 0x3f07dc22, v241
; __device__ __forceinline__ unsigned pk2(float lo, float hi) { unsigned r; asm("v_cvt_pk_bf16_f32 %0, %1, %2" : "=v"(r) : "v"(lo), "v"(hi)); return r; }
;     static __device__ __forceinline__ void unpack8(const u32x4 q, float (&x)[8]) { x[0] = bflo(q.x); x[1] = bfhi(q.x); x[2] = bflo(q.y); x[3] = bfhi(q.y); x[4] = bflo(q.z); x[5] = bfhi(q.z); x[6] = bflo(q.w); x[7] = bfhi(q.w); }
;     __device__ __forceinline__ void operator()(EPI_ARGS) const {
;     ...
;                     for (int t = 0; t < 1; ++t) { const int row = row0 + ai * 128 + (mp + t) * 16; const int r1 = row > 0 ? row - 1 : 0, r2 = row > 1 ? row - 2 : 0;
;                         q2[t] = *(const u32x4*)(up + (size_t)row * DFF + col); q1[t] = *(const u32x4*)(up + (size_t)r1 * DFF + col); q0[t] = *(const u32x4*)(up + (size_t)r2 * DFF + col); }
;                     __builtin_amdgcn_sched_barrier(0);
; #pragma unroll
;                     for (int t = 0; t < 1; ++t) { const int m = mp + t, row = row0 + ai * 128 + m * 16;
;                         const int i = row < TP ? row : ((row - TP) & 15); const int sidx = row < TP ? 0 : ((row - TP) >> 4);
;                         float x0[8], x1[8], x2[8]; unpack8(q0[t], x0); unpack8(q1[t], x1); unpack8(q2[t], x2);
;                         if (i < 2) {
;                             const bool smp = row >= TP; const float* p0 = cs + ((size_t)sidx * 2 + i) * DFF + col; const float* p1 = cs + ((size_t)sidx * 2 + 1) * DFF + col;
; #pragma unroll
;                             for (int e = 0; e < 8; ++e) { x0[e] = smp ? p0[e] : 0.f; if (i == 0) x1[e] = smp ? p1[e] : 0.f; } }
;     ...
;                         for (int e = 0; e < 8; ++e) { const float cv = bb[e] + x0[e] * w0[e] + x1[e] * w1[e] + x2[e] * w2[e]; r[e] = gelu_f(cv) * acc[ai][bj][m][e >> 2][e & 3]; }
;                         u32x4 w; w.x = pk2(r[0], r[1]); w.y = pk2(r[2], r[3]); w.z = pk2(r[4], r[5]); w.w = pk2(r[6], r[7]);
;                         *(u32x4*)(act + (size_t)row * DFF + col) = w; } } } }
	v_fmaak_f32 v5, v4, v2, 0x3f35f0e3
	v_pk_mul_f32 v[2:3], v[0:1], v[0:1]
	v_fmaak_f32 v5, v4, v5, 0xbe11a98e
	v_mul_f32_e32 v2, 0xbf38aa3b, v2
	v_exp_f32_e32 v2, v2
	v_fmaak_f32 v5, v4, v5, 0x3e027906
	v_mul_f32_e32 v4, v4, v5
	v_fma_f32 v5, |v1|, s84, 1.0
	v_rcp_f32_e32 v5, v5
	v_mul_f32_e32 v2, v2, v4
	v_mul_f32_e32 v4, v0, v2
	v_fma_f32 v2, -v0, v2, v0
	v_cndmask_b32_e32 v0, v2, v4, vcc
	v_mul_f32_e32 v26, v26, v0
	v_fmamk_f32 v0, v5, 0x3f07dc22, v241
	v_mul_f32_e32 v2, 0xbf38aa3b, v3
	v_fmaak_f32 v0, v5, v0, 0x3f35f0e3
	v_exp_f32_e32 v2, v2
	v_fmaak_f32 v0, v5, v0, 0xbe11a98e
	v_fmaak_f32 v0, v5, v0, 0x3e027906
	v_mul_f32_e32 v0, v5, v0
	v_mov_b32_e32 v37, v6
	v_mul_f32_e32 v0, v2, v0
	v_pk_mul_f32 v[2:3], v[72:73], v[36:37]
	v_pk_mul_f32 v[4:5], v[80:81], v[38:39]
	v_pk_fma_f32 v[6:7], v[76:77], v[44:45], v[84:85]
	v_mov_b32_e32 v30, v3
	v_mov_b32_e32 v31, v5
	v_pk_add_f32 v[6:7], v[30:31], v[6:7]
	v_mov_b32_e32 v3, v4
	v_pk_add_f32 v[2:3], v[2:3], v[6:7]
	v_mul_f32_e32 v34, v1, v0
	v_fma_f32 v4, |v2|, s84, 1.0
	v_rcp_f32_e32 v4, v4
	v_fma_f32 v0, -v1, v0, v1
	v_cmp_gt_f32_e32 vcc, 0, v1
	v_add_u32_e32 v44, 0xa0, v232
	s_nop 0
	v_cndmask_b32_e32 v0, v0, v34, vcc
	v_mul_f32_e32 v5, v27, v0
	v_fmamk_f32 v0, v4, 0x3f07dc22, v241
	v_fmaak_f32 v6, v4, v0, 0x3f35f0e3
	v_pk_mul_f32 v[0:1], v[2:3], v[2:3]
	v_fmaak_f32 v6, v4, v6, 0xbe11a98e
	v_mul_f32_e32 v0, 0xbf38aa3b, v0
	v_exp_f32_e32 v0, v0
	v_fmaak_f32 v6, v4, v6, 0x3e027906
	v_mul_f32_e32 v4, v4, v6
	v_fma_f32 v6, |v3|, s84, 1.0
	v_rcp_f32_e32 v6, v6
	v_mul_f32_e32 v0, v0, v4
	v_mul_f32_e32 v4, v2, v0
	v_fma_f32 v0, -v2, v0, v2
	v_cmp_gt_f32_e32 vcc, 0, v2
	v_mul_f32_e32 v1, 0xbf38aa3b, v1
	v_exp_f32_e32 v1, v1
	v_cndmask_b32_e32 v0, v0, v4, vcc
	v_mul_f32_e32 v4, v28, v0
	v_fmamk_f32 v0, v6, 0x3f07dc22, v241
	v_fmaak_f32 v0, v6, v0, 0x3f35f0e3
	v_fmaak_f32 v0, v6, v0, 0xbe11a98e
	v_fmaak_f32 v0, v6, v0, 0x3e027906
	v_mul_f32_e32 v0, v6, v0
	v_mul_f32_e32 v0, v1, v0
	v_mul_f32_e32 v1, v3, v0
	v_fma_f32 v0, -v3, v0, v3
	v_cmp_gt_f32_e32 vcc, 0, v3
	v_cvt_pk_bf16_f32 v2, v26, v5
	s_nop 1
	v_cndmask_b32_e32 v0, v0, v1, vcc
	v_mul_f32_e32 v3, v29, v0
	v_cvt_pk_bf16_f32 v3, v4, v3
	v_lshl_add_u64 v[4:5], s[80:81], 0, v[46:47]
	v_cvt_pk_bf16_f32 v0, v56, v40
	v_lshl_add_u64 v[4:5], v[4:5], 0, v[186:187]
	v_cvt_pk_bf16_f32 v1, v32, v33
	global_store_dwordx4 v[4:5], v[0:3], off offset:256
	s_nop 1
	v_max_i32_e32 v0, 1, v44
	v_add_u32_e32 v4, -1, v0
	v_max_i32_e32 v0, 2, v44
	v_add_u32_e32 v30, -2, v0
	v_mov_b64_e32 v[0:1], s[30:31]
	v_mad_i64_i32 v[2:3], s[0:1], v44, s76, v[0:1]
	v_mad_u64_u32 v[4:5], s[0:1], v4, s76, v[0:1]
	v_mad_u64_u32 v[0:1], s[0:1], v30, s76, v[0:1]
	v_lshl_add_u64 v[2:3], v[2:3], 0, v[186:187]
	v_lshl_add_u64 v[4:5], v[4:5], 0, v[186:187]
	v_lshl_add_u64 v[0:1], v[0:1], 0, v[186:187]
	s_movk_i32 s0, 0x1f60
	v_cmp_gt_i32_e64 s[0:1], s0, v232
	s_waitcnt vmcnt(1)
	v_mov_b64_e32 v[26:27], v[196:197]
	v_mov_b64_e32 v[28:29], v[198:199]
	v_mov_b64_e32 v[4:5], v[200:201]
	v_mov_b64_e32 v[6:7], v[202:203]
	v_mov_b64_e32 v[0:1], v[242:243]
	v_mov_b64_e32 v[2:3], v[244:245]
	v_lshlrev_b32_e32 v30, 16, v0
	v_and_b32_e32 v31, 0xffff0000, v0
	v_cndmask_b32_e64 v42, v228, v44, s[0:1]
	v_lshlrev_b32_e32 v32, 16, v1
	v_and_b32_e32 v33, 0xffff0000, v1
	v_lshlrev_b32_e32 v34, 16, v2
	v_and_b32_e32 v35, 0xffff0000, v2
	v_lshlrev_b32_e32 v36, 16, v3
	v_and_b32_e32 v37, 0xffff0000, v3
	v_lshlrev_b32_e32 v0, 16, v4
	v_and_b32_e32 v1, 0xffff0000, v4
	v_lshlrev_b32_e32 v2, 16, v5
	v_and_b32_e32 v3, 0xffff0000, v5
	v_lshlrev_b32_e32 v4, 16, v6
	v_and_b32_e32 v5, 0xffff0000, v6
	v_lshlrev_b32_e32 v6, 16, v7
	v_and_b32_e32 v7, 0xffff0000, v7
	v_cmp_gt_i32_e32 vcc, 2, v42
	s_and_saveexec_b64 s[8:9], vcc
	s_cbranch_execz .LBB0_1876
	s_movk_i32 s14, 0x1f5f
	v_cmp_lt_i32_e32 vcc, s14, v232
	s_add_i32 s14, s5, 0xffffe0a0
	s_ashr_i32 s14, s14, 4
	v_mov_b32_e32 v30, s14
	v_cndmask_b32_e64 v32, v30, 0, s[0:1]
	v_ashrrev_i32_e32 v33, 31, v32
	v_ashrrev_i32_e32 v43, 31, v42
	v_lshl_add_u64 v[30:31], v[32:33], 1, v[42:43]
	v_mov_b64_e32 v[34:35], s[68:69]
	v_mad_u64_u32 v[34:35], s[0:1], v30, s13, v[34:35]
	v_mad_i32_i24 v35, v31, s13, v35
	v_lshl_add_u64 v[40:41], v[184:185], 2, v[34:35]
	v_mov_b32_e32 v30, 0
	s_and_saveexec_b64 s[0:1], vcc
	s_cbranch_execz .LBB0_1829
	global_load_dword v30, v[40:41], off offset:512

;     static __device__ __forceinline__ void unpack8(const u32x4 q, float (&x)[8]) { x[0] = bflo(q.x); x[1] = bfhi(q.x); x[2] = bflo(q.y); x[3] = bfhi(q.y); x[4] = bflo(q.z); x[5] = bfhi(q.z); x[6] = bflo(q.w); x[7] = bfhi(q.w); }
;     __device__ __forceinline__ void operator()(EPI_ARGS) const {
;     ...
;                     for (int t = 0; t < 1; ++t) { const int row = row0 + ai * 128 + (mp + t) * 16; const int r1 = row > 0 ? row - 1 : 0, r2 = row > 1 ? row - 2 : 0;
;                         q2[t] = *(const u32x4*)(up + (size_t)row * DFF + col); q1[t] = *(const u32x4*)(up + (size_t)r1 * DFF + col); q0[t] = *(const u32x4*)(up + (size_t)r2 * DFF + col); }
;                     __builtin_amdgcn_sched_barrier(0);
; #pragma unroll
;                     for (int t = 0; t < 1; ++t) { const int m = mp + t, row = row0 + ai * 128 + m * 16;
;                         const int i = row < TP ? row : ((row - TP) & 15); const int sidx = row < TP ? 0 : ((row - TP) >> 4);
;                         float x0[8], x1[8], x2[8]; unpack8(q0[t], x0); unpack8(q1[t], x1); unpack8(q2[t], x2);
;                         if (i < 2) {
;                             const bool smp = row >= TP; const float* p0 = cs + ((size_t)sidx * 2 + i) * DFF + col; const float* p1 = cs + ((size_t)sidx * 2 + 1) * DFF + col;
; #pragma unroll
;                             for (int e = 0; e < 8; ++e) { x0[e] = smp ? p0[e] : 0.f; if (i == 0) x1[e] = smp ? p1[e] : 0.f; } }
;                         float r[8];
; #pragma unroll
;                         for (int e = 0; e < 8; ++e) { const float cv = bb[e] + x0[e] * w0[e] + x1[e] * w1[e] + x2[e] * w2[e]; r[e] = gelu_f(cv) * acc[ai][bj][m][e >> 2][e & 3]; }
.LBB0_1874:
	s_or_b64 exec, exec, s[0:1]
.LBB0_1875:
	s_or_b64 exec, exec, s[14:15]
	s_waitcnt vmcnt(0)
.LBB0_1876:
	s_or_b64 exec, exec, s[8:9]
	v_mad_i64_i32 v[38:39], s[0:1], v44, s76, 0
	v_lshlrev_b32_e32 v40, 16, v26
	v_and_b32_e32 v26, 0xffff0000, v26
	v_lshlrev_b32_e32 v42, 16, v27
	v_and_b32_e32 v44, 0xffff0000, v27
	s_waitcnt vmcnt(1)
	v_add_u32_e32 v240, 176, v232
	v_mov_b64_e32 v[238:239], s[30:31]
	v_mad_i64_i32 v[238:239], s[0:1], v240, s76, v[238:239]
	v_lshl_add_u64 v[238:239], v[238:239], 0, v[186:187]
	global_load_dwordx4 v[196:199], v[238:239], off offset:256
	v_add_u32_e32 v240, -1, v240
	v_mov_b64_e32 v[246:247], s[30:31]
	v_mad_i64_i32 v[246:247], s[0:1], v240, s76, v[246:247]
	v_lshl_add_u64 v[246:247], v[246:247], 0, v[186:187]
	global_load_dwordx4 v[200:203], v[246:247], off offset:256
	v_add_u32_e32 v240, -1, v240
	v_mov_b64_e32 v[238:239], s[30:31]
	v_mad_i64_i32 v[238:239], s[0:1], v240, s76, v[238:239]
	v_lshl_add_u64 v[238:239], v[238:239], 0, v[186:187]
	global_load_dwordx4 v[242:245], v[238:239], off offset:256
	v_mov_b32_e32 v41, v0
	v_mov_b32_e32 v27, v1
	v_pk_mul_f32 v[40:41], v[106:107], v[40:41]
	v_pk_mul_f32 v[0:1], v[90:91], v[26:27]
	v_pk_fma_f32 v[26:27], v[86:87], v[30:31], v[94:95]
	v_mov_b32_e32 v30, v41
	v_mov_b32_e32 v31, v1
	v_pk_add_f32 v[26:27], v[30:31], v[26:27]
	v_mov_b32_e32 v41, v0
	v_pk_add_f32 v[0:1], v[40:41], v[26:27]
	v_lshlrev_b32_e32 v46, 16, v28
	v_fma_f32 v26, |v0|, s84, 1.0
	v_rcp_f32_e32 v27, v26
	v_pk_mul_f32 v[40:41], v[0:1], v[0:1]
	v_and_b32_e32 v26, 0xffff0000, v28
	v_lshlrev_b32_e32 v28, 16, v29
	v_and_b32_e32 v30, 0xffff0000, v29
	v_fmamk_f32 v29, v27, 0x3f07dc22, v241
	v_mul_f32_e32 v31, 0xbf38aa3b, v40
	v_fmaak_f32 v29, v27, v29, 0x3f35f0e3
	v_exp_f32_e32 v31, v31
	v_fmaak_f32 v29, v27, v29, 0xbe11a98e
	v_fmaak_f32 v29, v27, v29, 0x3e027906
	v_mul_f32_e32 v27, v27, v29
	v_mul_f32_e32 v27, v31, v27
	v_fma_f32 v31, |v1|, s84, 1.0
	v_rcp_f32_e32 v31, v31
	v_mul_f32_e32 v29, v0, v27
	v_fma_f32 v27, -v0, v27, v0
	v_cmp_gt_f32_e32 vcc, 0, v0
	v_mov_b32_e32 v43, v2
	v_mov_b32_e32 v45, v3
	v_cndmask_b32_e32 v0, v27, v29, vcc
	v_mul_f32_e32 v48, v22, v0
	v_mul_f32_e32 v22, 0xbf38aa3b, v41
	v_pk_mul_f32 v[40:41], v[102:103], v[42:43]
	v_pk_mul_f32 v[2:3], v[92:93], v[44:45]
	v_fmamk_f32 v0, v31, 0x3f07dc22, v241
	v_pk_fma_f32 v[32:33], v[88:89], v[32:33], v[96:97]
	v_mov_b32_e32 v42, v41
	v_mov_b32_e32 v43, v3
	v_fmaak_f32 v0, v31, v0, 0x3f35f0e3
	v_exp_f32_e32 v22, v22
	v_pk_add_f32 v[32:33], v[42:43], v[32:33]
	v_mov_b32_e32 v41, v2
	v_fmaak_f32 v0, v31, v0, 0xbe11a98e
	v_pk_add_f32 v[2:3], v[40:41], v[32:33]
	v_fmaak_f32 v0, v31, v0, 0x3e027906
	v_fma_f32 v27, |v2|, s84, 1.0
	v_mul_f32_e32 v0, v31, v0
	v_rcp_f32_e32 v27, v27
	v_mul_f32_e32 v0, v22, v0
	v_mul_f32_e32 v22, v1, v0
	v_fma_f32 v0, -v1, v0, v1
	v_cmp_gt_f32_e32 vcc, 0, v1
	v_mov_b32_e32 v47, v4
	v_mov_b32_e32 v31, v7
	v_cndmask_b32_e32 v0, v0, v22, vcc
	v_mul_f32_e32 v32, v23, v0
	v_fmamk_f32 v0, v27, 0x3f07dc22, v241
	v_fmaak_f32 v22, v27, v0, 0x3f35f0e3
	v_pk_mul_f32 v[0:1], v[2:3], v[2:3]
	v_fmaak_f32 v22, v27, v22, 0xbe11a98e
	v_mul_f32_e32 v0, 0xbf38aa3b, v0
	v_exp_f32_e32 v0, v0
	v_fmaak_f32 v22, v27, v22, 0x3e027906
	v_fma_f32 v23, |v3|, s84, 1.0
	v_mul_f32_e32 v22, v27, v22
	v_rcp_f32_e32 v23, v23
	v_mul_f32_e32 v0, v0, v22
	v_mul_f32_e32 v22, v2, v0
	v_fma_f32 v0, -v2, v0, v2
	v_cmp_gt_f32_e32 vcc, 0, v2
	v_mul_f32_e32 v1, 0xbf38aa3b, v1
	v_exp_f32_e32 v1, v1
	v_cndmask_b32_e32 v0, v0, v22, vcc
	v_mul_f32_e32 v24, v24, v0
	v_fmamk_f32 v0, v23, 0x3f07dc22, v241
	v_fmaak_f32 v0, v23, v0, 0x3f35f0e3
	v_fmaak_f32 v0, v23, v0, 0xbe11a98e
	v_fmaak_f32 v0, v23, v0, 0x3e027906
	v_mul_f32_e32 v0, v23, v0
	v_mul_f32_e32 v0, v1, v0
	v_mov_b32_e32 v27, v5
	v_mul_f32_e32 v2, v3, v0
	v_fma_f32 v29, -v3, v0, v3
	v_pk_mul_f32 v[0:1], v[70:71], v[46:47]
	v_pk_mul_f32 v[4:5], v[78:79], v[26:27]
	v_pk_fma_f32 v[22:23], v[74:75], v[34:35], v[82:83]
	v_mov_b32_e32 v26, v1
	v_mov_b32_e32 v27, v5
	v_pk_add_f32 v[22:23], v[26:27], v[22:23]
	v_mov_b32_e32 v1, v4
	v_pk_add_f32 v[0:1], v[0:1], v[22:23]
	v_cmp_gt_f32_e32 vcc, 0, v3
	v_fma_f32 v4, |v0|, s84, 1.0
	v_rcp_f32_e32 v4, v4
	v_cndmask_b32_e32 v2, v29, v2, vcc
	v_mul_f32_e32 v25, v25, v2
	v_cmp_gt_f32_e32 vcc, 0, v0
	v_fmamk_f32 v2, v4, 0x3f07dc22, v241
; __device__ __forceinline__ unsigned pk2(float lo, float hi) { unsigned r; asm("v_cvt_pk_bf16_f32 %0, %1, %2" : "=v"(r) : "v"(lo), "v"(hi)); return r; }
;     static __device__ __forceinline__ void unpack8(const u32x4 q, float (&x)[8]) { x[0] = bflo(q.x); x[1] = bfhi(q.x); x[2] = bflo(q.y); x[3] = bfhi(q.y); x[4] = bflo(q.z); x[5] = bfhi(q.z); x[6] = bflo(q.w); x[7] = bfhi(q.w); }
;     __device__ __forceinline__ void operator()(EPI_ARGS) const {
;     ...
;                     for (int t = 0; t < 1; ++t) { const int row = row0 + ai * 128 + (mp + t) * 16; const int r1 = row > 0 ? row - 1 : 0, r2 = row > 1 ? row - 2 : 0;
;                         q2[t] = *(const u32x4*)(up + (size_t)row * DFF + col); q1[t] = *(const u32x4*)(up + (size_t)r1 * DFF + col); q0[t] = *(const u32x4*)(up + (size_t)r2 * DFF + col); }
;                     __builtin_amdgcn_sched_barrier(0);
; #pragma unroll
;                     for (int t = 0; t < 1; ++t) { const int m = mp + t, row = row0 + ai * 128 + m * 16;
;                         const int i = row < TP ? row : ((row - TP) & 15); const int sidx = row < TP ? 0 : ((row - TP) >> 4);
;                         float x0[8], x1[8], x2[8]; unpack8(q0[t], x0); unpack8(q1[t], x1); unpack8(q2[t], x2);
;                         if (i < 2) {
;                             const bool smp = row >= TP; const float* p0 = cs + ((size_t)sidx * 2 + i) * DFF + col; const float* p1 = cs + ((size_t)sidx * 2 + 1) * DFF + col;
; #pragma unroll
;                             for (int e = 0; e < 8; ++e) { x0[e] = smp ? p0[e] : 0.f; if (i == 0) x1[e] = smp ? p1[e] : 0.f; } }
;     ...
;                         for (int e = 0; e < 8; ++e) { const float cv = bb[e] + x0[e] * w0[e] + x1[e] * w1[e] + x2[e] * w2[e]; r[e] = gelu_f(cv) * acc[ai][bj][m][e >> 2][e & 3]; }
;                         u32x4 w; w.x = pk2(r[0], r[1]); w.y = pk2(r[2], r[3]); w.z = pk2(r[4], r[5]); w.w = pk2(r[6], r[7]);
;                         *(u32x4*)(act + (size_t)row * DFF + col) = w; } } } }
	v_fmaak_f32 v5, v4, v2, 0x3f35f0e3
	v_pk_mul_f32 v[2:3], v[0:1], v[0:1]
	v_fmaak_f32 v5, v4, v5, 0xbe11a98e
	v_mul_f32_e32 v2, 0xbf38aa3b, v2
	v_exp_f32_e32 v2, v2
	v_fmaak_f32 v5, v4, v5, 0x3e027906
	v_mul_f32_e32 v4, v4, v5
	v_fma_f32 v5, |v1|, s84, 1.0
	v_rcp_f32_e32 v5, v5
	v_mul_f32_e32 v2, v2, v4
	v_mul_f32_e32 v4, v0, v2
	v_fma_f32 v2, -v0, v2, v0
	v_cndmask_b32_e32 v0, v2, v4, vcc
	v_mul_f32_e32 v18, v18, v0
	v_fmamk_f32 v0, v5, 0x3f07dc22, v241
	v_mul_f32_e32 v2, 0xbf38aa3b, v3
	v_fmaak_f32 v0, v5, v0, 0x3f35f0e3
	v_exp_f32_e32 v2, v2
	v_fmaak_f32 v0, v5, v0, 0xbe11a98e
	v_fmaak_f32 v0, v5, v0, 0x3e027906
	v_mul_f32_e32 v0, v5, v0
	v_mov_b32_e32 v29, v6
	v_mul_f32_e32 v0, v2, v0
	v_pk_mul_f32 v[2:3], v[72:73], v[28:29]
	v_pk_mul_f32 v[4:5], v[80:81], v[30:31]
	v_pk_fma_f32 v[6:7], v[76:77], v[36:37], v[84:85]
	v_mov_b32_e32 v22, v3
	v_mov_b32_e32 v23, v5
	v_pk_add_f32 v[6:7], v[22:23], v[6:7]
	v_mov_b32_e32 v3, v4
	v_pk_add_f32 v[2:3], v[2:3], v[6:7]
	v_mul_f32_e32 v26, v1, v0
	v_fma_f32 v4, |v2|, s84, 1.0
	v_rcp_f32_e32 v4, v4
	v_fma_f32 v0, -v1, v0, v1
	v_cmp_gt_f32_e32 vcc, 0, v1
	v_add_u32_e32 v36, 0xb0, v232
	s_nop 0
	v_cndmask_b32_e32 v0, v0, v26, vcc
	v_mul_f32_e32 v5, v19, v0
	v_fmamk_f32 v0, v4, 0x3f07dc22, v241
	v_fmaak_f32 v6, v4, v0, 0x3f35f0e3
	v_pk_mul_f32 v[0:1], v[2:3], v[2:3]
	v_fmaak_f32 v6, v4, v6, 0xbe11a98e
	v_mul_f32_e32 v0, 0xbf38aa3b, v0
	v_exp_f32_e32 v0, v0
	v_fmaak_f32 v6, v4, v6, 0x3e027906
	v_mul_f32_e32 v4, v4, v6
	v_fma_f32 v6, |v3|, s84, 1.0
	v_rcp_f32_e32 v6, v6
	v_mul_f32_e32 v0, v0, v4
	v_mul_f32_e32 v4, v2, v0
	v_fma_f32 v0, -v2, v0, v2
	v_cmp_gt_f32_e32 vcc, 0, v2
	v_mul_f32_e32 v1, 0xbf38aa3b, v1
	v_exp_f32_e32 v1, v1
	v_cndmask_b32_e32 v0, v0, v4, vcc
	v_mul_f32_e32 v4, v20, v0
	v_fmamk_f32 v0, v6, 0x3f07dc22, v241
	v_fmaak_f32 v0, v6, v0, 0x3f35f0e3
	v_fmaak_f32 v0, v6, v0, 0xbe11a98e
	v_fmaak_f32 v0, v6, v0, 0x3e027906
	v_mul_f32_e32 v0, v6, v0
	v_mul_f32_e32 v0, v1, v0
	v_mul_f32_e32 v1, v3, v0
	v_fma_f32 v0, -v3, v0, v3
	v_cmp_gt_f32_e32 vcc, 0, v3
	v_cvt_pk_bf16_f32 v2, v18, v5
	s_nop 1
	v_cndmask_b32_e32 v0, v0, v1, vcc
	v_mul_f32_e32 v3, v21, v0
	v_cvt_pk_bf16_f32 v3, v4, v3
	v_lshl_add_u64 v[4:5], s[80:81], 0, v[38:39]
	v_cvt_pk_bf16_f32 v0, v48, v32
	v_lshl_add_u64 v[4:5], v[4:5], 0, v[186:187]
	v_cvt_pk_bf16_f32 v1, v24, v25
	global_store_dwordx4 v[4:5], v[0:3], off offset:256
	s_nop 1
	v_max_i32_e32 v0, 1, v36
	v_add_u32_e32 v4, -1, v0
	v_max_i32_e32 v0, 2, v36
	v_add_u32_e32 v22, -2, v0
	v_mov_b64_e32 v[0:1], s[30:31]
	v_mad_i64_i32 v[2:3], s[0:1], v36, s76, v[0:1]
	v_mad_u64_u32 v[4:5], s[0:1], v4, s76, v[0:1]
	v_mad_u64_u32 v[0:1], s[0:1], v22, s76, v[0:1]
	v_lshl_add_u64 v[2:3], v[2:3], 0, v[186:187]
	v_lshl_add_u64 v[4:5], v[4:5], 0, v[186:187]
	v_lshl_add_u64 v[0:1], v[0:1], 0, v[186:187]
	s_movk_i32 s0, 0x1f50
	v_cmp_gt_i32_e64 s[0:1], s0, v232
	s_waitcnt vmcnt(1)
	v_mov_b64_e32 v[18:19], v[196:197]
	v_mov_b64_e32 v[20:21], v[198:199]
	v_mov_b64_e32 v[4:5], v[200:201]
	v_mov_b64_e32 v[6:7], v[202:203]
	v_mov_b64_e32 v[0:1], v[242:243]
	v_mov_b64_e32 v[2:3], v[244:245]
	v_lshlrev_b32_e32 v22, 16, v0
	v_and_b32_e32 v23, 0xffff0000, v0
	v_cndmask_b32_e64 v34, v228, v36, s[0:1]
	v_lshlrev_b32_e32 v24, 16, v1
	v_and_b32_e32 v25, 0xffff0000, v1
	v_lshlrev_b32_e32 v26, 16, v2
	v_and_b32_e32 v27, 0xffff0000, v2
	v_lshlrev_b32_e32 v28, 16, v3
	v_and_b32_e32 v29, 0xffff0000, v3
	v_lshlrev_b32_e32 v0, 16, v4
	v_and_b32_e32 v1, 0xffff0000, v4
	v_lshlrev_b32_e32 v2, 16, v5
	v_and_b32_e32 v3, 0xffff0000, v5
	v_lshlrev_b32_e32 v4, 16, v6
	v_and_b32_e32 v5, 0xffff0000, v6
	v_lshlrev_b32_e32 v6, 16, v7
	v_and_b32_e32 v7, 0xffff0000, v7
	v_cmp_gt_i32_e32 vcc, 2, v34
	s_and_saveexec_b64 s[8:9], vcc
	s_cbranch_execz .LBB0_1926
	s_addk_i32 s5, 0xe0b0
	s_ashr_i32 s5, s5, 4
	v_mov_b32_e32 v22, s5
	v_cndmask_b32_e64 v24, v22, 0, s[0:1]
	v_ashrrev_i32_e32 v25, 31, v24
	v_ashrrev_i32_e32 v35, 31, v34
	v_lshl_add_u64 v[22:23], v[24:25], 1, v[34:35]
	v_mov_b64_e32 v[26:27], s[68:69]
	v_mad_u64_u32 v[26:27], s[0:1], v22, s13, v[26:27]
	s_movk_i32 s14, 0x1f4f
	v_mad_i32_i24 v27, v23, s13, v27
	v_cmp_lt_i32_e32 vcc, s14, v232
	v_lshl_add_u64 v[32:33], v[184:185], 2, v[26:27]
	v_mov_b32_e32 v22, 0
	s_and_saveexec_b64 s[0:1], vcc
	s_cbranch_execz .LBB0_1879
	global_load_dword v22, v[32:33], off offset:512

; __device__ __forceinline__ unsigned pk2(float lo, float hi) { unsigned r; asm("v_cvt_pk_bf16_f32 %0, %1, %2" : "=v"(r) : "v"(lo), "v"(hi)); return r; }
;     static __device__ __forceinline__ void unpack8(const u32x4 q, float (&x)[8]) { x[0] = bflo(q.x); x[1] = bfhi(q.x); x[2] = bflo(q.y); x[3] = bfhi(q.y); x[4] = bflo(q.z); x[5] = bfhi(q.z); x[6] = bflo(q.w); x[7] = bfhi(q.w); }
;     __device__ __forceinline__ void operator()(EPI_ARGS) const {
;         const int row0 = u.pm * 256 + wr * 64 + fr, colt = u.pn * 256 + wc * 32 + 8 * fq;
; #pragma unroll
;     ...
;                     for (int t = 0; t < 1; ++t) { const int m = mp + t, row = row0 + ai * 128 + m * 16;
;                         const int i = row < TP ? row : ((row - TP) & 15); const int sidx = row < TP ? 0 : ((row - TP) >> 4);
;                         float x0[8], x1[8], x2[8]; unpack8(q0[t], x0); unpack8(q1[t], x1); unpack8(q2[t], x2);
;                         if (i < 2) {
;                             const bool smp = row >= TP; const float* p0 = cs + ((size_t)sidx * 2 + i) * DFF + col; const float* p1 = cs + ((size_t)sidx * 2 + 1) * DFF + col;
; #pragma unroll
;                             for (int e = 0; e < 8; ++e) { x0[e] = smp ? p0[e] : 0.f; if (i == 0) x1[e] = smp ? p1[e] : 0.f; } }
;                         float r[8];
; #pragma unroll
;                         for (int e = 0; e < 8; ++e) { const float cv = bb[e] + x0[e] * w0[e] + x1[e] * w1[e] + x2[e] * w2[e]; r[e] = gelu_f(cv) * acc[ai][bj][m][e >> 2][e & 3]; }
;                         u32x4 w; w.x = pk2(r[0], r[1]); w.y = pk2(r[2], r[3]); w.z = pk2(r[4], r[5]); w.w = pk2(r[6], r[7]);
;                         *(u32x4*)(act + (size_t)row * DFF + col) = w; } } } }
.LBB0_1924:
	s_or_b64 exec, exec, s[0:1]
.LBB0_1925:
	s_or_b64 exec, exec, s[14:15]
	s_waitcnt vmcnt(0)
.LBB0_1926:
	s_or_b64 exec, exec, s[8:9]
	v_mad_i64_i32 v[30:31], s[0:1], v36, s76, 0
	v_lshlrev_b32_e32 v32, 16, v18
	v_and_b32_e32 v18, 0xffff0000, v18
	v_lshlrev_b32_e32 v34, 16, v19
	v_and_b32_e32 v36, 0xffff0000, v19
	s_waitcnt vmcnt(1)
	v_mov_b32_e32 v33, v0
	v_mov_b32_e32 v19, v1
	v_pk_mul_f32 v[32:33], v[106:107], v[32:33]
	v_pk_mul_f32 v[0:1], v[90:91], v[18:19]
	v_pk_fma_f32 v[18:19], v[86:87], v[22:23], v[94:95]
	v_mov_b32_e32 v22, v33
	v_mov_b32_e32 v23, v1
	v_pk_add_f32 v[18:19], v[22:23], v[18:19]
	v_mov_b32_e32 v33, v0
	v_pk_add_f32 v[0:1], v[32:33], v[18:19]
	v_lshlrev_b32_e32 v38, 16, v20
	v_fma_f32 v18, |v0|, s84, 1.0
	v_rcp_f32_e32 v19, v18
	v_pk_mul_f32 v[32:33], v[0:1], v[0:1]
	v_and_b32_e32 v18, 0xffff0000, v20
	v_lshlrev_b32_e32 v20, 16, v21
	v_and_b32_e32 v22, 0xffff0000, v21
	v_fmamk_f32 v21, v19, 0x3f07dc22, v241
	v_mul_f32_e32 v23, 0xbf38aa3b, v32
	v_fmaak_f32 v21, v19, v21, 0x3f35f0e3
	v_exp_f32_e32 v23, v23
	v_fmaak_f32 v21, v19, v21, 0xbe11a98e
	v_fmaak_f32 v21, v19, v21, 0x3e027906
	v_mul_f32_e32 v19, v19, v21
	v_mul_f32_e32 v19, v23, v19
	v_fma_f32 v23, |v1|, s84, 1.0
	v_rcp_f32_e32 v23, v23
	v_mul_f32_e32 v21, v0, v19
	v_fma_f32 v19, -v0, v19, v0
	v_cmp_gt_f32_e32 vcc, 0, v0
	v_mov_b32_e32 v35, v2
	v_mov_b32_e32 v37, v3
	v_cndmask_b32_e32 v0, v19, v21, vcc
	v_mul_f32_e32 v40, v14, v0
	v_mul_f32_e32 v14, 0xbf38aa3b, v33
	v_pk_mul_f32 v[32:33], v[102:103], v[34:35]
	v_pk_mul_f32 v[2:3], v[92:93], v[36:37]
	v_fmamk_f32 v0, v23, 0x3f07dc22, v241
	v_pk_fma_f32 v[24:25], v[88:89], v[24:25], v[96:97]
	v_mov_b32_e32 v34, v33
	v_mov_b32_e32 v35, v3
	v_fmaak_f32 v0, v23, v0, 0x3f35f0e3
	v_exp_f32_e32 v14, v14
	v_pk_add_f32 v[24:25], v[34:35], v[24:25]
	v_mov_b32_e32 v33, v2
	v_fmaak_f32 v0, v23, v0, 0xbe11a98e
	v_pk_add_f32 v[2:3], v[32:33], v[24:25]
	v_fmaak_f32 v0, v23, v0, 0x3e027906
	v_fma_f32 v19, |v2|, s84, 1.0
	v_mul_f32_e32 v0, v23, v0
	v_rcp_f32_e32 v19, v19
	v_mul_f32_e32 v0, v14, v0
	v_mul_f32_e32 v14, v1, v0
	v_fma_f32 v0, -v1, v0, v1
	v_cmp_gt_f32_e32 vcc, 0, v1
	v_mov_b32_e32 v39, v4
	v_mov_b32_e32 v23, v7
	v_cndmask_b32_e32 v0, v0, v14, vcc
	v_mul_f32_e32 v24, v15, v0
	v_fmamk_f32 v0, v19, 0x3f07dc22, v241
	v_fmaak_f32 v14, v19, v0, 0x3f35f0e3
	v_pk_mul_f32 v[0:1], v[2:3], v[2:3]
	v_fmaak_f32 v14, v19, v14, 0xbe11a98e
	v_mul_f32_e32 v0, 0xbf38aa3b, v0
	v_exp_f32_e32 v0, v0
	v_fmaak_f32 v14, v19, v14, 0x3e027906
	v_fma_f32 v15, |v3|, s84, 1.0
	v_mul_f32_e32 v14, v19, v14
	v_rcp_f32_e32 v15, v15
	v_mul_f32_e32 v0, v0, v14
	v_mul_f32_e32 v14, v2, v0
	v_fma_f32 v0, -v2, v0, v2
	v_cmp_gt_f32_e32 vcc, 0, v2
	v_mul_f32_e32 v1, 0xbf38aa3b, v1
	v_exp_f32_e32 v1, v1
	v_cndmask_b32_e32 v0, v0, v14, vcc
	v_mul_f32_e32 v16, v16, v0
	v_fmamk_f32 v0, v15, 0x3f07dc22, v241
	v_fmaak_f32 v0, v15, v0, 0x3f35f0e3
	v_fmaak_f32 v0, v15, v0, 0xbe11a98e
	v_fmaak_f32 v0, v15, v0, 0x3e027906
	v_mul_f32_e32 v0, v15, v0
	v_mul_f32_e32 v0, v1, v0
	v_mov_b32_e32 v19, v5
	v_mul_f32_e32 v2, v3, v0
	v_fma_f32 v21, -v3, v0, v3
	v_pk_mul_f32 v[0:1], v[70:71], v[38:39]
	v_pk_mul_f32 v[4:5], v[78:79], v[18:19]
	v_pk_fma_f32 v[14:15], v[74:75], v[26:27], v[82:83]
	v_mov_b32_e32 v18, v1
	v_mov_b32_e32 v19, v5
	v_pk_add_f32 v[14:15], v[18:19], v[14:15]
	v_mov_b32_e32 v1, v4
	v_pk_add_f32 v[0:1], v[0:1], v[14:15]
	v_cmp_gt_f32_e32 vcc, 0, v3
	v_fma_f32 v4, |v0|, s84, 1.0
	v_rcp_f32_e32 v4, v4
	v_cndmask_b32_e32 v2, v21, v2, vcc
	v_mul_f32_e32 v17, v17, v2
	v_cmp_gt_f32_e32 vcc, 0, v0
	v_fmamk_f32 v2, v4, 0x3f07dc22, v241
	v_fmaak_f32 v5, v4, v2, 0x3f35f0e3
	v_pk_mul_f32 v[2:3], v[0:1], v[0:1]
	v_fmaak_f32 v5, v4, v5, 0xbe11a98e
	v_mul_f32_e32 v2, 0xbf38aa3b, v2
	v_exp_f32_e32 v2, v2
	v_fmaak_f32 v5, v4, v5, 0x3e027906
	v_mul_f32_e32 v4, v4, v5
	v_fma_f32 v5, |v1|, s84, 1.0
	v_rcp_f32_e32 v5, v5
	v_mul_f32_e32 v2, v2, v4
	v_mul_f32_e32 v4, v0, v2
	v_fma_f32 v2, -v0, v2, v0
	v_cndmask_b32_e32 v0, v2, v4, vcc
	v_mul_f32_e32 v10, v10, v0
	v_fmamk_f32 v0, v5, 0x3f07dc22, v241
	v_mul_f32_e32 v2, 0xbf38aa3b, v3
	v_fmaak_f32 v0, v5, v0, 0x3f35f0e3
	v_exp_f32_e32 v2, v2
	v_fmaak_f32 v0, v5, v0, 0xbe11a98e
	v_fmaak_f32 v0, v5, v0, 0x3e027906
	v_mul_f32_e32 v0, v5, v0
	v_mov_b32_e32 v21, v6
	v_mul_f32_e32 v0, v2, v0
	v_pk_mul_f32 v[2:3], v[72:73], v[20:21]
	v_pk_mul_f32 v[4:5], v[80:81], v[22:23]
	v_pk_fma_f32 v[6:7], v[76:77], v[28:29], v[84:85]
	v_mov_b32_e32 v14, v3
	v_mov_b32_e32 v15, v5
	v_pk_add_f32 v[6:7], v[14:15], v[6:7]
	v_mov_b32_e32 v3, v4
	v_pk_add_f32 v[2:3], v[2:3], v[6:7]
	v_mul_f32_e32 v18, v1, v0
	v_fma_f32 v4, |v2|, s84, 1.0
	v_rcp_f32_e32 v4, v4
	v_fma_f32 v0, -v1, v0, v1
	v_cmp_gt_f32_e32 vcc, 0, v1
	s_nop 1
	v_cndmask_b32_e32 v0, v0, v18, vcc
	v_mul_f32_e32 v5, v11, v0
	v_fmamk_f32 v0, v4, 0x3f07dc22, v241
	v_fmaak_f32 v6, v4, v0, 0x3f35f0e3
	v_pk_mul_f32 v[0:1], v[2:3], v[2:3]
	v_fmaak_f32 v6, v4, v6, 0xbe11a98e
	v_mul_f32_e32 v0, 0xbf38aa3b, v0
	v_exp_f32_e32 v0, v0
	v_fmaak_f32 v6, v4, v6, 0x3e027906
	v_mul_f32_e32 v4, v4, v6
	v_fma_f32 v6, |v3|, s84, 1.0
	v_rcp_f32_e32 v6, v6
	v_mul_f32_e32 v0, v0, v4
	v_mul_f32_e32 v4, v2, v0
	v_fma_f32 v0, -v2, v0, v2
	v_cmp_gt_f32_e32 vcc, 0, v2
	v_mul_f32_e32 v1, 0xbf38aa3b, v1
	v_exp_f32_e32 v1, v1
	v_cndmask_b32_e32 v0, v0, v4, vcc
	v_mul_f32_e32 v4, v12, v0
	v_fmamk_f32 v0, v6, 0x3f07dc22, v241
	v_fmaak_f32 v0, v6, v0, 0x3f35f0e3
	v_fmaak_f32 v0, v6, v0, 0xbe11a98e
	v_fmaak_f32 v0, v6, v0, 0x3e027906
	v_mul_f32_e32 v0, v6, v0
	v_mul_f32_e32 v0, v1, v0
	v_mul_f32_e32 v1, v3, v0
	v_fma_f32 v0, -v3, v0, v3
	v_cmp_gt_f32_e32 vcc, 0, v3
	v_cvt_pk_bf16_f32 v2, v10, v5
	s_nop 1
	v_cndmask_b32_e32 v0, v0, v1, vcc
	v_mul_f32_e32 v3, v13, v0
	v_cvt_pk_bf16_f32 v3, v4, v3
	v_lshl_add_u64 v[4:5], s[80:81], 0, v[30:31]
	v_lshl_add_u64 v[4:5], v[184:185], 1, v[4:5]
	v_cvt_pk_bf16_f32 v0, v40, v24
	v_cvt_pk_bf16_f32 v1, v16, v17
	global_store_dwordx4 v[4:5], v[0:3], off offset:256
.LBB0_1927:
	v_mov_b64_e32 v[196:197], 0x8c3
	v_mov_b64_e32 v[198:199], 0x100
	v_mov_b64_e32 v[200:201], 0x2d6
	v_mov_b64_e32 v[202:203], 0x2d5
	v_mov_b32_e32 v238, 1
	v_mov_b32_e32 v239, 0x3e800000
	v_mov_b32_e32 v240, 0x358637bd
	v_mov_b32_e32 v242, 0x7f800000
	v_mov_b32_e32 v243, 0x41b17218
	v_mov_b32_e32 v244, 0x80
	v_mov_b32_e32 v245, 0xff800000
	v_mov_b32_e32 v247, 0xfffa8000
	v_mbcnt_lo_u32_b32 v246, -1, 0
	v_mbcnt_hi_u32_b32 v246, -1, v246
	s_andn2_b64 vcc, exec, s[36:37]
	s_mov_b64 s[0:1], -1
	s_cbranch_vccnz .LBB0_1112
	v_readlane_b32 s0, v255, 4
	v_readlane_b32 s1, v255, 5
	s_andn2_b64 vcc, exec, s[0:1]
	s_cbranch_vccnz .LBB0_1111
	s_barrier
	s_branch .LBB0_1111
